# MFMA issue order inside each K-half permuted so that no two consecutive MFMAs share a source fragment (w_in, w_out, down, up loops)
# baseline (speedup 1.0000x reference)
; #define PG8_STAGE(bufoff, gbase, voff) do { _Pragma("unroll") for (int _i = 0; _i < 2; ++_i) \
;         __builtin_amdgcn_global_load_lds((const unsigned*)((const char*)(gbase) + (voff)[_i]), (PG8_LAS unsigned*)(lds + (bufoff) + ldsw + _i * 8192), 16, 0, 0); } while (0)
; #define PG8_LDA(dst, b, h) do { _Pragma("unroll") for (int m = 0; m < 4; ++m) _Pragma("unroll") for (int k = 0; k < 2; ++k) dst[m][k] = *(const PG8_LAS bf16x8*)(lds + PG8_SA(b, h) + aoff + m * 2048 + k * 1024); } while (0)
; #define PG8_LDB(dst, b, h) do { _Pragma("unroll") for (int n = 0; n < 2; ++n) _Pragma("unroll") for (int k = 0; k < 2; ++k) dst[n][k] = *(const PG8_LAS bf16x8*)(lds + PG8_SB(b, h) + boff + n * 2048 + k * 1024); } while (0)
; #define PG8_WAIT_V(n) asm volatile("s_waitcnt vmcnt(" #n ")" ::: "memory")
; #define PG8_WAIT_L(n) asm volatile("s_waitcnt lgkmcnt(" #n ")" ::: "memory")
; #define PG8_BAR __builtin_amdgcn_s_barrier()
; #define PG8_SCHED __builtin_amdgcn_sched_barrier(0)
; template <class Epi, class Sched, bool ALIGN_EPI = false, bool SP2 = false>
; __device__ __forceinline__ void gemm_phase(PG8_LAS unsigned char* lds, const Gemm g, const Sched& S, const Epi& E) {
;     ...
;         const bool has_next = S.next(ui + 1, nxt);
;         const char* nA = has_next ? (const char*)g.A + (size_t)nxt.pm * tstep : cA; const char* nB = has_next ? (const char*)g.Bt + (size_t)nxt.pn * tstep : cB;
;         for (int t = 0; t < nt; t += 2) {
;             const bool last = (t == nt - 2);
;             const char* a1 = cA + (size_t)(t + 1) * kstep;
;             const char* a2 = last ? nA : cA + (size_t)(t + 2) * kstep; const char* b2 = last ? nB : cB + (size_t)(t + 2) * kstep;
;             const char* a3 = a2 + kstep; const char* b3 = b2 + kstep;
;             if (last && has_next) S.a_ready(nxt);
;             if constexpr (SP2) {
;             PG8_LDB(B0, 0, 0); PG8_LDB(B1, 0, 1); PG8_SCHED; PG8_LDA(At, 0, 0); PG8_STAGE(PG8_SA(1, 1), a1 + hstep, voffA);
;             PG8_WAIT_V(8); PG8_WAIT_L(0); PG8_BAR; PG8_MMA(0, 0, At, B0); PG8_MMA(0, 1, At, B1); PG8_BAR; PG8_SCHED;
;             PG8_LDA(At, 0, 1); PG8_STAGE(PG8_SB(0, 0), b2, voffB); PG8_STAGE(PG8_SB(0, 1), b2 + hstepB, voffB); PG8_STAGE(PG8_SA(0, 0), a2, voffA);
;             PG8_WAIT_V(8); PG8_WAIT_L(0); PG8_BAR; PG8_MMA(1, 0, At, B0); PG8_MMA(1, 1, At, B1); PG8_BAR; PG8_SCHED;
.LBB0_169:
	s_add_u32 s93, s46, 0x100
	s_addc_u32 s94, s47, 0
	s_ashr_i32 s69, s68, 31
	s_lshl_b64 s[4:5], s[68:69], 20
	s_add_u32 s76, s52, s4
	s_addc_u32 s77, s53, s5
	s_and_b64 s[4:5], s[38:39], exec
	s_cselect_b32 s4, s77, s71
	s_cselect_b32 s5, s76, s70
	s_ashr_i32 s63, s62, 31
	s_lshl_b64 s[6:7], s[62:63], 20
	v_readlane_b32 s8, v249, 19
	v_readlane_b32 s9, v249, 20
	s_add_u32 s72, s8, s6
	s_addc_u32 s73, s9, s7
	s_and_b64 s[6:7], s[38:39], exec
	s_cselect_b32 s6, s73, s47
	s_cselect_b32 s7, s72, s46
	s_add_u32 s8, s70, 0x80080
	s_addc_u32 s9, s71, 0
	v_lshl_add_u64 v[144:145], s[8:9], 0, v[140:141]
	v_lshl_add_u64 v[146:147], s[8:9], 0, v[142:143]
	s_mov_b32 s8, -2
	s_mov_b64 s[46:47], 0
	v_add_u32_e32 v186, 0x10000, v139
	v_add_u32_e32 v187, 0x14000, v139
	v_add_u32_e32 v198, 0x18000, v139
	v_add_u32_e32 v199, 0x1c000, v139
	s_add_u32 s9, s70, s46
	s_addc_u32 s10, s71, s47
	s_add_u32 s9, s9, 0x100
	s_addc_u32 s10, s10, 0
	s_add_u32 s100, s9, 0x7ff80
	s_addc_u32 s101, s10, 0
	s_add_u32 s11, s93, s46
	s_addc_u32 s12, s94, s47
	s_add_i32 s13, 0, 0x10000
	s_cmpk_eq_i32 s46, 0xf00
	s_cselect_b32 s85, s4, s10
	s_cselect_b32 s84, s5, s9
	s_cselect_b32 s81, s6, s12
	s_cselect_b32 s80, s7, s11
	s_add_i32 s9, 0, 0x14000
	ds_read_b128 v[148:151], v186
	ds_read_b128 v[152:155], v186 offset:1024
	ds_read_b128 v[156:159], v186 offset:2048
	ds_read_b128 v[160:163], v186 offset:3072
	ds_read_b128 v[166:169], v187
	ds_read_b128 v[170:173], v187 offset:1024
	ds_read_b128 v[174:177], v187 offset:2048
	ds_read_b128 v[178:181], v187 offset:3072
	s_add_i32 m0, s1, 0xc000
	ds_read_b128 v[182:185], v165
	ds_read_b128 v[206:209], v165 offset:1024
	ds_read_b128 v[210:213], v165 offset:2048
	ds_read_b128 v[214:217], v165 offset:3072
	ds_read_b128 v[218:221], v165 offset:4096
	ds_read_b128 v[236:239], v165 offset:5120
	ds_read_b128 v[240:243], v165 offset:6144
	ds_read_b128 v[244:247], v165 offset:7168
	global_load_lds_dwordx4 v140, s[100:101]
	s_add_i32 m0, s1, 0xe000
	s_nop 0
	global_load_lds_dwordx4 v142, s[100:101]
	s_waitcnt vmcnt(8)
	s_waitcnt lgkmcnt(0)
	s_barrier
	v_mfma_f32_16x16x32_bf16 v[126:129], v[148:151], v[182:185], 0
	v_mfma_f32_16x16x32_bf16 v[114:117], v[156:159], v[210:213], 0
	v_mfma_f32_16x16x32_bf16 v[110:113], v[148:151], v[218:221], 0
	v_mfma_f32_16x16x32_bf16 v[98:101], v[156:159], v[240:243], 0
	v_mfma_f32_16x16x32_bf16 v[118:121], v[148:151], v[210:213], 0
	v_mfma_f32_16x16x32_bf16 v[122:125], v[156:159], v[182:185], 0
	v_mfma_f32_16x16x32_bf16 v[102:105], v[148:151], v[240:243], 0
	v_mfma_f32_16x16x32_bf16 v[106:109], v[156:159], v[218:221], 0
	v_mfma_f32_16x16x32_bf16 v[126:129], v[152:155], v[206:209], v[126:129]
	v_mfma_f32_16x16x32_bf16 v[114:117], v[160:163], v[214:217], v[114:117]
	v_mfma_f32_16x16x32_bf16 v[110:113], v[152:155], v[236:239], v[110:113]
	v_mfma_f32_16x16x32_bf16 v[98:101], v[160:163], v[244:247], v[98:101]
	v_mfma_f32_16x16x32_bf16 v[118:121], v[152:155], v[214:217], v[118:121]
	v_mfma_f32_16x16x32_bf16 v[122:125], v[160:163], v[206:209], v[122:125]
	v_mfma_f32_16x16x32_bf16 v[102:105], v[152:155], v[244:247], v[102:105]
	v_mfma_f32_16x16x32_bf16 v[106:109], v[160:163], v[236:239], v[106:109]
	v_mfma_f32_16x16x32_bf16 v[94:97], v[166:169], v[182:185], 0
	v_mfma_f32_16x16x32_bf16 v[82:85], v[174:177], v[210:213], 0
	v_mfma_f32_16x16x32_bf16 v[78:81], v[166:169], v[218:221], 0
	v_mfma_f32_16x16x32_bf16 v[66:69], v[174:177], v[240:243], 0
	v_mfma_f32_16x16x32_bf16 v[86:89], v[166:169], v[210:213], 0
	v_mfma_f32_16x16x32_bf16 v[90:93], v[174:177], v[182:185], 0
	v_mfma_f32_16x16x32_bf16 v[70:73], v[166:169], v[240:243], 0
	v_mfma_f32_16x16x32_bf16 v[74:77], v[174:177], v[218:221], 0
	v_mfma_f32_16x16x32_bf16 v[94:97], v[170:173], v[206:209], v[94:97]
	v_mfma_f32_16x16x32_bf16 v[82:85], v[178:181], v[214:217], v[82:85]
	v_mfma_f32_16x16x32_bf16 v[78:81], v[170:173], v[236:239], v[78:81]
	v_mfma_f32_16x16x32_bf16 v[66:69], v[178:181], v[244:247], v[66:69]
	v_mfma_f32_16x16x32_bf16 v[86:89], v[170:173], v[214:217], v[86:89]
	v_mfma_f32_16x16x32_bf16 v[90:93], v[178:181], v[206:209], v[90:93]
	v_mfma_f32_16x16x32_bf16 v[70:73], v[170:173], v[244:247], v[70:73]
	v_mfma_f32_16x16x32_bf16 v[74:77], v[178:181], v[236:239], v[74:77]
	s_barrier
	s_add_i32 s10, s13, s0
	s_mov_b32 m0, s10
	ds_read_b128 v[182:185], v165 offset:16384
	ds_read_b128 v[206:209], v165 offset:17408
	ds_read_b128 v[210:213], v165 offset:18432
	ds_read_b128 v[214:217], v165 offset:19456
	ds_read_b128 v[218:221], v165 offset:20480
	ds_read_b128 v[236:239], v165 offset:21504
	ds_read_b128 v[240:243], v165 offset:22528
	ds_read_b128 v[244:247], v165 offset:23552
	global_load_lds_dwordx4 v132, s[80:81]
	s_add_i32 m0, s10, 0x2000
	s_add_u32 s10, s80, 0x20000
	s_addc_u32 s11, s81, 0
	s_add_i32 s9, s9, s0
	global_load_lds_dwordx4 v136, s[80:81]
	s_mov_b32 m0, s9
	s_nop 0
	global_load_lds_dwordx4 v132, s[10:11]
	s_add_i32 m0, s9, 0x2000
	s_nop 0
	global_load_lds_dwordx4 v136, s[10:11]
	s_mov_b32 m0, s1
	s_nop 0
	global_load_lds_dwordx4 v130, s[84:85]
	s_mov_b32 m0, s25
	s_nop 0
	global_load_lds_dwordx4 v134, s[84:85]
	s_waitcnt vmcnt(8)
	s_waitcnt lgkmcnt(0)
	s_barrier
; #define PG8_STAGE(bufoff, gbase, voff) do { _Pragma("unroll") for (int _i = 0; _i < 2; ++_i) \
;         __builtin_amdgcn_global_load_lds((const unsigned*)((const char*)(gbase) + (voff)[_i]), (PG8_LAS unsigned*)(lds + (bufoff) + ldsw + _i * 8192), 16, 0, 0); } while (0)
; #define PG8_LDA(dst, b, h) do { _Pragma("unroll") for (int m = 0; m < 4; ++m) _Pragma("unroll") for (int k = 0; k < 2; ++k) dst[m][k] = *(const PG8_LAS bf16x8*)(lds + PG8_SA(b, h) + aoff + m * 2048 + k * 1024); } while (0)
; #define PG8_LDB(dst, b, h) do { _Pragma("unroll") for (int n = 0; n < 2; ++n) _Pragma("unroll") for (int k = 0; k < 2; ++k) dst[n][k] = *(const PG8_LAS bf16x8*)(lds + PG8_SB(b, h) + boff + n * 2048 + k * 1024); } while (0)
; #define PG8_MMA(ai, bj, At, Bt) do { __builtin_amdgcn_s_setprio(1); _Pragma("unroll") for (int m = 0; m < 4; ++m) _Pragma("unroll") for (int n = 0; n < 2; ++n) _Pragma("unroll") for (int k = 0; k < 2; ++k) \
;         acc[ai][bj][m][n] = __builtin_amdgcn_mfma_f32_16x16x32_bf16(Bt[n][k], At[m][k], acc[ai][bj][m][n], 0, 0, 0); __builtin_amdgcn_s_setprio(0); } while (0)
; #define PG8_WAIT_V(n) asm volatile("s_waitcnt vmcnt(" #n ")" ::: "memory")
; #define PG8_WAIT_L(n) asm volatile("s_waitcnt lgkmcnt(" #n ")" ::: "memory")
; #define PG8_BAR __builtin_amdgcn_s_barrier()
; #define PG8_SCHED __builtin_amdgcn_sched_barrier(0)
; template <class Epi, class Sched, bool ALIGN_EPI = false, bool SP2 = false>
; __device__ __forceinline__ void gemm_phase(PG8_LAS unsigned char* lds, const Gemm g, const Sched& S, const Epi& E) {
;     ...
;             PG8_WAIT_V(8); PG8_WAIT_L(0); PG8_BAR; PG8_MMA(1, 0, At, B0); PG8_MMA(1, 1, At, B1); PG8_BAR; PG8_SCHED;
;             PG8_LDB(B0, 1, 0); PG8_LDB(B1, 1, 1); PG8_SCHED; PG8_LDA(At, 1, 0); PG8_STAGE(PG8_SA(0, 1), a2 + hstep, voffA);
;             PG8_WAIT_V(8); PG8_WAIT_L(0); PG8_BAR; PG8_MMA(0, 0, At, B0); PG8_MMA(0, 1, At, B1); PG8_BAR; PG8_SCHED;
	v_mfma_f32_16x16x32_bf16 v[62:65], v[148:151], v[182:185], 0
	v_mfma_f32_16x16x32_bf16 v[50:53], v[156:159], v[210:213], 0
	v_mfma_f32_16x16x32_bf16 v[46:49], v[148:151], v[218:221], 0
	v_mfma_f32_16x16x32_bf16 v[34:37], v[156:159], v[240:243], 0
	v_mfma_f32_16x16x32_bf16 v[54:57], v[148:151], v[210:213], 0
	v_mfma_f32_16x16x32_bf16 v[58:61], v[156:159], v[182:185], 0
	v_mfma_f32_16x16x32_bf16 v[38:41], v[148:151], v[240:243], 0
	v_mfma_f32_16x16x32_bf16 v[42:45], v[156:159], v[218:221], 0
	v_mfma_f32_16x16x32_bf16 v[62:65], v[152:155], v[206:209], v[62:65]
	v_mfma_f32_16x16x32_bf16 v[50:53], v[160:163], v[214:217], v[50:53]
	v_mfma_f32_16x16x32_bf16 v[46:49], v[152:155], v[236:239], v[46:49]
	v_mfma_f32_16x16x32_bf16 v[34:37], v[160:163], v[244:247], v[34:37]
	v_mfma_f32_16x16x32_bf16 v[54:57], v[152:155], v[214:217], v[54:57]
	v_mfma_f32_16x16x32_bf16 v[58:61], v[160:163], v[206:209], v[58:61]
	v_mfma_f32_16x16x32_bf16 v[38:41], v[152:155], v[244:247], v[38:41]
	v_mfma_f32_16x16x32_bf16 v[42:45], v[160:163], v[236:239], v[42:45]
	v_mfma_f32_16x16x32_bf16 v[30:33], v[166:169], v[182:185], 0
	v_mfma_f32_16x16x32_bf16 v[18:21], v[174:177], v[210:213], 0
	v_mfma_f32_16x16x32_bf16 v[14:17], v[166:169], v[218:221], 0
	v_mfma_f32_16x16x32_bf16 v[2:5], v[174:177], v[240:243], 0
	v_mfma_f32_16x16x32_bf16 v[22:25], v[166:169], v[210:213], 0
	v_mfma_f32_16x16x32_bf16 v[26:29], v[174:177], v[182:185], 0
	v_mfma_f32_16x16x32_bf16 v[6:9], v[166:169], v[240:243], 0
	v_mfma_f32_16x16x32_bf16 v[10:13], v[174:177], v[218:221], 0
	v_mfma_f32_16x16x32_bf16 v[30:33], v[170:173], v[206:209], v[30:33]
	v_mfma_f32_16x16x32_bf16 v[18:21], v[178:181], v[214:217], v[18:21]
	v_mfma_f32_16x16x32_bf16 v[14:17], v[170:173], v[236:239], v[14:17]
	v_mfma_f32_16x16x32_bf16 v[2:5], v[178:181], v[244:247], v[2:5]
	v_mfma_f32_16x16x32_bf16 v[22:25], v[170:173], v[214:217], v[22:25]
	v_mfma_f32_16x16x32_bf16 v[26:29], v[178:181], v[206:209], v[26:29]
	v_mfma_f32_16x16x32_bf16 v[6:9], v[170:173], v[244:247], v[6:9]
	v_mfma_f32_16x16x32_bf16 v[10:13], v[178:181], v[236:239], v[10:13]
	s_barrier
	s_add_i32 s9, 0, 0x18000
	s_add_i32 s12, 0, 0x1c000
	ds_read_b128 v[148:151], v198
	ds_read_b128 v[152:155], v198 offset:1024
	ds_read_b128 v[156:159], v198 offset:2048
	ds_read_b128 v[160:163], v198 offset:3072
	ds_read_b128 v[166:169], v199
	ds_read_b128 v[170:173], v199 offset:1024
	ds_read_b128 v[174:177], v199 offset:2048
	ds_read_b128 v[178:181], v199 offset:3072
	s_add_u32 s10, s84, 0x80000
	s_addc_u32 s11, s85, 0
	s_mov_b32 m0, s42
	ds_read_b128 v[182:185], v165 offset:32768
	ds_read_b128 v[206:209], v165 offset:33792
	ds_read_b128 v[210:213], v165 offset:34816
	ds_read_b128 v[214:217], v165 offset:35840
	ds_read_b128 v[218:221], v165 offset:36864
	ds_read_b128 v[236:239], v165 offset:37888
	ds_read_b128 v[240:243], v165 offset:38912
	ds_read_b128 v[244:247], v165 offset:39936
	global_load_lds_dwordx4 v130, s[10:11]
	s_mov_b32 m0, s51
	s_nop 0
	global_load_lds_dwordx4 v134, s[10:11]
	s_waitcnt vmcnt(8)
	s_waitcnt lgkmcnt(0)
	s_barrier
	v_mfma_f32_16x16x32_bf16 v[126:129], v[148:151], v[182:185], v[126:129]
	v_mfma_f32_16x16x32_bf16 v[114:117], v[156:159], v[210:213], v[114:117]
	v_mfma_f32_16x16x32_bf16 v[110:113], v[148:151], v[218:221], v[110:113]
	v_mfma_f32_16x16x32_bf16 v[98:101], v[156:159], v[240:243], v[98:101]
	v_mfma_f32_16x16x32_bf16 v[118:121], v[148:151], v[210:213], v[118:121]
	v_mfma_f32_16x16x32_bf16 v[122:125], v[156:159], v[182:185], v[122:125]
	v_mfma_f32_16x16x32_bf16 v[102:105], v[148:151], v[240:243], v[102:105]
	v_mfma_f32_16x16x32_bf16 v[106:109], v[156:159], v[218:221], v[106:109]
	v_mfma_f32_16x16x32_bf16 v[126:129], v[152:155], v[206:209], v[126:129]
	v_mfma_f32_16x16x32_bf16 v[114:117], v[160:163], v[214:217], v[114:117]
	v_mfma_f32_16x16x32_bf16 v[110:113], v[152:155], v[236:239], v[110:113]
	v_mfma_f32_16x16x32_bf16 v[98:101], v[160:163], v[244:247], v[98:101]
	v_mfma_f32_16x16x32_bf16 v[118:121], v[152:155], v[214:217], v[118:121]
	v_mfma_f32_16x16x32_bf16 v[122:125], v[160:163], v[206:209], v[122:125]
	v_mfma_f32_16x16x32_bf16 v[102:105], v[152:155], v[244:247], v[102:105]
	v_mfma_f32_16x16x32_bf16 v[106:109], v[160:163], v[236:239], v[106:109]
	v_mfma_f32_16x16x32_bf16 v[94:97], v[166:169], v[182:185], v[94:97]
	v_mfma_f32_16x16x32_bf16 v[82:85], v[174:177], v[210:213], v[82:85]
	v_mfma_f32_16x16x32_bf16 v[78:81], v[166:169], v[218:221], v[78:81]
	v_mfma_f32_16x16x32_bf16 v[66:69], v[174:177], v[240:243], v[66:69]
	v_mfma_f32_16x16x32_bf16 v[86:89], v[166:169], v[210:213], v[86:89]
	v_mfma_f32_16x16x32_bf16 v[90:93], v[174:177], v[182:185], v[90:93]
	v_mfma_f32_16x16x32_bf16 v[70:73], v[166:169], v[240:243], v[70:73]
	v_mfma_f32_16x16x32_bf16 v[74:77], v[174:177], v[218:221], v[74:77]
	v_mfma_f32_16x16x32_bf16 v[94:97], v[170:173], v[206:209], v[94:97]
	v_mfma_f32_16x16x32_bf16 v[82:85], v[178:181], v[214:217], v[82:85]
	v_mfma_f32_16x16x32_bf16 v[78:81], v[170:173], v[236:239], v[78:81]
	v_mfma_f32_16x16x32_bf16 v[66:69], v[178:181], v[244:247], v[66:69]
	v_mfma_f32_16x16x32_bf16 v[86:89], v[170:173], v[214:217], v[86:89]
	v_mfma_f32_16x16x32_bf16 v[90:93], v[178:181], v[206:209], v[90:93]
	v_mfma_f32_16x16x32_bf16 v[70:73], v[170:173], v[244:247], v[70:73]
	v_mfma_f32_16x16x32_bf16 v[74:77], v[178:181], v[236:239], v[74:77]
	s_barrier
; #define PG8_STAGE(bufoff, gbase, voff) do { _Pragma("unroll") for (int _i = 0; _i < 2; ++_i) \
;         __builtin_amdgcn_global_load_lds((const unsigned*)((const char*)(gbase) + (voff)[_i]), (PG8_LAS unsigned*)(lds + (bufoff) + ldsw + _i * 8192), 16, 0, 0); } while (0)
; #define PG8_LDA(dst, b, h) do { _Pragma("unroll") for (int m = 0; m < 4; ++m) _Pragma("unroll") for (int k = 0; k < 2; ++k) dst[m][k] = *(const PG8_LAS bf16x8*)(lds + PG8_SA(b, h) + aoff + m * 2048 + k * 1024); } while (0)
; #define PG8_LDB(dst, b, h) do { _Pragma("unroll") for (int n = 0; n < 2; ++n) _Pragma("unroll") for (int k = 0; k < 2; ++k) dst[n][k] = *(const PG8_LAS bf16x8*)(lds + PG8_SB(b, h) + boff + n * 2048 + k * 1024); } while (0)
; #define PG8_MMA(ai, bj, At, Bt) do { __builtin_amdgcn_s_setprio(1); _Pragma("unroll") for (int m = 0; m < 4; ++m) _Pragma("unroll") for (int n = 0; n < 2; ++n) _Pragma("unroll") for (int k = 0; k < 2; ++k) \
;         acc[ai][bj][m][n] = __builtin_amdgcn_mfma_f32_16x16x32_bf16(Bt[n][k], At[m][k], acc[ai][bj][m][n], 0, 0, 0); __builtin_amdgcn_s_setprio(0); } while (0)
; #define PG8_WAIT_V(n) asm volatile("s_waitcnt vmcnt(" #n ")" ::: "memory")
; #define PG8_WAIT_L(n) asm volatile("s_waitcnt lgkmcnt(" #n ")" ::: "memory")
; #define PG8_BAR __builtin_amdgcn_s_barrier()
; #define PG8_SCHED __builtin_amdgcn_sched_barrier(0)
; template <class Epi, class Sched, bool ALIGN_EPI = false, bool SP2 = false>
; __device__ __forceinline__ void gemm_phase(PG8_LAS unsigned char* lds, const Gemm g, const Sched& S, const Epi& E) {
;     ...
;         for (int t = 0; t < nt; t += 2) {
;             const bool last = (t == nt - 2);
;             const char* a1 = cA + (size_t)(t + 1) * kstep;
;             const char* a2 = last ? nA : cA + (size_t)(t + 2) * kstep; const char* b2 = last ? nB : cB + (size_t)(t + 2) * kstep;
;             const char* a3 = a2 + kstep; const char* b3 = b2 + kstep;
;             if (last && has_next) S.a_ready(nxt);
;             if constexpr (SP2) {
;             PG8_LDB(B0, 0, 0); PG8_LDB(B1, 0, 1); PG8_SCHED; PG8_LDA(At, 0, 0); PG8_STAGE(PG8_SA(1, 1), a1 + hstep, voffA);
;     ...
;             PG8_LDA(At, 1, 1); PG8_STAGE(PG8_SB(1, 0), b3, voffB); PG8_STAGE(PG8_SB(1, 1), b3 + hstepB, voffB); PG8_STAGE(PG8_SA(1, 0), a3, voffA);
;             PG8_WAIT_V(8); PG8_WAIT_L(0); PG8_BAR; PG8_MMA(1, 0, At, B0); PG8_MMA(1, 1, At, B1); PG8_BAR; PG8_SCHED;
	s_add_i32 s9, s9, s0
	s_mov_b32 m0, s9
	ds_read_b128 v[182:185], v165 offset:49152
	ds_read_b128 v[206:209], v165 offset:50176
	ds_read_b128 v[210:213], v165 offset:51200
	ds_read_b128 v[214:217], v165 offset:52224
	ds_read_b128 v[218:221], v165 offset:53248
	ds_read_b128 v[236:239], v165 offset:54272
	ds_read_b128 v[240:243], v165 offset:55296
	ds_read_b128 v[244:247], v165 offset:56320
	s_add_u32 s100, s80, s60
	s_addc_u32 s101, s81, s61
	global_load_lds_dwordx4 v132, s[100:101]
	s_add_i32 m0, s9, 0x2000
	s_add_u32 s10, s80, 0x20080
	s_addc_u32 s11, s81, 0
	s_add_i32 s9, s12, s0
	global_load_lds_dwordx4 v136, s[100:101]
	s_mov_b32 m0, s9
	s_nop 0
	global_load_lds_dwordx4 v132, s[10:11]
	s_add_i32 m0, s9, 0x2000
	s_nop 0
	global_load_lds_dwordx4 v136, s[10:11]
	s_mov_b32 m0, s66
	s_add_u32 s100, s84, s60
	s_addc_u32 s101, s85, s61
	global_load_lds_dwordx4 v130, s[100:101]
	s_mov_b32 m0, s67
	s_nop 0
	global_load_lds_dwordx4 v134, s[100:101]
	s_waitcnt vmcnt(8)
	s_waitcnt lgkmcnt(0)
	s_barrier
	v_mfma_f32_16x16x32_bf16 v[62:65], v[148:151], v[182:185], v[62:65]
	v_mfma_f32_16x16x32_bf16 v[50:53], v[156:159], v[210:213], v[50:53]
	v_mfma_f32_16x16x32_bf16 v[46:49], v[148:151], v[218:221], v[46:49]
	v_mfma_f32_16x16x32_bf16 v[34:37], v[156:159], v[240:243], v[34:37]
	v_mfma_f32_16x16x32_bf16 v[54:57], v[148:151], v[210:213], v[54:57]
	v_mfma_f32_16x16x32_bf16 v[58:61], v[156:159], v[182:185], v[58:61]
	v_mfma_f32_16x16x32_bf16 v[38:41], v[148:151], v[240:243], v[38:41]
	v_mfma_f32_16x16x32_bf16 v[42:45], v[156:159], v[218:221], v[42:45]
	v_mfma_f32_16x16x32_bf16 v[62:65], v[152:155], v[206:209], v[62:65]
	v_mfma_f32_16x16x32_bf16 v[50:53], v[160:163], v[214:217], v[50:53]
	v_mfma_f32_16x16x32_bf16 v[46:49], v[152:155], v[236:239], v[46:49]
	v_mfma_f32_16x16x32_bf16 v[34:37], v[160:163], v[244:247], v[34:37]
	v_mfma_f32_16x16x32_bf16 v[54:57], v[152:155], v[214:217], v[54:57]
	v_mfma_f32_16x16x32_bf16 v[58:61], v[160:163], v[206:209], v[58:61]
	v_mfma_f32_16x16x32_bf16 v[38:41], v[152:155], v[244:247], v[38:41]
	v_mfma_f32_16x16x32_bf16 v[42:45], v[160:163], v[236:239], v[42:45]
	v_mfma_f32_16x16x32_bf16 v[30:33], v[166:169], v[182:185], v[30:33]
	v_mfma_f32_16x16x32_bf16 v[18:21], v[174:177], v[210:213], v[18:21]
	v_mfma_f32_16x16x32_bf16 v[14:17], v[166:169], v[218:221], v[14:17]
	v_mfma_f32_16x16x32_bf16 v[2:5], v[174:177], v[240:243], v[2:5]
	v_mfma_f32_16x16x32_bf16 v[22:25], v[166:169], v[210:213], v[22:25]
	v_mfma_f32_16x16x32_bf16 v[26:29], v[174:177], v[182:185], v[26:29]
	v_mfma_f32_16x16x32_bf16 v[6:9], v[166:169], v[240:243], v[6:9]
	v_mfma_f32_16x16x32_bf16 v[10:13], v[174:177], v[218:221], v[10:13]
	v_mfma_f32_16x16x32_bf16 v[30:33], v[170:173], v[206:209], v[30:33]
	v_mfma_f32_16x16x32_bf16 v[18:21], v[178:181], v[214:217], v[18:21]
	v_mfma_f32_16x16x32_bf16 v[14:17], v[170:173], v[236:239], v[14:17]
	v_mfma_f32_16x16x32_bf16 v[2:5], v[178:181], v[244:247], v[2:5]
	v_mfma_f32_16x16x32_bf16 v[22:25], v[170:173], v[214:217], v[22:25]
	v_mfma_f32_16x16x32_bf16 v[26:29], v[178:181], v[206:209], v[26:29]
	v_mfma_f32_16x16x32_bf16 v[6:9], v[170:173], v[244:247], v[6:9]
	v_mfma_f32_16x16x32_bf16 v[10:13], v[178:181], v[236:239], v[10:13]
	s_barrier
	s_add_i32 s8, s8, 2
	s_add_u32 s46, s46, 0x100
	s_addc_u32 s47, s47, 0
	s_cmp_gt_u32 s8, 29
.LBB0_170:
	s_add_u32 s9, s70, s46
	s_addc_u32 s10, s71, s47
	s_add_u32 s9, s9, 0x100
	s_addc_u32 s10, s10, 0
	s_add_u32 s100, s9, 0x7ff80
	s_addc_u32 s101, s10, 0
	s_add_u32 s11, s93, s46
	s_addc_u32 s12, s94, s47
	s_add_i32 s13, 0, 0x10000
	s_cmpk_eq_i32 s46, 0xf00
	s_cselect_b32 s85, s4, s10
	s_cselect_b32 s84, s5, s9
	s_cselect_b32 s81, s6, s12
	s_cselect_b32 s80, s7, s11
	s_add_i32 s9, 0, 0x14000
	ds_read_b128 v[148:151], v186
	ds_read_b128 v[152:155], v186 offset:1024
	ds_read_b128 v[156:159], v186 offset:2048
	ds_read_b128 v[160:163], v186 offset:3072
	ds_read_b128 v[166:169], v187
	ds_read_b128 v[170:173], v187 offset:1024
	ds_read_b128 v[174:177], v187 offset:2048
	ds_read_b128 v[178:181], v187 offset:3072
	s_add_i32 m0, s1, 0xc000
	ds_read_b128 v[182:185], v165
	ds_read_b128 v[206:209], v165 offset:1024
	ds_read_b128 v[210:213], v165 offset:2048
	ds_read_b128 v[214:217], v165 offset:3072
	ds_read_b128 v[218:221], v165 offset:4096
	ds_read_b128 v[236:239], v165 offset:5120
	ds_read_b128 v[240:243], v165 offset:6144
	ds_read_b128 v[244:247], v165 offset:7168
	global_load_lds_dwordx4 v140, s[100:101]
	s_add_i32 m0, s1, 0xe000
	s_nop 0
	global_load_lds_dwordx4 v142, s[100:101]
	s_waitcnt vmcnt(8)
	s_waitcnt lgkmcnt(0)
	s_barrier
; #define PG8_STAGE(bufoff, gbase, voff) do { _Pragma("unroll") for (int _i = 0; _i < 2; ++_i) \
;         __builtin_amdgcn_global_load_lds((const unsigned*)((const char*)(gbase) + (voff)[_i]), (PG8_LAS unsigned*)(lds + (bufoff) + ldsw + _i * 8192), 16, 0, 0); } while (0)
; #define PG8_LDA(dst, b, h) do { _Pragma("unroll") for (int m = 0; m < 4; ++m) _Pragma("unroll") for (int k = 0; k < 2; ++k) dst[m][k] = *(const PG8_LAS bf16x8*)(lds + PG8_SA(b, h) + aoff + m * 2048 + k * 1024); } while (0)
; #define PG8_LDB(dst, b, h) do { _Pragma("unroll") for (int n = 0; n < 2; ++n) _Pragma("unroll") for (int k = 0; k < 2; ++k) dst[n][k] = *(const PG8_LAS bf16x8*)(lds + PG8_SB(b, h) + boff + n * 2048 + k * 1024); } while (0)
; #define PG8_MMA(ai, bj, At, Bt) do { __builtin_amdgcn_s_setprio(1); _Pragma("unroll") for (int m = 0; m < 4; ++m) _Pragma("unroll") for (int n = 0; n < 2; ++n) _Pragma("unroll") for (int k = 0; k < 2; ++k) \
;         acc[ai][bj][m][n] = __builtin_amdgcn_mfma_f32_16x16x32_bf16(Bt[n][k], At[m][k], acc[ai][bj][m][n], 0, 0, 0); __builtin_amdgcn_s_setprio(0); } while (0)
; #define PG8_WAIT_V(n) asm volatile("s_waitcnt vmcnt(" #n ")" ::: "memory")
; #define PG8_WAIT_L(n) asm volatile("s_waitcnt lgkmcnt(" #n ")" ::: "memory")
; #define PG8_BAR __builtin_amdgcn_s_barrier()
; #define PG8_SCHED __builtin_amdgcn_sched_barrier(0)
; template <class Epi, class Sched, bool ALIGN_EPI = false, bool SP2 = false>
; __device__ __forceinline__ void gemm_phase(PG8_LAS unsigned char* lds, const Gemm g, const Sched& S, const Epi& E) {
;     ...
;             PG8_LDB(B0, 0, 0); PG8_LDB(B1, 0, 1); PG8_SCHED; PG8_LDA(At, 0, 0); PG8_STAGE(PG8_SA(1, 1), a1 + hstep, voffA);
;             PG8_WAIT_V(8); PG8_WAIT_L(0); PG8_BAR; PG8_MMA(0, 0, At, B0); PG8_MMA(0, 1, At, B1); PG8_BAR; PG8_SCHED;
;             PG8_LDA(At, 0, 1); PG8_STAGE(PG8_SB(0, 0), b2, voffB); PG8_STAGE(PG8_SB(0, 1), b2 + hstepB, voffB); PG8_STAGE(PG8_SA(0, 0), a2, voffA);
;             PG8_WAIT_V(8); PG8_WAIT_L(0); PG8_BAR; PG8_MMA(1, 0, At, B0); PG8_MMA(1, 1, At, B1); PG8_BAR; PG8_SCHED;
	v_mfma_f32_16x16x32_bf16 v[126:129], v[148:151], v[182:185], v[126:129]
	v_mfma_f32_16x16x32_bf16 v[114:117], v[156:159], v[210:213], v[114:117]
	v_mfma_f32_16x16x32_bf16 v[110:113], v[148:151], v[218:221], v[110:113]
	v_mfma_f32_16x16x32_bf16 v[98:101], v[156:159], v[240:243], v[98:101]
	v_mfma_f32_16x16x32_bf16 v[118:121], v[148:151], v[210:213], v[118:121]
	v_mfma_f32_16x16x32_bf16 v[122:125], v[156:159], v[182:185], v[122:125]
	v_mfma_f32_16x16x32_bf16 v[102:105], v[148:151], v[240:243], v[102:105]
	v_mfma_f32_16x16x32_bf16 v[106:109], v[156:159], v[218:221], v[106:109]
	v_mfma_f32_16x16x32_bf16 v[126:129], v[152:155], v[206:209], v[126:129]
	v_mfma_f32_16x16x32_bf16 v[114:117], v[160:163], v[214:217], v[114:117]
	v_mfma_f32_16x16x32_bf16 v[110:113], v[152:155], v[236:239], v[110:113]
	v_mfma_f32_16x16x32_bf16 v[98:101], v[160:163], v[244:247], v[98:101]
	v_mfma_f32_16x16x32_bf16 v[118:121], v[152:155], v[214:217], v[118:121]
	v_mfma_f32_16x16x32_bf16 v[122:125], v[160:163], v[206:209], v[122:125]
	v_mfma_f32_16x16x32_bf16 v[102:105], v[152:155], v[244:247], v[102:105]
	v_mfma_f32_16x16x32_bf16 v[106:109], v[160:163], v[236:239], v[106:109]
	v_mfma_f32_16x16x32_bf16 v[94:97], v[166:169], v[182:185], v[94:97]
	v_mfma_f32_16x16x32_bf16 v[82:85], v[174:177], v[210:213], v[82:85]
	v_mfma_f32_16x16x32_bf16 v[78:81], v[166:169], v[218:221], v[78:81]
	v_mfma_f32_16x16x32_bf16 v[66:69], v[174:177], v[240:243], v[66:69]
	v_mfma_f32_16x16x32_bf16 v[86:89], v[166:169], v[210:213], v[86:89]
	v_mfma_f32_16x16x32_bf16 v[90:93], v[174:177], v[182:185], v[90:93]
	v_mfma_f32_16x16x32_bf16 v[70:73], v[166:169], v[240:243], v[70:73]
	v_mfma_f32_16x16x32_bf16 v[74:77], v[174:177], v[218:221], v[74:77]
	v_mfma_f32_16x16x32_bf16 v[94:97], v[170:173], v[206:209], v[94:97]
	v_mfma_f32_16x16x32_bf16 v[82:85], v[178:181], v[214:217], v[82:85]
	v_mfma_f32_16x16x32_bf16 v[78:81], v[170:173], v[236:239], v[78:81]
	v_mfma_f32_16x16x32_bf16 v[66:69], v[178:181], v[244:247], v[66:69]
	v_mfma_f32_16x16x32_bf16 v[86:89], v[170:173], v[214:217], v[86:89]
	v_mfma_f32_16x16x32_bf16 v[90:93], v[178:181], v[206:209], v[90:93]
	v_mfma_f32_16x16x32_bf16 v[70:73], v[170:173], v[244:247], v[70:73]
	v_mfma_f32_16x16x32_bf16 v[74:77], v[178:181], v[236:239], v[74:77]
	s_barrier
	s_add_i32 s10, s13, s0
	s_mov_b32 m0, s10
	ds_read_b128 v[182:185], v165 offset:16384
	ds_read_b128 v[206:209], v165 offset:17408
	ds_read_b128 v[210:213], v165 offset:18432
	ds_read_b128 v[214:217], v165 offset:19456
	ds_read_b128 v[218:221], v165 offset:20480
	ds_read_b128 v[236:239], v165 offset:21504
	ds_read_b128 v[240:243], v165 offset:22528
	ds_read_b128 v[244:247], v165 offset:23552
	global_load_lds_dwordx4 v132, s[80:81]
	s_add_i32 m0, s10, 0x2000
	s_add_u32 s10, s80, 0x20000
	s_addc_u32 s11, s81, 0
	s_add_i32 s9, s9, s0
	global_load_lds_dwordx4 v136, s[80:81]
	s_mov_b32 m0, s9
	s_nop 0
	global_load_lds_dwordx4 v132, s[10:11]
	s_add_i32 m0, s9, 0x2000
	s_nop 0
	global_load_lds_dwordx4 v136, s[10:11]
	s_mov_b32 m0, s1
	s_nop 0
	global_load_lds_dwordx4 v130, s[84:85]
	s_mov_b32 m0, s25
	s_nop 0
	global_load_lds_dwordx4 v134, s[84:85]
	s_waitcnt vmcnt(8)
	s_waitcnt lgkmcnt(0)
	s_barrier
	v_mfma_f32_16x16x32_bf16 v[62:65], v[148:151], v[182:185], v[62:65]
	v_mfma_f32_16x16x32_bf16 v[50:53], v[156:159], v[210:213], v[50:53]
	v_mfma_f32_16x16x32_bf16 v[46:49], v[148:151], v[218:221], v[46:49]
	v_mfma_f32_16x16x32_bf16 v[34:37], v[156:159], v[240:243], v[34:37]
	v_mfma_f32_16x16x32_bf16 v[54:57], v[148:151], v[210:213], v[54:57]
	v_mfma_f32_16x16x32_bf16 v[58:61], v[156:159], v[182:185], v[58:61]
	v_mfma_f32_16x16x32_bf16 v[38:41], v[148:151], v[240:243], v[38:41]
	v_mfma_f32_16x16x32_bf16 v[42:45], v[156:159], v[218:221], v[42:45]
	v_mfma_f32_16x16x32_bf16 v[62:65], v[152:155], v[206:209], v[62:65]
	v_mfma_f32_16x16x32_bf16 v[50:53], v[160:163], v[214:217], v[50:53]
	v_mfma_f32_16x16x32_bf16 v[46:49], v[152:155], v[236:239], v[46:49]
	v_mfma_f32_16x16x32_bf16 v[34:37], v[160:163], v[244:247], v[34:37]
	v_mfma_f32_16x16x32_bf16 v[54:57], v[152:155], v[214:217], v[54:57]
	v_mfma_f32_16x16x32_bf16 v[58:61], v[160:163], v[206:209], v[58:61]
	v_mfma_f32_16x16x32_bf16 v[38:41], v[152:155], v[244:247], v[38:41]
	v_mfma_f32_16x16x32_bf16 v[42:45], v[160:163], v[236:239], v[42:45]
	v_mfma_f32_16x16x32_bf16 v[30:33], v[166:169], v[182:185], v[30:33]
	v_mfma_f32_16x16x32_bf16 v[18:21], v[174:177], v[210:213], v[18:21]
	v_mfma_f32_16x16x32_bf16 v[14:17], v[166:169], v[218:221], v[14:17]
	v_mfma_f32_16x16x32_bf16 v[2:5], v[174:177], v[240:243], v[2:5]
	v_mfma_f32_16x16x32_bf16 v[22:25], v[166:169], v[210:213], v[22:25]
	v_mfma_f32_16x16x32_bf16 v[26:29], v[174:177], v[182:185], v[26:29]
	v_mfma_f32_16x16x32_bf16 v[6:9], v[166:169], v[240:243], v[6:9]
	v_mfma_f32_16x16x32_bf16 v[10:13], v[174:177], v[218:221], v[10:13]
	v_mfma_f32_16x16x32_bf16 v[30:33], v[170:173], v[206:209], v[30:33]
	v_mfma_f32_16x16x32_bf16 v[18:21], v[178:181], v[214:217], v[18:21]
	v_mfma_f32_16x16x32_bf16 v[14:17], v[170:173], v[236:239], v[14:17]
	v_mfma_f32_16x16x32_bf16 v[2:5], v[178:181], v[244:247], v[2:5]
	v_mfma_f32_16x16x32_bf16 v[22:25], v[170:173], v[214:217], v[22:25]
	v_mfma_f32_16x16x32_bf16 v[26:29], v[178:181], v[206:209], v[26:29]
	v_mfma_f32_16x16x32_bf16 v[6:9], v[170:173], v[244:247], v[6:9]
	v_mfma_f32_16x16x32_bf16 v[10:13], v[178:181], v[236:239], v[10:13]
	s_barrier
; #define PG8_STAGE(bufoff, gbase, voff) do { _Pragma("unroll") for (int _i = 0; _i < 2; ++_i) \
;         __builtin_amdgcn_global_load_lds((const unsigned*)((const char*)(gbase) + (voff)[_i]), (PG8_LAS unsigned*)(lds + (bufoff) + ldsw + _i * 8192), 16, 0, 0); } while (0)
; #define PG8_LDA(dst, b, h) do { _Pragma("unroll") for (int m = 0; m < 4; ++m) _Pragma("unroll") for (int k = 0; k < 2; ++k) dst[m][k] = *(const PG8_LAS bf16x8*)(lds + PG8_SA(b, h) + aoff + m * 2048 + k * 1024); } while (0)
; #define PG8_LDB(dst, b, h) do { _Pragma("unroll") for (int n = 0; n < 2; ++n) _Pragma("unroll") for (int k = 0; k < 2; ++k) dst[n][k] = *(const PG8_LAS bf16x8*)(lds + PG8_SB(b, h) + boff + n * 2048 + k * 1024); } while (0)
; #define PG8_MMA(ai, bj, At, Bt) do { __builtin_amdgcn_s_setprio(1); _Pragma("unroll") for (int m = 0; m < 4; ++m) _Pragma("unroll") for (int n = 0; n < 2; ++n) _Pragma("unroll") for (int k = 0; k < 2; ++k) \
;         acc[ai][bj][m][n] = __builtin_amdgcn_mfma_f32_16x16x32_bf16(Bt[n][k], At[m][k], acc[ai][bj][m][n], 0, 0, 0); __builtin_amdgcn_s_setprio(0); } while (0)
; #define PG8_WAIT_V(n) asm volatile("s_waitcnt vmcnt(" #n ")" ::: "memory")
; #define PG8_WAIT_L(n) asm volatile("s_waitcnt lgkmcnt(" #n ")" ::: "memory")
; #define PG8_BAR __builtin_amdgcn_s_barrier()
; #define PG8_SCHED __builtin_amdgcn_sched_barrier(0)
; template <class Epi, class Sched, bool ALIGN_EPI = false, bool SP2 = false>
; __device__ __forceinline__ void gemm_phase(PG8_LAS unsigned char* lds, const Gemm g, const Sched& S, const Epi& E) {
;     ...
;             PG8_LDB(B0, 1, 0); PG8_LDB(B1, 1, 1); PG8_SCHED; PG8_LDA(At, 1, 0); PG8_STAGE(PG8_SA(0, 1), a2 + hstep, voffA);
;             PG8_WAIT_V(8); PG8_WAIT_L(0); PG8_BAR; PG8_MMA(0, 0, At, B0); PG8_MMA(0, 1, At, B1); PG8_BAR; PG8_SCHED;
;             PG8_LDA(At, 1, 1); PG8_STAGE(PG8_SB(1, 0), b3, voffB); PG8_STAGE(PG8_SB(1, 1), b3 + hstepB, voffB); PG8_STAGE(PG8_SA(1, 0), a3, voffA);
;             PG8_WAIT_V(8); PG8_WAIT_L(0); PG8_BAR; PG8_MMA(1, 0, At, B0); PG8_MMA(1, 1, At, B1); PG8_BAR; PG8_SCHED;
;     ...
;         if constexpr (ALIGN_EPI) { if (wr == 0) PG8_BAR; }
	s_add_i32 s9, 0, 0x18000
	s_add_i32 s12, 0, 0x1c000
	ds_read_b128 v[148:151], v198
	ds_read_b128 v[152:155], v198 offset:1024
	ds_read_b128 v[156:159], v198 offset:2048
	ds_read_b128 v[160:163], v198 offset:3072
	ds_read_b128 v[166:169], v199
	ds_read_b128 v[170:173], v199 offset:1024
	ds_read_b128 v[174:177], v199 offset:2048
	ds_read_b128 v[178:181], v199 offset:3072
	s_add_u32 s10, s84, 0x80000
	s_addc_u32 s11, s85, 0
	s_mov_b32 m0, s42
	ds_read_b128 v[182:185], v165 offset:32768
	ds_read_b128 v[206:209], v165 offset:33792
	ds_read_b128 v[210:213], v165 offset:34816
	ds_read_b128 v[214:217], v165 offset:35840
	ds_read_b128 v[218:221], v165 offset:36864
	ds_read_b128 v[236:239], v165 offset:37888
	ds_read_b128 v[240:243], v165 offset:38912
	ds_read_b128 v[244:247], v165 offset:39936
	global_load_lds_dwordx4 v130, s[10:11]
	s_mov_b32 m0, s51
	s_nop 0
	global_load_lds_dwordx4 v134, s[10:11]
	s_waitcnt vmcnt(8)
	s_waitcnt lgkmcnt(0)
	s_barrier
	v_mfma_f32_16x16x32_bf16 v[126:129], v[148:151], v[182:185], v[126:129]
	v_mfma_f32_16x16x32_bf16 v[114:117], v[156:159], v[210:213], v[114:117]
	v_mfma_f32_16x16x32_bf16 v[110:113], v[148:151], v[218:221], v[110:113]
	v_mfma_f32_16x16x32_bf16 v[98:101], v[156:159], v[240:243], v[98:101]
	v_mfma_f32_16x16x32_bf16 v[118:121], v[148:151], v[210:213], v[118:121]
	v_mfma_f32_16x16x32_bf16 v[122:125], v[156:159], v[182:185], v[122:125]
	v_mfma_f32_16x16x32_bf16 v[102:105], v[148:151], v[240:243], v[102:105]
	v_mfma_f32_16x16x32_bf16 v[106:109], v[156:159], v[218:221], v[106:109]
	v_mfma_f32_16x16x32_bf16 v[126:129], v[152:155], v[206:209], v[126:129]
	v_mfma_f32_16x16x32_bf16 v[114:117], v[160:163], v[214:217], v[114:117]
	v_mfma_f32_16x16x32_bf16 v[110:113], v[152:155], v[236:239], v[110:113]
	v_mfma_f32_16x16x32_bf16 v[98:101], v[160:163], v[244:247], v[98:101]
	v_mfma_f32_16x16x32_bf16 v[118:121], v[152:155], v[214:217], v[118:121]
	v_mfma_f32_16x16x32_bf16 v[122:125], v[160:163], v[206:209], v[122:125]
	v_mfma_f32_16x16x32_bf16 v[102:105], v[152:155], v[244:247], v[102:105]
	v_mfma_f32_16x16x32_bf16 v[106:109], v[160:163], v[236:239], v[106:109]
	v_mfma_f32_16x16x32_bf16 v[94:97], v[166:169], v[182:185], v[94:97]
	v_mfma_f32_16x16x32_bf16 v[82:85], v[174:177], v[210:213], v[82:85]
	v_mfma_f32_16x16x32_bf16 v[78:81], v[166:169], v[218:221], v[78:81]
	v_mfma_f32_16x16x32_bf16 v[66:69], v[174:177], v[240:243], v[66:69]
	v_mfma_f32_16x16x32_bf16 v[86:89], v[166:169], v[210:213], v[86:89]
	v_mfma_f32_16x16x32_bf16 v[90:93], v[174:177], v[182:185], v[90:93]
	v_mfma_f32_16x16x32_bf16 v[70:73], v[166:169], v[240:243], v[70:73]
	v_mfma_f32_16x16x32_bf16 v[74:77], v[174:177], v[218:221], v[74:77]
	v_mfma_f32_16x16x32_bf16 v[94:97], v[170:173], v[206:209], v[94:97]
	v_mfma_f32_16x16x32_bf16 v[82:85], v[178:181], v[214:217], v[82:85]
	v_mfma_f32_16x16x32_bf16 v[78:81], v[170:173], v[236:239], v[78:81]
	v_mfma_f32_16x16x32_bf16 v[66:69], v[178:181], v[244:247], v[66:69]
	v_mfma_f32_16x16x32_bf16 v[86:89], v[170:173], v[214:217], v[86:89]
	v_mfma_f32_16x16x32_bf16 v[90:93], v[178:181], v[206:209], v[90:93]
	v_mfma_f32_16x16x32_bf16 v[70:73], v[170:173], v[244:247], v[70:73]
	v_mfma_f32_16x16x32_bf16 v[74:77], v[178:181], v[236:239], v[74:77]
	s_barrier
	s_add_i32 s9, s9, s0
	s_mov_b32 m0, s9
	ds_read_b128 v[182:185], v165 offset:49152
	ds_read_b128 v[206:209], v165 offset:50176
	ds_read_b128 v[210:213], v165 offset:51200
	ds_read_b128 v[214:217], v165 offset:52224
	ds_read_b128 v[218:221], v165 offset:53248
	ds_read_b128 v[236:239], v165 offset:54272
	ds_read_b128 v[240:243], v165 offset:55296
	ds_read_b128 v[244:247], v165 offset:56320
	s_add_u32 s100, s80, s60
	s_addc_u32 s101, s81, s61
	global_load_lds_dwordx4 v132, s[100:101]
	s_add_i32 m0, s9, 0x2000
	s_add_u32 s10, s80, 0x20080
	s_addc_u32 s11, s81, 0
	s_add_i32 s9, s12, s0
	global_load_lds_dwordx4 v136, s[100:101]
	s_mov_b32 m0, s9
	s_nop 0
	global_load_lds_dwordx4 v132, s[10:11]
	s_add_i32 m0, s9, 0x2000
	s_nop 0
	global_load_lds_dwordx4 v136, s[10:11]
	s_mov_b32 m0, s66
	s_add_u32 s100, s84, s60
	s_addc_u32 s101, s85, s61
	global_load_lds_dwordx4 v130, s[100:101]
	s_mov_b32 m0, s67
	s_nop 0
	global_load_lds_dwordx4 v134, s[100:101]
	s_waitcnt vmcnt(8)
	s_waitcnt lgkmcnt(0)
	s_barrier
	v_mfma_f32_16x16x32_bf16 v[62:65], v[148:151], v[182:185], v[62:65]
	v_mfma_f32_16x16x32_bf16 v[50:53], v[156:159], v[210:213], v[50:53]
	v_mfma_f32_16x16x32_bf16 v[46:49], v[148:151], v[218:221], v[46:49]
	v_mfma_f32_16x16x32_bf16 v[34:37], v[156:159], v[240:243], v[34:37]
	v_mfma_f32_16x16x32_bf16 v[54:57], v[148:151], v[210:213], v[54:57]
	v_mfma_f32_16x16x32_bf16 v[58:61], v[156:159], v[182:185], v[58:61]
	v_mfma_f32_16x16x32_bf16 v[38:41], v[148:151], v[240:243], v[38:41]
	v_mfma_f32_16x16x32_bf16 v[42:45], v[156:159], v[218:221], v[42:45]
	v_mfma_f32_16x16x32_bf16 v[62:65], v[152:155], v[206:209], v[62:65]
	v_mfma_f32_16x16x32_bf16 v[50:53], v[160:163], v[214:217], v[50:53]
	v_mfma_f32_16x16x32_bf16 v[46:49], v[152:155], v[236:239], v[46:49]
	v_mfma_f32_16x16x32_bf16 v[34:37], v[160:163], v[244:247], v[34:37]
	v_mfma_f32_16x16x32_bf16 v[54:57], v[152:155], v[214:217], v[54:57]
	v_mfma_f32_16x16x32_bf16 v[58:61], v[160:163], v[206:209], v[58:61]
	v_mfma_f32_16x16x32_bf16 v[38:41], v[152:155], v[244:247], v[38:41]
	v_mfma_f32_16x16x32_bf16 v[42:45], v[160:163], v[236:239], v[42:45]
	v_mfma_f32_16x16x32_bf16 v[30:33], v[166:169], v[182:185], v[30:33]
	v_mfma_f32_16x16x32_bf16 v[18:21], v[174:177], v[210:213], v[18:21]
	v_mfma_f32_16x16x32_bf16 v[14:17], v[166:169], v[218:221], v[14:17]
	v_mfma_f32_16x16x32_bf16 v[2:5], v[174:177], v[240:243], v[2:5]
	v_mfma_f32_16x16x32_bf16 v[22:25], v[166:169], v[210:213], v[22:25]
	v_mfma_f32_16x16x32_bf16 v[26:29], v[174:177], v[182:185], v[26:29]
	v_mfma_f32_16x16x32_bf16 v[6:9], v[166:169], v[240:243], v[6:9]
	v_mfma_f32_16x16x32_bf16 v[10:13], v[174:177], v[218:221], v[10:13]
	v_mfma_f32_16x16x32_bf16 v[30:33], v[170:173], v[206:209], v[30:33]
	v_mfma_f32_16x16x32_bf16 v[18:21], v[178:181], v[214:217], v[18:21]
	v_mfma_f32_16x16x32_bf16 v[14:17], v[170:173], v[236:239], v[14:17]
	v_mfma_f32_16x16x32_bf16 v[2:5], v[178:181], v[244:247], v[2:5]
	v_mfma_f32_16x16x32_bf16 v[22:25], v[170:173], v[214:217], v[22:25]
	v_mfma_f32_16x16x32_bf16 v[26:29], v[178:181], v[206:209], v[26:29]
	v_mfma_f32_16x16x32_bf16 v[6:9], v[170:173], v[244:247], v[6:9]
	v_mfma_f32_16x16x32_bf16 v[10:13], v[178:181], v[236:239], v[10:13]
	s_barrier
	s_add_i32 s8, s8, 2
	s_add_u32 s46, s46, 0x100
	s_addc_u32 s47, s47, 0
	s_cmp_gt_u32 s8, 29
	s_cbranch_scc0 .LBB0_170
	s_and_b64 vcc, exec, s[54:55]
	s_cbranch_vccz .LBB0_173
	s_barrier

; #define PG8_STAGE(bufoff, gbase, voff) do { _Pragma("unroll") for (int _i = 0; _i < 2; ++_i) \
;         __builtin_amdgcn_global_load_lds((const unsigned*)((const char*)(gbase) + (voff)[_i]), (PG8_LAS unsigned*)(lds + (bufoff) + ldsw + _i * 8192), 16, 0, 0); } while (0)
; #define PG8_LDA(dst, b, h) do { _Pragma("unroll") for (int m = 0; m < 4; ++m) _Pragma("unroll") for (int k = 0; k < 2; ++k) dst[m][k] = *(const PG8_LAS bf16x8*)(lds + PG8_SA(b, h) + aoff + m * 2048 + k * 1024); } while (0)
; #define PG8_LDB(dst, b, h) do { _Pragma("unroll") for (int n = 0; n < 2; ++n) _Pragma("unroll") for (int k = 0; k < 2; ++k) dst[n][k] = *(const PG8_LAS bf16x8*)(lds + PG8_SB(b, h) + boff + n * 2048 + k * 1024); } while (0)
; #define PG8_MMA(ai, bj, At, Bt) do { __builtin_amdgcn_s_setprio(1); _Pragma("unroll") for (int m = 0; m < 4; ++m) _Pragma("unroll") for (int n = 0; n < 2; ++n) _Pragma("unroll") for (int k = 0; k < 2; ++k) \
;         acc[ai][bj][m][n] = __builtin_amdgcn_mfma_f32_16x16x32_bf16(Bt[n][k], At[m][k], acc[ai][bj][m][n], 0, 0, 0); __builtin_amdgcn_s_setprio(0); } while (0)
; #define PG8_BAR __builtin_amdgcn_s_barrier()
; template <class Epi, class Sched, bool ALIGN_EPI = false, bool SP2 = false>
; __device__ __forceinline__ void gemm_phase(PG8_LAS unsigned char* lds, const Gemm g, const Sched& S, const Epi& E) {
;     ...
;         const bool has_next = S.next(ui + 1, nxt);
;         const char* nA = has_next ? (const char*)g.A + (size_t)nxt.pm * tstep : cA; const char* nB = has_next ? (const char*)g.Bt + (size_t)nxt.pn * tstep : cB;
;         for (int t = 0; t < nt; t += 2) {
;             const bool last = (t == nt - 2);
;             const char* a1 = cA + (size_t)(t + 1) * kstep;
;             const char* a2 = last ? nA : cA + (size_t)(t + 2) * kstep; const char* b2 = last ? nB : cB + (size_t)(t + 2) * kstep;
;             const char* a3 = a2 + kstep; const char* b3 = b2 + kstep;
;             if (last && has_next) S.a_ready(nxt);
;             if constexpr (SP2) {
;             PG8_LDB(B0, 0, 0); PG8_LDB(B1, 0, 1); PG8_SCHED; PG8_LDA(At, 0, 0); PG8_STAGE(PG8_SA(1, 1), a1 + hstep, voffA);
;             PG8_WAIT_V(8); PG8_WAIT_L(0); PG8_BAR; PG8_MMA(0, 0, At, B0); PG8_MMA(0, 1, At, B1); PG8_BAR; PG8_SCHED;
;             PG8_LDA(At, 0, 1); PG8_STAGE(PG8_SB(0, 0), b2, voffB); PG8_STAGE(PG8_SB(0, 1), b2 + hstepB, voffB); PG8_STAGE(PG8_SA(0, 0), a2, voffA);
.LBB0_926:
	s_ashr_i32 s73, s72, 31
	s_lshl_b64 s[4:5], s[72:73], 20
	v_readlane_b32 s6, v249, 9
	v_readlane_b32 s7, v249, 10
	s_add_u32 s76, s6, s4
	s_addc_u32 s77, s7, s5
	s_and_b64 s[4:5], s[92:93], exec
	s_cselect_b32 s36, s77, s39
	s_cselect_b32 s37, s76, s38
	s_ashr_i32 s69, s68, 31
	s_lshl_b64 s[4:5], s[68:69], 20
	v_readlane_b32 s6, v249, 17
	v_readlane_b32 s7, v249, 18
	s_add_u32 s80, s6, s4
	s_addc_u32 s81, s7, s5
	s_and_b64 s[4:5], s[92:93], exec
	s_cselect_b32 s4, s81, s47
	s_cselect_b32 s5, s80, s46
	s_add_u32 s38, s38, 0x80080
	s_addc_u32 s39, s39, 0
	s_add_u32 s6, s46, 0x100
	v_mov_b32_e32 v2, 0
	s_addc_u32 s7, s47, 0
	s_mov_b32 s8, -2
	v_mov_b32_e32 v3, v2
	v_mov_b32_e32 v4, v2
	v_mov_b32_e32 v5, v2
	v_mov_b32_e32 v6, v2
	v_mov_b32_e32 v7, v2
	v_mov_b32_e32 v8, v2
	v_mov_b32_e32 v9, v2
	v_mov_b32_e32 v18, v2
	v_mov_b32_e32 v19, v2
	v_mov_b32_e32 v20, v2
	v_mov_b32_e32 v21, v2
	v_mov_b32_e32 v22, v2
	v_mov_b32_e32 v23, v2
	v_mov_b32_e32 v24, v2
	v_mov_b32_e32 v25, v2
	v_mov_b32_e32 v34, v2
	s_waitcnt lgkmcnt(0)
	v_add_u32_e32 v186, 0x10000, v193
	v_add_u32_e32 v187, 0x14000, v193
	v_add_u32_e32 v198, 0x18000, v193
	v_add_u32_e32 v199, 0x1c000, v193
	s_add_u32 s9, s38, 0xfff80080
	s_addc_u32 s10, s39, -1
	s_add_i32 s11, 0, 0x10000
	s_cmp_eq_u32 s8, 28
	s_cselect_b32 s95, s36, s10
	s_cselect_b32 s94, s37, s9
	s_cselect_b32 s47, s4, s7
	s_cselect_b32 s46, s5, s6
	s_add_i32 s9, 0, 0x14000
	ds_read_b128 v[66:69], v186
	ds_read_b128 v[70:73], v186 offset:1024
	ds_read_b128 v[78:81], v186 offset:2048
	ds_read_b128 v[86:89], v186 offset:3072
	ds_read_b128 v[146:149], v187
	ds_read_b128 v[150:153], v187 offset:1024
	ds_read_b128 v[154:157], v187 offset:2048
	ds_read_b128 v[158:161], v187 offset:3072
	s_add_i32 m0, s66, 0xc000
	ds_read_b128 v[162:165], v236
	ds_read_b128 v[166:169], v236 offset:1024
	ds_read_b128 v[170:173], v236 offset:2048
	ds_read_b128 v[174:177], v236 offset:3072
	ds_read_b128 v[178:181], v236 offset:4096
	ds_read_b128 v[182:185], v236 offset:5120
	ds_read_b128 v[216:219], v236 offset:6144
	ds_read_b128 v[220:223], v236 offset:7168
	global_load_lds_dwordx4 v212, s[38:39]
	s_add_i32 m0, s66, 0xe000
	s_nop 0
	global_load_lds_dwordx4 v214, s[38:39]
	s_waitcnt vmcnt(8)
	s_waitcnt lgkmcnt(0)
	s_barrier
	v_mfma_f32_16x16x32_bf16 v[142:145], v[66:69], v[162:165], 0
	v_mfma_f32_16x16x32_bf16 v[122:125], v[78:81], v[170:173], 0
	v_mfma_f32_16x16x32_bf16 v[110:113], v[66:69], v[178:181], 0
	v_mfma_f32_16x16x32_bf16 v[90:93], v[78:81], v[216:219], 0
	v_mfma_f32_16x16x32_bf16 v[126:129], v[66:69], v[170:173], 0
	v_mfma_f32_16x16x32_bf16 v[138:141], v[78:81], v[162:165], 0
	v_mfma_f32_16x16x32_bf16 v[94:97], v[66:69], v[216:219], 0
	v_mfma_f32_16x16x32_bf16 v[106:109], v[78:81], v[178:181], 0
	v_mfma_f32_16x16x32_bf16 v[142:145], v[70:73], v[166:169], v[142:145]
	v_mfma_f32_16x16x32_bf16 v[122:125], v[86:89], v[174:177], v[122:125]
	v_mfma_f32_16x16x32_bf16 v[110:113], v[70:73], v[182:185], v[110:113]
	v_mfma_f32_16x16x32_bf16 v[90:93], v[86:89], v[220:223], v[90:93]
	v_mfma_f32_16x16x32_bf16 v[126:129], v[70:73], v[174:177], v[126:129]
	v_mfma_f32_16x16x32_bf16 v[138:141], v[86:89], v[166:169], v[138:141]
	v_mfma_f32_16x16x32_bf16 v[94:97], v[70:73], v[220:223], v[94:97]
	v_mfma_f32_16x16x32_bf16 v[106:109], v[86:89], v[182:185], v[106:109]
	v_mfma_f32_16x16x32_bf16 v[134:137], v[146:149], v[162:165], 0
	v_mfma_f32_16x16x32_bf16 v[114:117], v[154:157], v[170:173], 0
	v_mfma_f32_16x16x32_bf16 v[102:105], v[146:149], v[178:181], 0
	v_mfma_f32_16x16x32_bf16 v[74:77], v[154:157], v[216:219], 0
	v_mfma_f32_16x16x32_bf16 v[118:121], v[146:149], v[170:173], 0
	v_mfma_f32_16x16x32_bf16 v[130:133], v[154:157], v[162:165], 0
	v_mfma_f32_16x16x32_bf16 v[82:85], v[146:149], v[216:219], 0
	v_mfma_f32_16x16x32_bf16 v[98:101], v[154:157], v[178:181], 0
	v_mfma_f32_16x16x32_bf16 v[134:137], v[150:153], v[166:169], v[134:137]
	v_mfma_f32_16x16x32_bf16 v[114:117], v[158:161], v[174:177], v[114:117]
	v_mfma_f32_16x16x32_bf16 v[102:105], v[150:153], v[182:185], v[102:105]
	v_mfma_f32_16x16x32_bf16 v[74:77], v[158:161], v[220:223], v[74:77]
	v_mfma_f32_16x16x32_bf16 v[118:121], v[150:153], v[174:177], v[118:121]
	v_mfma_f32_16x16x32_bf16 v[130:133], v[158:161], v[166:169], v[130:133]
	v_mfma_f32_16x16x32_bf16 v[82:85], v[150:153], v[220:223], v[82:85]
	v_mfma_f32_16x16x32_bf16 v[98:101], v[158:161], v[182:185], v[98:101]
	s_barrier
	s_add_i32 s10, s11, s25
	s_mov_b32 m0, s10
	ds_read_b128 v[162:165], v236 offset:16384
	ds_read_b128 v[166:169], v236 offset:17408
	ds_read_b128 v[170:173], v236 offset:18432
	ds_read_b128 v[174:177], v236 offset:19456
	ds_read_b128 v[178:181], v236 offset:20480
	ds_read_b128 v[182:185], v236 offset:21504
	ds_read_b128 v[216:219], v236 offset:22528
	ds_read_b128 v[220:223], v236 offset:23552
	global_load_lds_dwordx4 v190, s[46:47]
	s_add_i32 m0, s10, 0x2000
	s_add_u32 s10, s46, 0x20000
	s_addc_u32 s11, s47, 0
	s_add_i32 s9, s9, s25
	global_load_lds_dwordx4 v206, s[46:47]
	s_mov_b32 m0, s9
	s_nop 0
	global_load_lds_dwordx4 v190, s[10:11]
	s_add_i32 m0, s9, 0x2000
	s_nop 0
	global_load_lds_dwordx4 v206, s[10:11]
	s_mov_b32 m0, s66
	s_nop 0
	global_load_lds_dwordx4 v210, s[94:95]
	s_mov_b32 m0, s67
	s_nop 0
	global_load_lds_dwordx4 v208, s[94:95]
	s_waitcnt vmcnt(8)
	s_waitcnt lgkmcnt(0)
	s_barrier
; #define PG8_STAGE(bufoff, gbase, voff) do { _Pragma("unroll") for (int _i = 0; _i < 2; ++_i) \
;         __builtin_amdgcn_global_load_lds((const unsigned*)((const char*)(gbase) + (voff)[_i]), (PG8_LAS unsigned*)(lds + (bufoff) + ldsw + _i * 8192), 16, 0, 0); } while (0)
; #define PG8_LDA(dst, b, h) do { _Pragma("unroll") for (int m = 0; m < 4; ++m) _Pragma("unroll") for (int k = 0; k < 2; ++k) dst[m][k] = *(const PG8_LAS bf16x8*)(lds + PG8_SA(b, h) + aoff + m * 2048 + k * 1024); } while (0)
; #define PG8_LDB(dst, b, h) do { _Pragma("unroll") for (int n = 0; n < 2; ++n) _Pragma("unroll") for (int k = 0; k < 2; ++k) dst[n][k] = *(const PG8_LAS bf16x8*)(lds + PG8_SB(b, h) + boff + n * 2048 + k * 1024); } while (0)
; #define PG8_MMA(ai, bj, At, Bt) do { __builtin_amdgcn_s_setprio(1); _Pragma("unroll") for (int m = 0; m < 4; ++m) _Pragma("unroll") for (int n = 0; n < 2; ++n) _Pragma("unroll") for (int k = 0; k < 2; ++k) \
;         acc[ai][bj][m][n] = __builtin_amdgcn_mfma_f32_16x16x32_bf16(Bt[n][k], At[m][k], acc[ai][bj][m][n], 0, 0, 0); __builtin_amdgcn_s_setprio(0); } while (0)
; #define PG8_WAIT_V(n) asm volatile("s_waitcnt vmcnt(" #n ")" ::: "memory")
; #define PG8_WAIT_L(n) asm volatile("s_waitcnt lgkmcnt(" #n ")" ::: "memory")
; #define PG8_BAR __builtin_amdgcn_s_barrier()
; #define PG8_SCHED __builtin_amdgcn_sched_barrier(0)
; template <class Epi, class Sched, bool ALIGN_EPI = false, bool SP2 = false>
; __device__ __forceinline__ void gemm_phase(PG8_LAS unsigned char* lds, const Gemm g, const Sched& S, const Epi& E) {
;     ...
;             PG8_WAIT_V(8); PG8_WAIT_L(0); PG8_BAR; PG8_MMA(1, 0, At, B0); PG8_MMA(1, 1, At, B1); PG8_BAR; PG8_SCHED;
;             PG8_LDB(B0, 1, 0); PG8_LDB(B1, 1, 1); PG8_SCHED; PG8_LDA(At, 1, 0); PG8_STAGE(PG8_SA(0, 1), a2 + hstep, voffA);
;             PG8_WAIT_V(8); PG8_WAIT_L(0); PG8_BAR; PG8_MMA(0, 0, At, B0); PG8_MMA(0, 1, At, B1); PG8_BAR; PG8_SCHED;
	v_mfma_f32_16x16x32_bf16 v[62:65], v[66:69], v[162:165], 0
	v_mfma_f32_16x16x32_bf16 v[42:45], v[78:81], v[170:173], 0
	v_mfma_f32_16x16x32_bf16 v[30:33], v[66:69], v[178:181], 0
	v_mfma_f32_16x16x32_bf16 v[10:13], v[78:81], v[216:219], 0
	v_mfma_f32_16x16x32_bf16 v[46:49], v[66:69], v[170:173], 0
	v_mfma_f32_16x16x32_bf16 v[58:61], v[78:81], v[162:165], 0
	v_mfma_f32_16x16x32_bf16 v[14:17], v[66:69], v[216:219], 0
	v_mfma_f32_16x16x32_bf16 v[26:29], v[78:81], v[178:181], 0
	v_mfma_f32_16x16x32_bf16 v[62:65], v[70:73], v[166:169], v[62:65]
	v_mfma_f32_16x16x32_bf16 v[42:45], v[86:89], v[174:177], v[42:45]
	v_mfma_f32_16x16x32_bf16 v[30:33], v[70:73], v[182:185], v[30:33]
	v_mfma_f32_16x16x32_bf16 v[10:13], v[86:89], v[220:223], v[10:13]
	v_mfma_f32_16x16x32_bf16 v[46:49], v[70:73], v[174:177], v[46:49]
	v_mfma_f32_16x16x32_bf16 v[58:61], v[86:89], v[166:169], v[58:61]
	v_mfma_f32_16x16x32_bf16 v[14:17], v[70:73], v[220:223], v[14:17]
	v_mfma_f32_16x16x32_bf16 v[26:29], v[86:89], v[182:185], v[26:29]
	v_mfma_f32_16x16x32_bf16 v[54:57], v[146:149], v[162:165], 0
	v_mfma_f32_16x16x32_bf16 v[34:37], v[154:157], v[170:173], 0
	v_mfma_f32_16x16x32_bf16 v[22:25], v[146:149], v[178:181], 0
	v_mfma_f32_16x16x32_bf16 v[2:5], v[154:157], v[216:219], 0
	v_mfma_f32_16x16x32_bf16 v[38:41], v[146:149], v[170:173], 0
	v_mfma_f32_16x16x32_bf16 v[50:53], v[154:157], v[162:165], 0
	v_mfma_f32_16x16x32_bf16 v[6:9], v[146:149], v[216:219], 0
	v_mfma_f32_16x16x32_bf16 v[18:21], v[154:157], v[178:181], 0
	v_mfma_f32_16x16x32_bf16 v[54:57], v[150:153], v[166:169], v[54:57]
	v_mfma_f32_16x16x32_bf16 v[34:37], v[158:161], v[174:177], v[34:37]
	v_mfma_f32_16x16x32_bf16 v[22:25], v[150:153], v[182:185], v[22:25]
	v_mfma_f32_16x16x32_bf16 v[2:5], v[158:161], v[220:223], v[2:5]
	v_mfma_f32_16x16x32_bf16 v[38:41], v[150:153], v[174:177], v[38:41]
	v_mfma_f32_16x16x32_bf16 v[50:53], v[158:161], v[166:169], v[50:53]
	v_mfma_f32_16x16x32_bf16 v[6:9], v[150:153], v[220:223], v[6:9]
	v_mfma_f32_16x16x32_bf16 v[18:21], v[158:161], v[182:185], v[18:21]
	s_barrier
	s_add_i32 s9, 0, 0x18000
	s_add_i32 s12, 0, 0x1c000
	ds_read_b128 v[66:69], v198
	ds_read_b128 v[70:73], v198 offset:1024
	ds_read_b128 v[78:81], v198 offset:2048
	ds_read_b128 v[86:89], v198 offset:3072
	ds_read_b128 v[146:149], v199
	ds_read_b128 v[150:153], v199 offset:1024
	ds_read_b128 v[154:157], v199 offset:2048
	ds_read_b128 v[158:161], v199 offset:3072
	s_add_u32 s10, s94, 0x80000
	s_addc_u32 s11, s95, 0
	s_mov_b32 m0, s59
	ds_read_b128 v[162:165], v236 offset:32768
	ds_read_b128 v[166:169], v236 offset:33792
	ds_read_b128 v[170:173], v236 offset:34816
	ds_read_b128 v[174:177], v236 offset:35840
	ds_read_b128 v[178:181], v236 offset:36864
	ds_read_b128 v[182:185], v236 offset:37888
	ds_read_b128 v[216:219], v236 offset:38912
	ds_read_b128 v[220:223], v236 offset:39936
	global_load_lds_dwordx4 v210, s[10:11]
	s_mov_b32 m0, s74
	s_nop 0
	global_load_lds_dwordx4 v208, s[10:11]
	s_waitcnt vmcnt(8)
	s_waitcnt lgkmcnt(0)
	s_barrier
	v_mfma_f32_16x16x32_bf16 v[142:145], v[66:69], v[162:165], v[142:145]
	v_mfma_f32_16x16x32_bf16 v[122:125], v[78:81], v[170:173], v[122:125]
	v_mfma_f32_16x16x32_bf16 v[110:113], v[66:69], v[178:181], v[110:113]
	v_mfma_f32_16x16x32_bf16 v[90:93], v[78:81], v[216:219], v[90:93]
	v_mfma_f32_16x16x32_bf16 v[126:129], v[66:69], v[170:173], v[126:129]
	v_mfma_f32_16x16x32_bf16 v[138:141], v[78:81], v[162:165], v[138:141]
	v_mfma_f32_16x16x32_bf16 v[94:97], v[66:69], v[216:219], v[94:97]
	v_mfma_f32_16x16x32_bf16 v[106:109], v[78:81], v[178:181], v[106:109]
	v_mfma_f32_16x16x32_bf16 v[142:145], v[70:73], v[166:169], v[142:145]
	v_mfma_f32_16x16x32_bf16 v[122:125], v[86:89], v[174:177], v[122:125]
	v_mfma_f32_16x16x32_bf16 v[110:113], v[70:73], v[182:185], v[110:113]
	v_mfma_f32_16x16x32_bf16 v[90:93], v[86:89], v[220:223], v[90:93]
	v_mfma_f32_16x16x32_bf16 v[126:129], v[70:73], v[174:177], v[126:129]
	v_mfma_f32_16x16x32_bf16 v[138:141], v[86:89], v[166:169], v[138:141]
	v_mfma_f32_16x16x32_bf16 v[94:97], v[70:73], v[220:223], v[94:97]
	v_mfma_f32_16x16x32_bf16 v[106:109], v[86:89], v[182:185], v[106:109]
	v_mfma_f32_16x16x32_bf16 v[134:137], v[146:149], v[162:165], v[134:137]
	v_mfma_f32_16x16x32_bf16 v[114:117], v[154:157], v[170:173], v[114:117]
	v_mfma_f32_16x16x32_bf16 v[102:105], v[146:149], v[178:181], v[102:105]
	v_mfma_f32_16x16x32_bf16 v[74:77], v[154:157], v[216:219], v[74:77]
	v_mfma_f32_16x16x32_bf16 v[118:121], v[146:149], v[170:173], v[118:121]
	v_mfma_f32_16x16x32_bf16 v[130:133], v[154:157], v[162:165], v[130:133]
	v_mfma_f32_16x16x32_bf16 v[82:85], v[146:149], v[216:219], v[82:85]
	v_mfma_f32_16x16x32_bf16 v[98:101], v[154:157], v[178:181], v[98:101]
	v_mfma_f32_16x16x32_bf16 v[134:137], v[150:153], v[166:169], v[134:137]
	v_mfma_f32_16x16x32_bf16 v[114:117], v[158:161], v[174:177], v[114:117]
	v_mfma_f32_16x16x32_bf16 v[102:105], v[150:153], v[182:185], v[102:105]
	v_mfma_f32_16x16x32_bf16 v[74:77], v[158:161], v[220:223], v[74:77]
	v_mfma_f32_16x16x32_bf16 v[118:121], v[150:153], v[174:177], v[118:121]
	v_mfma_f32_16x16x32_bf16 v[130:133], v[158:161], v[166:169], v[130:133]
	v_mfma_f32_16x16x32_bf16 v[82:85], v[150:153], v[220:223], v[82:85]
	v_mfma_f32_16x16x32_bf16 v[98:101], v[158:161], v[182:185], v[98:101]
	s_barrier
; #define PG8_STAGE(bufoff, gbase, voff) do { _Pragma("unroll") for (int _i = 0; _i < 2; ++_i) \
;         __builtin_amdgcn_global_load_lds((const unsigned*)((const char*)(gbase) + (voff)[_i]), (PG8_LAS unsigned*)(lds + (bufoff) + ldsw + _i * 8192), 16, 0, 0); } while (0)
; #define PG8_LDA(dst, b, h) do { _Pragma("unroll") for (int m = 0; m < 4; ++m) _Pragma("unroll") for (int k = 0; k < 2; ++k) dst[m][k] = *(const PG8_LAS bf16x8*)(lds + PG8_SA(b, h) + aoff + m * 2048 + k * 1024); } while (0)
; #define PG8_LDB(dst, b, h) do { _Pragma("unroll") for (int n = 0; n < 2; ++n) _Pragma("unroll") for (int k = 0; k < 2; ++k) dst[n][k] = *(const PG8_LAS bf16x8*)(lds + PG8_SB(b, h) + boff + n * 2048 + k * 1024); } while (0)
; template <class Epi, class Sched, bool ALIGN_EPI = false, bool SP2 = false>
; __device__ __forceinline__ void gemm_phase(PG8_LAS unsigned char* lds, const Gemm g, const Sched& S, const Epi& E) {
;     ...
;         for (int t = 0; t < nt; t += 2) {
;             const bool last = (t == nt - 2);
;             const char* a1 = cA + (size_t)(t + 1) * kstep;
;             const char* a2 = last ? nA : cA + (size_t)(t + 2) * kstep; const char* b2 = last ? nB : cB + (size_t)(t + 2) * kstep;
;             const char* a3 = a2 + kstep; const char* b3 = b2 + kstep;
;             if (last && has_next) S.a_ready(nxt);
;             if constexpr (SP2) {
;             PG8_LDB(B0, 0, 0); PG8_LDB(B1, 0, 1); PG8_SCHED; PG8_LDA(At, 0, 0); PG8_STAGE(PG8_SA(1, 1), a1 + hstep, voffA);
;             PG8_WAIT_V(8); PG8_WAIT_L(0); PG8_BAR; PG8_MMA(0, 0, At, B0); PG8_MMA(0, 1, At, B1); PG8_BAR; PG8_SCHED;
;             PG8_LDA(At, 0, 1); PG8_STAGE(PG8_SB(0, 0), b2, voffB); PG8_STAGE(PG8_SB(0, 1), b2 + hstepB, voffB); PG8_STAGE(PG8_SA(0, 0), a2, voffA);
;             PG8_WAIT_V(8); PG8_WAIT_L(0); PG8_BAR; PG8_MMA(1, 0, At, B0); PG8_MMA(1, 1, At, B1); PG8_BAR; PG8_SCHED;
;             PG8_LDB(B0, 1, 0); PG8_LDB(B1, 1, 1); PG8_SCHED; PG8_LDA(At, 1, 0); PG8_STAGE(PG8_SA(0, 1), a2 + hstep, voffA);
;             PG8_WAIT_V(8); PG8_WAIT_L(0); PG8_BAR; PG8_MMA(0, 0, At, B0); PG8_MMA(0, 1, At, B1); PG8_BAR; PG8_SCHED;
;             PG8_LDA(At, 1, 1); PG8_STAGE(PG8_SB(1, 0), b3, voffB); PG8_STAGE(PG8_SB(1, 1), b3 + hstepB, voffB); PG8_STAGE(PG8_SA(1, 0), a3, voffA);
;             PG8_WAIT_V(8); PG8_WAIT_L(0); PG8_BAR; PG8_MMA(1, 0, At, B0); PG8_MMA(1, 1, At, B1); PG8_BAR; PG8_SCHED;
	s_add_i32 s9, s9, s25
	s_mov_b32 m0, s9
	ds_read_b128 v[162:165], v236 offset:49152
	ds_read_b128 v[166:169], v236 offset:50176
	ds_read_b128 v[170:173], v236 offset:51200
	ds_read_b128 v[174:177], v236 offset:52224
	ds_read_b128 v[178:181], v236 offset:53248
	ds_read_b128 v[182:185], v236 offset:54272
	ds_read_b128 v[216:219], v236 offset:55296
	ds_read_b128 v[220:223], v236 offset:56320
	s_add_u32 s100, s46, s60
	s_addc_u32 s101, s47, s61
	global_load_lds_dwordx4 v190, s[100:101]
	s_add_i32 m0, s9, 0x2000
	s_add_u32 s10, s46, 0x20080
	s_addc_u32 s11, s47, 0
	s_add_i32 s9, s12, s25
	global_load_lds_dwordx4 v206, s[100:101]
	s_mov_b32 m0, s9
	s_nop 0
	global_load_lds_dwordx4 v190, s[10:11]
	s_add_i32 m0, s9, 0x2000
	s_nop 0
	global_load_lds_dwordx4 v206, s[10:11]
	s_mov_b32 m0, s75
	s_add_u32 s100, s94, s60
	s_addc_u32 s101, s95, s61
	global_load_lds_dwordx4 v210, s[100:101]
	s_mov_b32 m0, s0
	s_nop 0
	global_load_lds_dwordx4 v208, s[100:101]
	s_waitcnt vmcnt(8)
	s_waitcnt lgkmcnt(0)
	s_barrier
	v_mfma_f32_16x16x32_bf16 v[62:65], v[66:69], v[162:165], v[62:65]
	v_mfma_f32_16x16x32_bf16 v[42:45], v[78:81], v[170:173], v[42:45]
	v_mfma_f32_16x16x32_bf16 v[30:33], v[66:69], v[178:181], v[30:33]
	v_mfma_f32_16x16x32_bf16 v[10:13], v[78:81], v[216:219], v[10:13]
	v_mfma_f32_16x16x32_bf16 v[46:49], v[66:69], v[170:173], v[46:49]
	v_mfma_f32_16x16x32_bf16 v[58:61], v[78:81], v[162:165], v[58:61]
	v_mfma_f32_16x16x32_bf16 v[14:17], v[66:69], v[216:219], v[14:17]
	v_mfma_f32_16x16x32_bf16 v[26:29], v[78:81], v[178:181], v[26:29]
	v_mfma_f32_16x16x32_bf16 v[62:65], v[70:73], v[166:169], v[62:65]
	v_mfma_f32_16x16x32_bf16 v[42:45], v[86:89], v[174:177], v[42:45]
	v_mfma_f32_16x16x32_bf16 v[30:33], v[70:73], v[182:185], v[30:33]
	v_mfma_f32_16x16x32_bf16 v[10:13], v[86:89], v[220:223], v[10:13]
	v_mfma_f32_16x16x32_bf16 v[46:49], v[70:73], v[174:177], v[46:49]
	v_mfma_f32_16x16x32_bf16 v[58:61], v[86:89], v[166:169], v[58:61]
	v_mfma_f32_16x16x32_bf16 v[14:17], v[70:73], v[220:223], v[14:17]
	v_mfma_f32_16x16x32_bf16 v[26:29], v[86:89], v[182:185], v[26:29]
	v_mfma_f32_16x16x32_bf16 v[54:57], v[146:149], v[162:165], v[54:57]
	v_mfma_f32_16x16x32_bf16 v[34:37], v[154:157], v[170:173], v[34:37]
	v_mfma_f32_16x16x32_bf16 v[22:25], v[146:149], v[178:181], v[22:25]
	v_mfma_f32_16x16x32_bf16 v[2:5], v[154:157], v[216:219], v[2:5]
	v_mfma_f32_16x16x32_bf16 v[38:41], v[146:149], v[170:173], v[38:41]
	v_mfma_f32_16x16x32_bf16 v[50:53], v[154:157], v[162:165], v[50:53]
	v_mfma_f32_16x16x32_bf16 v[6:9], v[146:149], v[216:219], v[6:9]
	v_mfma_f32_16x16x32_bf16 v[18:21], v[154:157], v[178:181], v[18:21]
	v_mfma_f32_16x16x32_bf16 v[54:57], v[150:153], v[166:169], v[54:57]
	v_mfma_f32_16x16x32_bf16 v[34:37], v[158:161], v[174:177], v[34:37]
	v_mfma_f32_16x16x32_bf16 v[22:25], v[150:153], v[182:185], v[22:25]
	v_mfma_f32_16x16x32_bf16 v[2:5], v[158:161], v[220:223], v[2:5]
	v_mfma_f32_16x16x32_bf16 v[38:41], v[150:153], v[174:177], v[38:41]
	v_mfma_f32_16x16x32_bf16 v[50:53], v[158:161], v[166:169], v[50:53]
	v_mfma_f32_16x16x32_bf16 v[6:9], v[150:153], v[220:223], v[6:9]
	v_mfma_f32_16x16x32_bf16 v[18:21], v[158:161], v[182:185], v[18:21]
	s_barrier
	s_add_i32 s8, s8, 2
	s_add_u32 s38, s38, 0x100
	s_addc_u32 s39, s39, 0
	s_add_u32 s6, s6, 0x100
	s_addc_u32 s7, s7, 0
	s_cmp_gt_u32 s8, 29
.LBB0_927:
	s_add_u32 s9, s38, 0xfff80080
	s_addc_u32 s10, s39, -1
	s_add_i32 s11, 0, 0x10000
	s_cmp_eq_u32 s8, 28
	s_cselect_b32 s95, s36, s10
	s_cselect_b32 s94, s37, s9
	s_cselect_b32 s47, s4, s7
	s_cselect_b32 s46, s5, s6
	s_add_i32 s9, 0, 0x14000
	ds_read_b128 v[66:69], v186
	ds_read_b128 v[70:73], v186 offset:1024
	ds_read_b128 v[78:81], v186 offset:2048
	ds_read_b128 v[86:89], v186 offset:3072
	ds_read_b128 v[146:149], v187
	ds_read_b128 v[150:153], v187 offset:1024
	ds_read_b128 v[154:157], v187 offset:2048
	ds_read_b128 v[158:161], v187 offset:3072
	s_add_i32 m0, s66, 0xc000
	ds_read_b128 v[162:165], v236
	ds_read_b128 v[166:169], v236 offset:1024
	ds_read_b128 v[170:173], v236 offset:2048
	ds_read_b128 v[174:177], v236 offset:3072
	ds_read_b128 v[178:181], v236 offset:4096
	ds_read_b128 v[182:185], v236 offset:5120
	ds_read_b128 v[216:219], v236 offset:6144
	ds_read_b128 v[220:223], v236 offset:7168
	global_load_lds_dwordx4 v212, s[38:39]
	s_add_i32 m0, s66, 0xe000
	s_nop 0
	global_load_lds_dwordx4 v214, s[38:39]
	s_waitcnt vmcnt(8)
	s_waitcnt lgkmcnt(0)
	s_barrier
	v_mfma_f32_16x16x32_bf16 v[142:145], v[66:69], v[162:165], v[142:145]
	v_mfma_f32_16x16x32_bf16 v[122:125], v[78:81], v[170:173], v[122:125]
	v_mfma_f32_16x16x32_bf16 v[110:113], v[66:69], v[178:181], v[110:113]
	v_mfma_f32_16x16x32_bf16 v[90:93], v[78:81], v[216:219], v[90:93]
	v_mfma_f32_16x16x32_bf16 v[126:129], v[66:69], v[170:173], v[126:129]
	v_mfma_f32_16x16x32_bf16 v[138:141], v[78:81], v[162:165], v[138:141]
	v_mfma_f32_16x16x32_bf16 v[94:97], v[66:69], v[216:219], v[94:97]
	v_mfma_f32_16x16x32_bf16 v[106:109], v[78:81], v[178:181], v[106:109]
	v_mfma_f32_16x16x32_bf16 v[142:145], v[70:73], v[166:169], v[142:145]
	v_mfma_f32_16x16x32_bf16 v[122:125], v[86:89], v[174:177], v[122:125]
	v_mfma_f32_16x16x32_bf16 v[110:113], v[70:73], v[182:185], v[110:113]
	v_mfma_f32_16x16x32_bf16 v[90:93], v[86:89], v[220:223], v[90:93]
	v_mfma_f32_16x16x32_bf16 v[126:129], v[70:73], v[174:177], v[126:129]
	v_mfma_f32_16x16x32_bf16 v[138:141], v[86:89], v[166:169], v[138:141]
	v_mfma_f32_16x16x32_bf16 v[94:97], v[70:73], v[220:223], v[94:97]
	v_mfma_f32_16x16x32_bf16 v[106:109], v[86:89], v[182:185], v[106:109]
	v_mfma_f32_16x16x32_bf16 v[134:137], v[146:149], v[162:165], v[134:137]
	v_mfma_f32_16x16x32_bf16 v[114:117], v[154:157], v[170:173], v[114:117]
	v_mfma_f32_16x16x32_bf16 v[102:105], v[146:149], v[178:181], v[102:105]
	v_mfma_f32_16x16x32_bf16 v[74:77], v[154:157], v[216:219], v[74:77]
	v_mfma_f32_16x16x32_bf16 v[118:121], v[146:149], v[170:173], v[118:121]
	v_mfma_f32_16x16x32_bf16 v[130:133], v[154:157], v[162:165], v[130:133]
	v_mfma_f32_16x16x32_bf16 v[82:85], v[146:149], v[216:219], v[82:85]
	v_mfma_f32_16x16x32_bf16 v[98:101], v[154:157], v[178:181], v[98:101]
	v_mfma_f32_16x16x32_bf16 v[134:137], v[150:153], v[166:169], v[134:137]
	v_mfma_f32_16x16x32_bf16 v[114:117], v[158:161], v[174:177], v[114:117]
	v_mfma_f32_16x16x32_bf16 v[102:105], v[150:153], v[182:185], v[102:105]
	v_mfma_f32_16x16x32_bf16 v[74:77], v[158:161], v[220:223], v[74:77]
	v_mfma_f32_16x16x32_bf16 v[118:121], v[150:153], v[174:177], v[118:121]
	v_mfma_f32_16x16x32_bf16 v[130:133], v[158:161], v[166:169], v[130:133]
	v_mfma_f32_16x16x32_bf16 v[82:85], v[150:153], v[220:223], v[82:85]
	v_mfma_f32_16x16x32_bf16 v[98:101], v[158:161], v[182:185], v[98:101]
	s_barrier
; #define PG8_STAGE(bufoff, gbase, voff) do { _Pragma("unroll") for (int _i = 0; _i < 2; ++_i) \
;         __builtin_amdgcn_global_load_lds((const unsigned*)((const char*)(gbase) + (voff)[_i]), (PG8_LAS unsigned*)(lds + (bufoff) + ldsw + _i * 8192), 16, 0, 0); } while (0)
; #define PG8_LDA(dst, b, h) do { _Pragma("unroll") for (int m = 0; m < 4; ++m) _Pragma("unroll") for (int k = 0; k < 2; ++k) dst[m][k] = *(const PG8_LAS bf16x8*)(lds + PG8_SA(b, h) + aoff + m * 2048 + k * 1024); } while (0)
; #define PG8_LDB(dst, b, h) do { _Pragma("unroll") for (int n = 0; n < 2; ++n) _Pragma("unroll") for (int k = 0; k < 2; ++k) dst[n][k] = *(const PG8_LAS bf16x8*)(lds + PG8_SB(b, h) + boff + n * 2048 + k * 1024); } while (0)
; #define PG8_MMA(ai, bj, At, Bt) do { __builtin_amdgcn_s_setprio(1); _Pragma("unroll") for (int m = 0; m < 4; ++m) _Pragma("unroll") for (int n = 0; n < 2; ++n) _Pragma("unroll") for (int k = 0; k < 2; ++k) \
;         acc[ai][bj][m][n] = __builtin_amdgcn_mfma_f32_16x16x32_bf16(Bt[n][k], At[m][k], acc[ai][bj][m][n], 0, 0, 0); __builtin_amdgcn_s_setprio(0); } while (0)
; #define PG8_WAIT_V(n) asm volatile("s_waitcnt vmcnt(" #n ")" ::: "memory")
; #define PG8_WAIT_L(n) asm volatile("s_waitcnt lgkmcnt(" #n ")" ::: "memory")
; #define PG8_BAR __builtin_amdgcn_s_barrier()
; #define PG8_SCHED __builtin_amdgcn_sched_barrier(0)
; template <class Epi, class Sched, bool ALIGN_EPI = false, bool SP2 = false>
; __device__ __forceinline__ void gemm_phase(PG8_LAS unsigned char* lds, const Gemm g, const Sched& S, const Epi& E) {
;     ...
;             PG8_LDA(At, 0, 1); PG8_STAGE(PG8_SB(0, 0), b2, voffB); PG8_STAGE(PG8_SB(0, 1), b2 + hstepB, voffB); PG8_STAGE(PG8_SA(0, 0), a2, voffA);
;             PG8_WAIT_V(8); PG8_WAIT_L(0); PG8_BAR; PG8_MMA(1, 0, At, B0); PG8_MMA(1, 1, At, B1); PG8_BAR; PG8_SCHED;
;             PG8_LDB(B0, 1, 0); PG8_LDB(B1, 1, 1); PG8_SCHED; PG8_LDA(At, 1, 0); PG8_STAGE(PG8_SA(0, 1), a2 + hstep, voffA);
	s_add_i32 s10, s11, s25
	s_mov_b32 m0, s10
	ds_read_b128 v[162:165], v236 offset:16384
	ds_read_b128 v[166:169], v236 offset:17408
	ds_read_b128 v[170:173], v236 offset:18432
	ds_read_b128 v[174:177], v236 offset:19456
	ds_read_b128 v[178:181], v236 offset:20480
	ds_read_b128 v[182:185], v236 offset:21504
	ds_read_b128 v[216:219], v236 offset:22528
	ds_read_b128 v[220:223], v236 offset:23552
	global_load_lds_dwordx4 v190, s[46:47]
	s_add_i32 m0, s10, 0x2000
	s_add_u32 s10, s46, 0x20000
	s_addc_u32 s11, s47, 0
	s_add_i32 s9, s9, s25
	global_load_lds_dwordx4 v206, s[46:47]
	s_mov_b32 m0, s9
	s_nop 0
	global_load_lds_dwordx4 v190, s[10:11]
	s_add_i32 m0, s9, 0x2000
	s_nop 0
	global_load_lds_dwordx4 v206, s[10:11]
	s_mov_b32 m0, s66
	s_nop 0
	global_load_lds_dwordx4 v210, s[94:95]
	s_mov_b32 m0, s67
	s_nop 0
	global_load_lds_dwordx4 v208, s[94:95]
	s_waitcnt vmcnt(8)
	s_waitcnt lgkmcnt(0)
	s_barrier
	v_mfma_f32_16x16x32_bf16 v[62:65], v[66:69], v[162:165], v[62:65]
	v_mfma_f32_16x16x32_bf16 v[42:45], v[78:81], v[170:173], v[42:45]
	v_mfma_f32_16x16x32_bf16 v[30:33], v[66:69], v[178:181], v[30:33]
	v_mfma_f32_16x16x32_bf16 v[10:13], v[78:81], v[216:219], v[10:13]
	v_mfma_f32_16x16x32_bf16 v[46:49], v[66:69], v[170:173], v[46:49]
	v_mfma_f32_16x16x32_bf16 v[58:61], v[78:81], v[162:165], v[58:61]
	v_mfma_f32_16x16x32_bf16 v[14:17], v[66:69], v[216:219], v[14:17]
	v_mfma_f32_16x16x32_bf16 v[26:29], v[78:81], v[178:181], v[26:29]
	v_mfma_f32_16x16x32_bf16 v[62:65], v[70:73], v[166:169], v[62:65]
	v_mfma_f32_16x16x32_bf16 v[42:45], v[86:89], v[174:177], v[42:45]
	v_mfma_f32_16x16x32_bf16 v[30:33], v[70:73], v[182:185], v[30:33]
	v_mfma_f32_16x16x32_bf16 v[10:13], v[86:89], v[220:223], v[10:13]
	v_mfma_f32_16x16x32_bf16 v[46:49], v[70:73], v[174:177], v[46:49]
	v_mfma_f32_16x16x32_bf16 v[58:61], v[86:89], v[166:169], v[58:61]
	v_mfma_f32_16x16x32_bf16 v[14:17], v[70:73], v[220:223], v[14:17]
	v_mfma_f32_16x16x32_bf16 v[26:29], v[86:89], v[182:185], v[26:29]
	v_mfma_f32_16x16x32_bf16 v[54:57], v[146:149], v[162:165], v[54:57]
	v_mfma_f32_16x16x32_bf16 v[34:37], v[154:157], v[170:173], v[34:37]
	v_mfma_f32_16x16x32_bf16 v[22:25], v[146:149], v[178:181], v[22:25]
	v_mfma_f32_16x16x32_bf16 v[2:5], v[154:157], v[216:219], v[2:5]
	v_mfma_f32_16x16x32_bf16 v[38:41], v[146:149], v[170:173], v[38:41]
	v_mfma_f32_16x16x32_bf16 v[50:53], v[154:157], v[162:165], v[50:53]
	v_mfma_f32_16x16x32_bf16 v[6:9], v[146:149], v[216:219], v[6:9]
	v_mfma_f32_16x16x32_bf16 v[18:21], v[154:157], v[178:181], v[18:21]
	v_mfma_f32_16x16x32_bf16 v[54:57], v[150:153], v[166:169], v[54:57]
	v_mfma_f32_16x16x32_bf16 v[34:37], v[158:161], v[174:177], v[34:37]
	v_mfma_f32_16x16x32_bf16 v[22:25], v[150:153], v[182:185], v[22:25]
	v_mfma_f32_16x16x32_bf16 v[2:5], v[158:161], v[220:223], v[2:5]
	v_mfma_f32_16x16x32_bf16 v[38:41], v[150:153], v[174:177], v[38:41]
	v_mfma_f32_16x16x32_bf16 v[50:53], v[158:161], v[166:169], v[50:53]
	v_mfma_f32_16x16x32_bf16 v[6:9], v[150:153], v[220:223], v[6:9]
	v_mfma_f32_16x16x32_bf16 v[18:21], v[158:161], v[182:185], v[18:21]
	s_barrier
	s_add_i32 s9, 0, 0x18000
	s_add_i32 s12, 0, 0x1c000
	ds_read_b128 v[66:69], v198
	ds_read_b128 v[70:73], v198 offset:1024
	ds_read_b128 v[78:81], v198 offset:2048
	ds_read_b128 v[86:89], v198 offset:3072
	ds_read_b128 v[146:149], v199
	ds_read_b128 v[150:153], v199 offset:1024
	ds_read_b128 v[154:157], v199 offset:2048
	ds_read_b128 v[158:161], v199 offset:3072
	s_add_u32 s10, s94, 0x80000
	s_addc_u32 s11, s95, 0
	s_mov_b32 m0, s59
	ds_read_b128 v[162:165], v236 offset:32768
	ds_read_b128 v[166:169], v236 offset:33792
	ds_read_b128 v[170:173], v236 offset:34816
	ds_read_b128 v[174:177], v236 offset:35840
	ds_read_b128 v[178:181], v236 offset:36864
	ds_read_b128 v[182:185], v236 offset:37888
	ds_read_b128 v[216:219], v236 offset:38912
	ds_read_b128 v[220:223], v236 offset:39936
	global_load_lds_dwordx4 v210, s[10:11]
	s_mov_b32 m0, s74
	s_nop 0
	global_load_lds_dwordx4 v208, s[10:11]
	s_waitcnt vmcnt(8)
	s_waitcnt lgkmcnt(0)
	s_barrier
; #define PG8_STAGE(bufoff, gbase, voff) do { _Pragma("unroll") for (int _i = 0; _i < 2; ++_i) \
;         __builtin_amdgcn_global_load_lds((const unsigned*)((const char*)(gbase) + (voff)[_i]), (PG8_LAS unsigned*)(lds + (bufoff) + ldsw + _i * 8192), 16, 0, 0); } while (0)
; #define PG8_LDA(dst, b, h) do { _Pragma("unroll") for (int m = 0; m < 4; ++m) _Pragma("unroll") for (int k = 0; k < 2; ++k) dst[m][k] = *(const PG8_LAS bf16x8*)(lds + PG8_SA(b, h) + aoff + m * 2048 + k * 1024); } while (0)
; #define PG8_MMA(ai, bj, At, Bt) do { __builtin_amdgcn_s_setprio(1); _Pragma("unroll") for (int m = 0; m < 4; ++m) _Pragma("unroll") for (int n = 0; n < 2; ++n) _Pragma("unroll") for (int k = 0; k < 2; ++k) \
;         acc[ai][bj][m][n] = __builtin_amdgcn_mfma_f32_16x16x32_bf16(Bt[n][k], At[m][k], acc[ai][bj][m][n], 0, 0, 0); __builtin_amdgcn_s_setprio(0); } while (0)
; #define PG8_WAIT_V(n) asm volatile("s_waitcnt vmcnt(" #n ")" ::: "memory")
; #define PG8_WAIT_L(n) asm volatile("s_waitcnt lgkmcnt(" #n ")" ::: "memory")
; #define PG8_BAR __builtin_amdgcn_s_barrier()
; #define PG8_SCHED __builtin_amdgcn_sched_barrier(0)
; template <class Epi, class Sched, bool ALIGN_EPI = false, bool SP2 = false>
; __device__ __forceinline__ void gemm_phase(PG8_LAS unsigned char* lds, const Gemm g, const Sched& S, const Epi& E) {
;     ...
;             PG8_WAIT_V(8); PG8_WAIT_L(0); PG8_BAR; PG8_MMA(0, 0, At, B0); PG8_MMA(0, 1, At, B1); PG8_BAR; PG8_SCHED;
;             PG8_LDA(At, 1, 1); PG8_STAGE(PG8_SB(1, 0), b3, voffB); PG8_STAGE(PG8_SB(1, 1), b3 + hstepB, voffB); PG8_STAGE(PG8_SA(1, 0), a3, voffA);
;             PG8_WAIT_V(8); PG8_WAIT_L(0); PG8_BAR; PG8_MMA(1, 0, At, B0); PG8_MMA(1, 1, At, B1); PG8_BAR; PG8_SCHED;
;     ...
;         if constexpr (ALIGN_EPI) { if (wr == 0) PG8_BAR; }
	v_mfma_f32_16x16x32_bf16 v[142:145], v[66:69], v[162:165], v[142:145]
	v_mfma_f32_16x16x32_bf16 v[122:125], v[78:81], v[170:173], v[122:125]
	v_mfma_f32_16x16x32_bf16 v[110:113], v[66:69], v[178:181], v[110:113]
	v_mfma_f32_16x16x32_bf16 v[90:93], v[78:81], v[216:219], v[90:93]
	v_mfma_f32_16x16x32_bf16 v[126:129], v[66:69], v[170:173], v[126:129]
	v_mfma_f32_16x16x32_bf16 v[138:141], v[78:81], v[162:165], v[138:141]
	v_mfma_f32_16x16x32_bf16 v[94:97], v[66:69], v[216:219], v[94:97]
	v_mfma_f32_16x16x32_bf16 v[106:109], v[78:81], v[178:181], v[106:109]
	v_mfma_f32_16x16x32_bf16 v[142:145], v[70:73], v[166:169], v[142:145]
	v_mfma_f32_16x16x32_bf16 v[122:125], v[86:89], v[174:177], v[122:125]
	v_mfma_f32_16x16x32_bf16 v[110:113], v[70:73], v[182:185], v[110:113]
	v_mfma_f32_16x16x32_bf16 v[90:93], v[86:89], v[220:223], v[90:93]
	v_mfma_f32_16x16x32_bf16 v[126:129], v[70:73], v[174:177], v[126:129]
	v_mfma_f32_16x16x32_bf16 v[138:141], v[86:89], v[166:169], v[138:141]
	v_mfma_f32_16x16x32_bf16 v[94:97], v[70:73], v[220:223], v[94:97]
	v_mfma_f32_16x16x32_bf16 v[106:109], v[86:89], v[182:185], v[106:109]
	v_mfma_f32_16x16x32_bf16 v[134:137], v[146:149], v[162:165], v[134:137]
	v_mfma_f32_16x16x32_bf16 v[114:117], v[154:157], v[170:173], v[114:117]
	v_mfma_f32_16x16x32_bf16 v[102:105], v[146:149], v[178:181], v[102:105]
	v_mfma_f32_16x16x32_bf16 v[74:77], v[154:157], v[216:219], v[74:77]
	v_mfma_f32_16x16x32_bf16 v[118:121], v[146:149], v[170:173], v[118:121]
	v_mfma_f32_16x16x32_bf16 v[130:133], v[154:157], v[162:165], v[130:133]
	v_mfma_f32_16x16x32_bf16 v[82:85], v[146:149], v[216:219], v[82:85]
	v_mfma_f32_16x16x32_bf16 v[98:101], v[154:157], v[178:181], v[98:101]
	v_mfma_f32_16x16x32_bf16 v[134:137], v[150:153], v[166:169], v[134:137]
	v_mfma_f32_16x16x32_bf16 v[114:117], v[158:161], v[174:177], v[114:117]
	v_mfma_f32_16x16x32_bf16 v[102:105], v[150:153], v[182:185], v[102:105]
	v_mfma_f32_16x16x32_bf16 v[74:77], v[158:161], v[220:223], v[74:77]
	v_mfma_f32_16x16x32_bf16 v[118:121], v[150:153], v[174:177], v[118:121]
	v_mfma_f32_16x16x32_bf16 v[130:133], v[158:161], v[166:169], v[130:133]
	v_mfma_f32_16x16x32_bf16 v[82:85], v[150:153], v[220:223], v[82:85]
	v_mfma_f32_16x16x32_bf16 v[98:101], v[158:161], v[182:185], v[98:101]
	s_barrier
	s_add_i32 s9, s9, s25
	s_mov_b32 m0, s9
	ds_read_b128 v[162:165], v236 offset:49152
	ds_read_b128 v[166:169], v236 offset:50176
	ds_read_b128 v[170:173], v236 offset:51200
	ds_read_b128 v[174:177], v236 offset:52224
	ds_read_b128 v[178:181], v236 offset:53248
	ds_read_b128 v[182:185], v236 offset:54272
	ds_read_b128 v[216:219], v236 offset:55296
	ds_read_b128 v[220:223], v236 offset:56320
	s_add_u32 s100, s46, s60
	s_addc_u32 s101, s47, s61
	global_load_lds_dwordx4 v190, s[100:101]
	s_add_i32 m0, s9, 0x2000
	s_add_u32 s10, s46, 0x20080
	s_addc_u32 s11, s47, 0
	s_add_i32 s9, s12, s25
	global_load_lds_dwordx4 v206, s[100:101]
	s_mov_b32 m0, s9
	s_nop 0
	global_load_lds_dwordx4 v190, s[10:11]
	s_add_i32 m0, s9, 0x2000
	s_nop 0
	global_load_lds_dwordx4 v206, s[10:11]
	s_mov_b32 m0, s75
	s_add_u32 s100, s94, s60
	s_addc_u32 s101, s95, s61
	global_load_lds_dwordx4 v210, s[100:101]
	s_mov_b32 m0, s0
	s_nop 0
	global_load_lds_dwordx4 v208, s[100:101]
	s_waitcnt vmcnt(8)
	s_waitcnt lgkmcnt(0)
	s_barrier
	v_mfma_f32_16x16x32_bf16 v[62:65], v[66:69], v[162:165], v[62:65]
	v_mfma_f32_16x16x32_bf16 v[42:45], v[78:81], v[170:173], v[42:45]
	v_mfma_f32_16x16x32_bf16 v[30:33], v[66:69], v[178:181], v[30:33]
	v_mfma_f32_16x16x32_bf16 v[10:13], v[78:81], v[216:219], v[10:13]
	v_mfma_f32_16x16x32_bf16 v[46:49], v[66:69], v[170:173], v[46:49]
	v_mfma_f32_16x16x32_bf16 v[58:61], v[78:81], v[162:165], v[58:61]
	v_mfma_f32_16x16x32_bf16 v[14:17], v[66:69], v[216:219], v[14:17]
	v_mfma_f32_16x16x32_bf16 v[26:29], v[78:81], v[178:181], v[26:29]
	v_mfma_f32_16x16x32_bf16 v[62:65], v[70:73], v[166:169], v[62:65]
	v_mfma_f32_16x16x32_bf16 v[42:45], v[86:89], v[174:177], v[42:45]
	v_mfma_f32_16x16x32_bf16 v[30:33], v[70:73], v[182:185], v[30:33]
	v_mfma_f32_16x16x32_bf16 v[10:13], v[86:89], v[220:223], v[10:13]
	v_mfma_f32_16x16x32_bf16 v[46:49], v[70:73], v[174:177], v[46:49]
	v_mfma_f32_16x16x32_bf16 v[58:61], v[86:89], v[166:169], v[58:61]
	v_mfma_f32_16x16x32_bf16 v[14:17], v[70:73], v[220:223], v[14:17]
	v_mfma_f32_16x16x32_bf16 v[26:29], v[86:89], v[182:185], v[26:29]
	v_mfma_f32_16x16x32_bf16 v[54:57], v[146:149], v[162:165], v[54:57]
	v_mfma_f32_16x16x32_bf16 v[34:37], v[154:157], v[170:173], v[34:37]
	v_mfma_f32_16x16x32_bf16 v[22:25], v[146:149], v[178:181], v[22:25]
	v_mfma_f32_16x16x32_bf16 v[2:5], v[154:157], v[216:219], v[2:5]
	v_mfma_f32_16x16x32_bf16 v[38:41], v[146:149], v[170:173], v[38:41]
	v_mfma_f32_16x16x32_bf16 v[50:53], v[154:157], v[162:165], v[50:53]
	v_mfma_f32_16x16x32_bf16 v[6:9], v[146:149], v[216:219], v[6:9]
	v_mfma_f32_16x16x32_bf16 v[18:21], v[154:157], v[178:181], v[18:21]
	v_mfma_f32_16x16x32_bf16 v[54:57], v[150:153], v[166:169], v[54:57]
	v_mfma_f32_16x16x32_bf16 v[34:37], v[158:161], v[174:177], v[34:37]
	v_mfma_f32_16x16x32_bf16 v[22:25], v[150:153], v[182:185], v[22:25]
	v_mfma_f32_16x16x32_bf16 v[2:5], v[158:161], v[220:223], v[2:5]
	v_mfma_f32_16x16x32_bf16 v[38:41], v[150:153], v[174:177], v[38:41]
	v_mfma_f32_16x16x32_bf16 v[50:53], v[158:161], v[166:169], v[50:53]
	v_mfma_f32_16x16x32_bf16 v[6:9], v[150:153], v[220:223], v[6:9]
	v_mfma_f32_16x16x32_bf16 v[18:21], v[158:161], v[182:185], v[18:21]
	s_barrier
	s_add_i32 s8, s8, 2
	s_add_u32 s38, s38, 0x100
	s_addc_u32 s39, s39, 0
	s_add_u32 s6, s6, 0x100
	s_addc_u32 s7, s7, 0
	s_cmp_gt_u32 s8, 29
	s_cbranch_scc0 .LBB0_927
	s_and_b64 vcc, exec, s[70:71]
	s_cbranch_vccz .LBB0_930
	s_barrier

; #define PG8_STAGE(bufoff, gbase, voff) do { _Pragma("unroll") for (int _i = 0; _i < 2; ++_i) \
;         __builtin_amdgcn_global_load_lds((const unsigned*)((const char*)(gbase) + (voff)[_i]), (PG8_LAS unsigned*)(lds + (bufoff) + ldsw + _i * 8192), 16, 0, 0); } while (0)
; #define PG8_LDA(dst, b, h) do { _Pragma("unroll") for (int m = 0; m < 4; ++m) _Pragma("unroll") for (int k = 0; k < 2; ++k) dst[m][k] = *(const PG8_LAS bf16x8*)(lds + PG8_SA(b, h) + aoff + m * 2048 + k * 1024); } while (0)
; #define PG8_LDB(dst, b, h) do { _Pragma("unroll") for (int n = 0; n < 2; ++n) _Pragma("unroll") for (int k = 0; k < 2; ++k) dst[n][k] = *(const PG8_LAS bf16x8*)(lds + PG8_SB(b, h) + boff + n * 2048 + k * 1024); } while (0)
; #define PG8_MMA(ai, bj, At, Bt) do { __builtin_amdgcn_s_setprio(1); _Pragma("unroll") for (int m = 0; m < 4; ++m) _Pragma("unroll") for (int n = 0; n < 2; ++n) _Pragma("unroll") for (int k = 0; k < 2; ++k) \
;         acc[ai][bj][m][n] = __builtin_amdgcn_mfma_f32_16x16x32_bf16(Bt[n][k], At[m][k], acc[ai][bj][m][n], 0, 0, 0); __builtin_amdgcn_s_setprio(0); } while (0)
; #define PG8_BAR __builtin_amdgcn_s_barrier()
; template <class Epi, class Sched, bool ALIGN_EPI = false, bool SP2 = false>
; __device__ __forceinline__ void gemm_phase(PG8_LAS unsigned char* lds, const Gemm g, const Sched& S, const Epi& E) {
;     ...
;         const bool has_next = S.next(ui + 1, nxt);
;         const char* nA = has_next ? (const char*)g.A + (size_t)nxt.pm * tstep : cA; const char* nB = has_next ? (const char*)g.Bt + (size_t)nxt.pn * tstep : cB;
;         for (int t = 0; t < nt; t += 2) {
;             const bool last = (t == nt - 2);
;             const char* a1 = cA + (size_t)(t + 1) * kstep;
;             const char* a2 = last ? nA : cA + (size_t)(t + 2) * kstep; const char* b2 = last ? nB : cB + (size_t)(t + 2) * kstep;
;             const char* a3 = a2 + kstep; const char* b3 = b2 + kstep;
;             if (last && has_next) S.a_ready(nxt);
;             if constexpr (SP2) {
;             PG8_LDB(B0, 0, 0); PG8_LDB(B1, 0, 1); PG8_SCHED; PG8_LDA(At, 0, 0); PG8_STAGE(PG8_SA(1, 1), a1 + hstep, voffA);
;             PG8_WAIT_V(8); PG8_WAIT_L(0); PG8_BAR; PG8_MMA(0, 0, At, B0); PG8_MMA(0, 1, At, B1); PG8_BAR; PG8_SCHED;
;             PG8_LDA(At, 0, 1); PG8_STAGE(PG8_SB(0, 0), b2, voffB); PG8_STAGE(PG8_SB(0, 1), b2 + hstepB, voffB); PG8_STAGE(PG8_SA(0, 0), a2, voffA);
.LBB0_1070:
	s_ashr_i32 s97, s96, 31
	s_lshl_b64 s[4:5], s[96:97], 22
	s_add_u32 s26, s0, s4
	s_addc_u32 s27, s1, s5
	s_and_b64 s[4:5], s[92:93], exec
	s_cselect_b32 s97, s27, s39
	s_cselect_b32 s4, s26, s38
	s_ashr_i32 s85, s84, 31
	s_lshl_b64 s[6:7], s[84:85], 22
	s_add_u32 s94, s56, s6
	s_addc_u32 s95, s57, s7
	s_and_b64 s[6:7], s[92:93], exec
	s_cselect_b32 s5, s95, s47
	s_cselect_b32 s6, s94, s46
	s_add_u32 s38, s38, 0x200080
	s_addc_u32 s39, s39, 0
	s_add_u32 s7, s46, 0x100
	s_addc_u32 s8, s47, 0
	s_mov_b32 s9, -2
	s_waitcnt lgkmcnt(0)
	v_add_u32_e32 v186, 0x10000, v164
	v_add_u32_e32 v187, 0x14000, v164
	v_add_u32_e32 v198, 0x18000, v164
	v_add_u32_e32 v199, 0x1c000, v164
	s_add_u32 s10, s38, 0xffe00080
	s_addc_u32 s11, s39, -1
	s_add_i32 s12, 0, 0x10000
	s_cmpk_eq_i32 s9, 0x7c
	s_cselect_b32 vcc_hi, s97, s11
	s_cselect_b32 vcc_lo, s4, s10
	s_cselect_b32 s47, s5, s8
	s_cselect_b32 s46, s6, s7
	s_add_i32 s13, 0, 0x14000
	ds_read_b128 v[130:133], v186
	ds_read_b128 v[134:137], v186 offset:1024
	ds_read_b128 v[138:141], v186 offset:2048
	ds_read_b128 v[152:155], v186 offset:3072
	ds_read_b128 v[156:159], v187
	ds_read_b128 v[160:163], v187 offset:1024
	ds_read_b128 v[168:171], v187 offset:2048
	ds_read_b128 v[172:175], v187 offset:3072
	s_add_i32 m0, s74, 0xc000
	ds_read_b128 v[176:179], v166
	ds_read_b128 v[180:183], v166 offset:1024
	ds_read_b128 v[206:209], v166 offset:2048
	ds_read_b128 v[210:213], v166 offset:3072
	ds_read_b128 v[214:217], v166 offset:4096
	ds_read_b128 v[218:221], v166 offset:5120
	ds_read_b128 v[236:239], v166 offset:6144
	ds_read_b128 v[240:243], v166 offset:7168
	global_load_lds_dwordx4 v148, s[38:39]
	s_add_i32 m0, s74, 0xe000
	s_nop 0
	global_load_lds_dwordx4 v150, s[38:39]
	s_waitcnt vmcnt(8)
	s_waitcnt lgkmcnt(0)
	s_barrier
	v_mfma_f32_16x16x32_bf16 v[126:129], v[130:133], v[176:179], 0
	v_mfma_f32_16x16x32_bf16 v[106:109], v[138:141], v[206:209], 0
	v_mfma_f32_16x16x32_bf16 v[94:97], v[130:133], v[214:217], 0
	v_mfma_f32_16x16x32_bf16 v[74:77], v[138:141], v[236:239], 0
	v_mfma_f32_16x16x32_bf16 v[110:113], v[130:133], v[206:209], 0
	v_mfma_f32_16x16x32_bf16 v[122:125], v[138:141], v[176:179], 0
	v_mfma_f32_16x16x32_bf16 v[78:81], v[130:133], v[236:239], 0
	v_mfma_f32_16x16x32_bf16 v[90:93], v[138:141], v[214:217], 0
	v_mfma_f32_16x16x32_bf16 v[126:129], v[134:137], v[180:183], v[126:129]
	v_mfma_f32_16x16x32_bf16 v[106:109], v[152:155], v[210:213], v[106:109]
	v_mfma_f32_16x16x32_bf16 v[94:97], v[134:137], v[218:221], v[94:97]
	v_mfma_f32_16x16x32_bf16 v[74:77], v[152:155], v[240:243], v[74:77]
	v_mfma_f32_16x16x32_bf16 v[110:113], v[134:137], v[210:213], v[110:113]
	v_mfma_f32_16x16x32_bf16 v[122:125], v[152:155], v[180:183], v[122:125]
	v_mfma_f32_16x16x32_bf16 v[78:81], v[134:137], v[240:243], v[78:81]
	v_mfma_f32_16x16x32_bf16 v[90:93], v[152:155], v[218:221], v[90:93]
	v_mfma_f32_16x16x32_bf16 v[118:121], v[156:159], v[176:179], 0
	v_mfma_f32_16x16x32_bf16 v[98:101], v[168:171], v[206:209], 0
	v_mfma_f32_16x16x32_bf16 v[86:89], v[156:159], v[214:217], 0
	v_mfma_f32_16x16x32_bf16 v[66:69], v[168:171], v[236:239], 0
	v_mfma_f32_16x16x32_bf16 v[102:105], v[156:159], v[206:209], 0
	v_mfma_f32_16x16x32_bf16 v[114:117], v[168:171], v[176:179], 0
	v_mfma_f32_16x16x32_bf16 v[70:73], v[156:159], v[236:239], 0
	v_mfma_f32_16x16x32_bf16 v[82:85], v[168:171], v[214:217], 0
	v_mfma_f32_16x16x32_bf16 v[118:121], v[160:163], v[180:183], v[118:121]
	v_mfma_f32_16x16x32_bf16 v[98:101], v[172:175], v[210:213], v[98:101]
	v_mfma_f32_16x16x32_bf16 v[86:89], v[160:163], v[218:221], v[86:89]
	v_mfma_f32_16x16x32_bf16 v[66:69], v[172:175], v[240:243], v[66:69]
	v_mfma_f32_16x16x32_bf16 v[102:105], v[160:163], v[210:213], v[102:105]
	v_mfma_f32_16x16x32_bf16 v[114:117], v[172:175], v[180:183], v[114:117]
	v_mfma_f32_16x16x32_bf16 v[70:73], v[160:163], v[240:243], v[70:73]
	v_mfma_f32_16x16x32_bf16 v[82:85], v[172:175], v[218:221], v[82:85]
	s_barrier
	s_add_i32 s10, s12, s67
	s_mov_b32 m0, s10
	ds_read_b128 v[176:179], v166 offset:16384
	ds_read_b128 v[180:183], v166 offset:17408
	ds_read_b128 v[206:209], v166 offset:18432
	ds_read_b128 v[210:213], v166 offset:19456
	ds_read_b128 v[214:217], v166 offset:20480
	ds_read_b128 v[218:221], v166 offset:21504
	ds_read_b128 v[236:239], v166 offset:22528
	ds_read_b128 v[240:243], v166 offset:23552
	global_load_lds_dwordx4 v146, s[46:47]
	s_add_i32 m0, s10, 0x2000
	s_add_u32 s10, s46, 0x80000
	s_addc_u32 s11, s47, 0
	s_add_i32 s12, s13, s67
	global_load_lds_dwordx4 v142, s[46:47]
	s_mov_b32 m0, s12
	s_nop 0
	global_load_lds_dwordx4 v146, s[10:11]
	s_add_i32 m0, s12, 0x2000
	s_nop 0
	global_load_lds_dwordx4 v142, s[10:11]
	s_mov_b32 m0, s74
	s_nop 0
	global_load_lds_dwordx4 v190, vcc
	s_mov_b32 m0, s75
	s_nop 0
	global_load_lds_dwordx4 v144, vcc
	s_waitcnt vmcnt(8)
	s_waitcnt lgkmcnt(0)
	s_barrier
; #define PG8_STAGE(bufoff, gbase, voff) do { _Pragma("unroll") for (int _i = 0; _i < 2; ++_i) \
;         __builtin_amdgcn_global_load_lds((const unsigned*)((const char*)(gbase) + (voff)[_i]), (PG8_LAS unsigned*)(lds + (bufoff) + ldsw + _i * 8192), 16, 0, 0); } while (0)
; #define PG8_LDA(dst, b, h) do { _Pragma("unroll") for (int m = 0; m < 4; ++m) _Pragma("unroll") for (int k = 0; k < 2; ++k) dst[m][k] = *(const PG8_LAS bf16x8*)(lds + PG8_SA(b, h) + aoff + m * 2048 + k * 1024); } while (0)
; #define PG8_LDB(dst, b, h) do { _Pragma("unroll") for (int n = 0; n < 2; ++n) _Pragma("unroll") for (int k = 0; k < 2; ++k) dst[n][k] = *(const PG8_LAS bf16x8*)(lds + PG8_SB(b, h) + boff + n * 2048 + k * 1024); } while (0)
; #define PG8_MMA(ai, bj, At, Bt) do { __builtin_amdgcn_s_setprio(1); _Pragma("unroll") for (int m = 0; m < 4; ++m) _Pragma("unroll") for (int n = 0; n < 2; ++n) _Pragma("unroll") for (int k = 0; k < 2; ++k) \
;         acc[ai][bj][m][n] = __builtin_amdgcn_mfma_f32_16x16x32_bf16(Bt[n][k], At[m][k], acc[ai][bj][m][n], 0, 0, 0); __builtin_amdgcn_s_setprio(0); } while (0)
; #define PG8_WAIT_V(n) asm volatile("s_waitcnt vmcnt(" #n ")" ::: "memory")
; #define PG8_WAIT_L(n) asm volatile("s_waitcnt lgkmcnt(" #n ")" ::: "memory")
; #define PG8_BAR __builtin_amdgcn_s_barrier()
; #define PG8_SCHED __builtin_amdgcn_sched_barrier(0)
; template <class Epi, class Sched, bool ALIGN_EPI = false, bool SP2 = false>
; __device__ __forceinline__ void gemm_phase(PG8_LAS unsigned char* lds, const Gemm g, const Sched& S, const Epi& E) {
;     ...
;             PG8_WAIT_V(8); PG8_WAIT_L(0); PG8_BAR; PG8_MMA(1, 0, At, B0); PG8_MMA(1, 1, At, B1); PG8_BAR; PG8_SCHED;
;             PG8_LDB(B0, 1, 0); PG8_LDB(B1, 1, 1); PG8_SCHED; PG8_LDA(At, 1, 0); PG8_STAGE(PG8_SA(0, 1), a2 + hstep, voffA);
;             PG8_WAIT_V(8); PG8_WAIT_L(0); PG8_BAR; PG8_MMA(0, 0, At, B0); PG8_MMA(0, 1, At, B1); PG8_BAR; PG8_SCHED;
	v_mfma_f32_16x16x32_bf16 v[62:65], v[130:133], v[176:179], 0
	v_mfma_f32_16x16x32_bf16 v[42:45], v[138:141], v[206:209], 0
	v_mfma_f32_16x16x32_bf16 v[30:33], v[130:133], v[214:217], 0
	v_mfma_f32_16x16x32_bf16 v[10:13], v[138:141], v[236:239], 0
	v_mfma_f32_16x16x32_bf16 v[46:49], v[130:133], v[206:209], 0
	v_mfma_f32_16x16x32_bf16 v[58:61], v[138:141], v[176:179], 0
	v_mfma_f32_16x16x32_bf16 v[14:17], v[130:133], v[236:239], 0
	v_mfma_f32_16x16x32_bf16 v[26:29], v[138:141], v[214:217], 0
	v_mfma_f32_16x16x32_bf16 v[62:65], v[134:137], v[180:183], v[62:65]
	v_mfma_f32_16x16x32_bf16 v[42:45], v[152:155], v[210:213], v[42:45]
	v_mfma_f32_16x16x32_bf16 v[30:33], v[134:137], v[218:221], v[30:33]
	v_mfma_f32_16x16x32_bf16 v[10:13], v[152:155], v[240:243], v[10:13]
	v_mfma_f32_16x16x32_bf16 v[46:49], v[134:137], v[210:213], v[46:49]
	v_mfma_f32_16x16x32_bf16 v[58:61], v[152:155], v[180:183], v[58:61]
	v_mfma_f32_16x16x32_bf16 v[14:17], v[134:137], v[240:243], v[14:17]
	v_mfma_f32_16x16x32_bf16 v[26:29], v[152:155], v[218:221], v[26:29]
	v_mfma_f32_16x16x32_bf16 v[54:57], v[156:159], v[176:179], 0
	v_mfma_f32_16x16x32_bf16 v[34:37], v[168:171], v[206:209], 0
	v_mfma_f32_16x16x32_bf16 v[22:25], v[156:159], v[214:217], 0
	v_mfma_f32_16x16x32_bf16 v[2:5], v[168:171], v[236:239], 0
	v_mfma_f32_16x16x32_bf16 v[38:41], v[156:159], v[206:209], 0
	v_mfma_f32_16x16x32_bf16 v[50:53], v[168:171], v[176:179], 0
	v_mfma_f32_16x16x32_bf16 v[6:9], v[156:159], v[236:239], 0
	v_mfma_f32_16x16x32_bf16 v[18:21], v[168:171], v[214:217], 0
	v_mfma_f32_16x16x32_bf16 v[54:57], v[160:163], v[180:183], v[54:57]
	v_mfma_f32_16x16x32_bf16 v[34:37], v[172:175], v[210:213], v[34:37]
	v_mfma_f32_16x16x32_bf16 v[22:25], v[160:163], v[218:221], v[22:25]
	v_mfma_f32_16x16x32_bf16 v[2:5], v[172:175], v[240:243], v[2:5]
	v_mfma_f32_16x16x32_bf16 v[38:41], v[160:163], v[210:213], v[38:41]
	v_mfma_f32_16x16x32_bf16 v[50:53], v[172:175], v[180:183], v[50:53]
	v_mfma_f32_16x16x32_bf16 v[6:9], v[160:163], v[240:243], v[6:9]
	v_mfma_f32_16x16x32_bf16 v[18:21], v[172:175], v[218:221], v[18:21]
	s_barrier
	s_add_i32 s12, 0, 0x18000
	s_add_i32 s13, 0, 0x1c000
	ds_read_b128 v[130:133], v198
	ds_read_b128 v[134:137], v198 offset:1024
	ds_read_b128 v[138:141], v198 offset:2048
	ds_read_b128 v[152:155], v198 offset:3072
	ds_read_b128 v[156:159], v199
	ds_read_b128 v[160:163], v199 offset:1024
	ds_read_b128 v[168:171], v199 offset:2048
	ds_read_b128 v[172:175], v199 offset:3072
	s_add_u32 s10, vcc_lo, 0x200000
	s_addc_u32 s11, vcc_hi, 0
	s_mov_b32 m0, s86
	ds_read_b128 v[176:179], v166 offset:32768
	ds_read_b128 v[180:183], v166 offset:33792
	ds_read_b128 v[206:209], v166 offset:34816
	ds_read_b128 v[210:213], v166 offset:35840
	ds_read_b128 v[214:217], v166 offset:36864
	ds_read_b128 v[218:221], v166 offset:37888
	ds_read_b128 v[236:239], v166 offset:38912
	ds_read_b128 v[240:243], v166 offset:39936
	global_load_lds_dwordx4 v190, s[10:11]
	s_mov_b32 m0, s87
	s_nop 0
	global_load_lds_dwordx4 v144, s[10:11]
	s_waitcnt vmcnt(8)
	s_waitcnt lgkmcnt(0)
	s_barrier
	v_mfma_f32_16x16x32_bf16 v[126:129], v[130:133], v[176:179], v[126:129]
	v_mfma_f32_16x16x32_bf16 v[106:109], v[138:141], v[206:209], v[106:109]
	v_mfma_f32_16x16x32_bf16 v[94:97], v[130:133], v[214:217], v[94:97]
	v_mfma_f32_16x16x32_bf16 v[74:77], v[138:141], v[236:239], v[74:77]
	v_mfma_f32_16x16x32_bf16 v[110:113], v[130:133], v[206:209], v[110:113]
	v_mfma_f32_16x16x32_bf16 v[122:125], v[138:141], v[176:179], v[122:125]
	v_mfma_f32_16x16x32_bf16 v[78:81], v[130:133], v[236:239], v[78:81]
	v_mfma_f32_16x16x32_bf16 v[90:93], v[138:141], v[214:217], v[90:93]
	v_mfma_f32_16x16x32_bf16 v[126:129], v[134:137], v[180:183], v[126:129]
	v_mfma_f32_16x16x32_bf16 v[106:109], v[152:155], v[210:213], v[106:109]
	v_mfma_f32_16x16x32_bf16 v[94:97], v[134:137], v[218:221], v[94:97]
	v_mfma_f32_16x16x32_bf16 v[74:77], v[152:155], v[240:243], v[74:77]
	v_mfma_f32_16x16x32_bf16 v[110:113], v[134:137], v[210:213], v[110:113]
	v_mfma_f32_16x16x32_bf16 v[122:125], v[152:155], v[180:183], v[122:125]
	v_mfma_f32_16x16x32_bf16 v[78:81], v[134:137], v[240:243], v[78:81]
	v_mfma_f32_16x16x32_bf16 v[90:93], v[152:155], v[218:221], v[90:93]
	v_mfma_f32_16x16x32_bf16 v[118:121], v[156:159], v[176:179], v[118:121]
	v_mfma_f32_16x16x32_bf16 v[98:101], v[168:171], v[206:209], v[98:101]
	v_mfma_f32_16x16x32_bf16 v[86:89], v[156:159], v[214:217], v[86:89]
	v_mfma_f32_16x16x32_bf16 v[66:69], v[168:171], v[236:239], v[66:69]
	v_mfma_f32_16x16x32_bf16 v[102:105], v[156:159], v[206:209], v[102:105]
	v_mfma_f32_16x16x32_bf16 v[114:117], v[168:171], v[176:179], v[114:117]
	v_mfma_f32_16x16x32_bf16 v[70:73], v[156:159], v[236:239], v[70:73]
	v_mfma_f32_16x16x32_bf16 v[82:85], v[168:171], v[214:217], v[82:85]
	v_mfma_f32_16x16x32_bf16 v[118:121], v[160:163], v[180:183], v[118:121]
	v_mfma_f32_16x16x32_bf16 v[98:101], v[172:175], v[210:213], v[98:101]
	v_mfma_f32_16x16x32_bf16 v[86:89], v[160:163], v[218:221], v[86:89]
	v_mfma_f32_16x16x32_bf16 v[66:69], v[172:175], v[240:243], v[66:69]
	v_mfma_f32_16x16x32_bf16 v[102:105], v[160:163], v[210:213], v[102:105]
	v_mfma_f32_16x16x32_bf16 v[114:117], v[172:175], v[180:183], v[114:117]
	v_mfma_f32_16x16x32_bf16 v[70:73], v[160:163], v[240:243], v[70:73]
	v_mfma_f32_16x16x32_bf16 v[82:85], v[172:175], v[218:221], v[82:85]
	s_barrier
; #define PG8_STAGE(bufoff, gbase, voff) do { _Pragma("unroll") for (int _i = 0; _i < 2; ++_i) \
;         __builtin_amdgcn_global_load_lds((const unsigned*)((const char*)(gbase) + (voff)[_i]), (PG8_LAS unsigned*)(lds + (bufoff) + ldsw + _i * 8192), 16, 0, 0); } while (0)
; #define PG8_LDA(dst, b, h) do { _Pragma("unroll") for (int m = 0; m < 4; ++m) _Pragma("unroll") for (int k = 0; k < 2; ++k) dst[m][k] = *(const PG8_LAS bf16x8*)(lds + PG8_SA(b, h) + aoff + m * 2048 + k * 1024); } while (0)
; #define PG8_LDB(dst, b, h) do { _Pragma("unroll") for (int n = 0; n < 2; ++n) _Pragma("unroll") for (int k = 0; k < 2; ++k) dst[n][k] = *(const PG8_LAS bf16x8*)(lds + PG8_SB(b, h) + boff + n * 2048 + k * 1024); } while (0)
; template <class Epi, class Sched, bool ALIGN_EPI = false, bool SP2 = false>
; __device__ __forceinline__ void gemm_phase(PG8_LAS unsigned char* lds, const Gemm g, const Sched& S, const Epi& E) {
;     ...
;         for (int t = 0; t < nt; t += 2) {
;             const bool last = (t == nt - 2);
;             const char* a1 = cA + (size_t)(t + 1) * kstep;
;             const char* a2 = last ? nA : cA + (size_t)(t + 2) * kstep; const char* b2 = last ? nB : cB + (size_t)(t + 2) * kstep;
;             const char* a3 = a2 + kstep; const char* b3 = b2 + kstep;
;             if (last && has_next) S.a_ready(nxt);
;             if constexpr (SP2) {
;             PG8_LDB(B0, 0, 0); PG8_LDB(B1, 0, 1); PG8_SCHED; PG8_LDA(At, 0, 0); PG8_STAGE(PG8_SA(1, 1), a1 + hstep, voffA);
;             PG8_WAIT_V(8); PG8_WAIT_L(0); PG8_BAR; PG8_MMA(0, 0, At, B0); PG8_MMA(0, 1, At, B1); PG8_BAR; PG8_SCHED;
;             PG8_LDA(At, 0, 1); PG8_STAGE(PG8_SB(0, 0), b2, voffB); PG8_STAGE(PG8_SB(0, 1), b2 + hstepB, voffB); PG8_STAGE(PG8_SA(0, 0), a2, voffA);
;             PG8_WAIT_V(8); PG8_WAIT_L(0); PG8_BAR; PG8_MMA(1, 0, At, B0); PG8_MMA(1, 1, At, B1); PG8_BAR; PG8_SCHED;
;             PG8_LDB(B0, 1, 0); PG8_LDB(B1, 1, 1); PG8_SCHED; PG8_LDA(At, 1, 0); PG8_STAGE(PG8_SA(0, 1), a2 + hstep, voffA);
;             PG8_WAIT_V(8); PG8_WAIT_L(0); PG8_BAR; PG8_MMA(0, 0, At, B0); PG8_MMA(0, 1, At, B1); PG8_BAR; PG8_SCHED;
;             PG8_LDA(At, 1, 1); PG8_STAGE(PG8_SB(1, 0), b3, voffB); PG8_STAGE(PG8_SB(1, 1), b3 + hstepB, voffB); PG8_STAGE(PG8_SA(1, 0), a3, voffA);
;             PG8_WAIT_V(8); PG8_WAIT_L(0); PG8_BAR; PG8_MMA(1, 0, At, B0); PG8_MMA(1, 1, At, B1); PG8_BAR; PG8_SCHED;
	s_add_i32 s10, s12, s67
	s_mov_b32 m0, s10
	ds_read_b128 v[176:179], v166 offset:49152
	ds_read_b128 v[180:183], v166 offset:50176
	ds_read_b128 v[206:209], v166 offset:51200
	ds_read_b128 v[210:213], v166 offset:52224
	ds_read_b128 v[214:217], v166 offset:53248
	ds_read_b128 v[218:221], v166 offset:54272
	ds_read_b128 v[236:239], v166 offset:55296
	ds_read_b128 v[240:243], v166 offset:56320
	s_add_u32 s100, s46, s60
	s_addc_u32 s101, s47, s61
	global_load_lds_dwordx4 v146, s[100:101]
	s_add_i32 m0, s10, 0x2000
	s_add_u32 s10, s46, 0x80080
	s_addc_u32 s11, s47, 0
	s_add_i32 s12, s13, s67
	global_load_lds_dwordx4 v142, s[100:101]
	s_mov_b32 m0, s12
	s_nop 0
	global_load_lds_dwordx4 v146, s[10:11]
	s_add_i32 m0, s12, 0x2000
	s_nop 0
	global_load_lds_dwordx4 v142, s[10:11]
	s_mov_b32 m0, s82
	s_add_u32 s100, vcc_lo, s60
	s_addc_u32 s101, vcc_hi, s61
	global_load_lds_dwordx4 v190, s[100:101]
	s_mov_b32 m0, s42
	s_nop 0
	global_load_lds_dwordx4 v144, s[100:101]
	s_waitcnt vmcnt(8)
	s_waitcnt lgkmcnt(0)
	s_barrier
	v_mfma_f32_16x16x32_bf16 v[62:65], v[130:133], v[176:179], v[62:65]
	v_mfma_f32_16x16x32_bf16 v[42:45], v[138:141], v[206:209], v[42:45]
	v_mfma_f32_16x16x32_bf16 v[30:33], v[130:133], v[214:217], v[30:33]
	v_mfma_f32_16x16x32_bf16 v[10:13], v[138:141], v[236:239], v[10:13]
	v_mfma_f32_16x16x32_bf16 v[46:49], v[130:133], v[206:209], v[46:49]
	v_mfma_f32_16x16x32_bf16 v[58:61], v[138:141], v[176:179], v[58:61]
	v_mfma_f32_16x16x32_bf16 v[14:17], v[130:133], v[236:239], v[14:17]
	v_mfma_f32_16x16x32_bf16 v[26:29], v[138:141], v[214:217], v[26:29]
	v_mfma_f32_16x16x32_bf16 v[62:65], v[134:137], v[180:183], v[62:65]
	v_mfma_f32_16x16x32_bf16 v[42:45], v[152:155], v[210:213], v[42:45]
	v_mfma_f32_16x16x32_bf16 v[30:33], v[134:137], v[218:221], v[30:33]
	v_mfma_f32_16x16x32_bf16 v[10:13], v[152:155], v[240:243], v[10:13]
	v_mfma_f32_16x16x32_bf16 v[46:49], v[134:137], v[210:213], v[46:49]
	v_mfma_f32_16x16x32_bf16 v[58:61], v[152:155], v[180:183], v[58:61]
	v_mfma_f32_16x16x32_bf16 v[14:17], v[134:137], v[240:243], v[14:17]
	v_mfma_f32_16x16x32_bf16 v[26:29], v[152:155], v[218:221], v[26:29]
	v_mfma_f32_16x16x32_bf16 v[54:57], v[156:159], v[176:179], v[54:57]
	v_mfma_f32_16x16x32_bf16 v[34:37], v[168:171], v[206:209], v[34:37]
	v_mfma_f32_16x16x32_bf16 v[22:25], v[156:159], v[214:217], v[22:25]
	v_mfma_f32_16x16x32_bf16 v[2:5], v[168:171], v[236:239], v[2:5]
	v_mfma_f32_16x16x32_bf16 v[38:41], v[156:159], v[206:209], v[38:41]
	v_mfma_f32_16x16x32_bf16 v[50:53], v[168:171], v[176:179], v[50:53]
	v_mfma_f32_16x16x32_bf16 v[6:9], v[156:159], v[236:239], v[6:9]
	v_mfma_f32_16x16x32_bf16 v[18:21], v[168:171], v[214:217], v[18:21]
	v_mfma_f32_16x16x32_bf16 v[54:57], v[160:163], v[180:183], v[54:57]
	v_mfma_f32_16x16x32_bf16 v[34:37], v[172:175], v[210:213], v[34:37]
	v_mfma_f32_16x16x32_bf16 v[22:25], v[160:163], v[218:221], v[22:25]
	v_mfma_f32_16x16x32_bf16 v[2:5], v[172:175], v[240:243], v[2:5]
	v_mfma_f32_16x16x32_bf16 v[38:41], v[160:163], v[210:213], v[38:41]
	v_mfma_f32_16x16x32_bf16 v[50:53], v[172:175], v[180:183], v[50:53]
	v_mfma_f32_16x16x32_bf16 v[6:9], v[160:163], v[240:243], v[6:9]
	v_mfma_f32_16x16x32_bf16 v[18:21], v[172:175], v[218:221], v[18:21]
	s_barrier
	s_add_i32 s9, s9, 2
	s_add_u32 s38, s38, 0x100
	s_addc_u32 s39, s39, 0
	s_add_u32 s7, s7, 0x100
	s_addc_u32 s8, s8, 0
	s_cmpk_gt_u32 s9, 0x7d
.LBB0_1071:
	s_add_u32 s10, s38, 0xffe00080
	s_addc_u32 s11, s39, -1
	s_add_i32 s12, 0, 0x10000
	s_cmpk_eq_i32 s9, 0x7c
	s_cselect_b32 vcc_hi, s97, s11
	s_cselect_b32 vcc_lo, s4, s10
	s_cselect_b32 s47, s5, s8
	s_cselect_b32 s46, s6, s7
	s_add_i32 s13, 0, 0x14000
	ds_read_b128 v[130:133], v186
	ds_read_b128 v[134:137], v186 offset:1024
	ds_read_b128 v[138:141], v186 offset:2048
	ds_read_b128 v[152:155], v186 offset:3072
	ds_read_b128 v[156:159], v187
	ds_read_b128 v[160:163], v187 offset:1024
	ds_read_b128 v[168:171], v187 offset:2048
	ds_read_b128 v[172:175], v187 offset:3072
	s_add_i32 m0, s74, 0xc000
	ds_read_b128 v[176:179], v166
	ds_read_b128 v[180:183], v166 offset:1024
	ds_read_b128 v[206:209], v166 offset:2048
	ds_read_b128 v[210:213], v166 offset:3072
	ds_read_b128 v[214:217], v166 offset:4096
	ds_read_b128 v[218:221], v166 offset:5120
	ds_read_b128 v[236:239], v166 offset:6144
	ds_read_b128 v[240:243], v166 offset:7168
	global_load_lds_dwordx4 v148, s[38:39]
	s_add_i32 m0, s74, 0xe000
	s_nop 0
	global_load_lds_dwordx4 v150, s[38:39]
	s_waitcnt vmcnt(8)
	s_waitcnt lgkmcnt(0)
	s_barrier
	v_mfma_f32_16x16x32_bf16 v[126:129], v[130:133], v[176:179], v[126:129]
	v_mfma_f32_16x16x32_bf16 v[106:109], v[138:141], v[206:209], v[106:109]
	v_mfma_f32_16x16x32_bf16 v[94:97], v[130:133], v[214:217], v[94:97]
	v_mfma_f32_16x16x32_bf16 v[74:77], v[138:141], v[236:239], v[74:77]
	v_mfma_f32_16x16x32_bf16 v[110:113], v[130:133], v[206:209], v[110:113]
	v_mfma_f32_16x16x32_bf16 v[122:125], v[138:141], v[176:179], v[122:125]
	v_mfma_f32_16x16x32_bf16 v[78:81], v[130:133], v[236:239], v[78:81]
	v_mfma_f32_16x16x32_bf16 v[90:93], v[138:141], v[214:217], v[90:93]
	v_mfma_f32_16x16x32_bf16 v[126:129], v[134:137], v[180:183], v[126:129]
	v_mfma_f32_16x16x32_bf16 v[106:109], v[152:155], v[210:213], v[106:109]
	v_mfma_f32_16x16x32_bf16 v[94:97], v[134:137], v[218:221], v[94:97]
	v_mfma_f32_16x16x32_bf16 v[74:77], v[152:155], v[240:243], v[74:77]
	v_mfma_f32_16x16x32_bf16 v[110:113], v[134:137], v[210:213], v[110:113]
	v_mfma_f32_16x16x32_bf16 v[122:125], v[152:155], v[180:183], v[122:125]
	v_mfma_f32_16x16x32_bf16 v[78:81], v[134:137], v[240:243], v[78:81]
	v_mfma_f32_16x16x32_bf16 v[90:93], v[152:155], v[218:221], v[90:93]
	v_mfma_f32_16x16x32_bf16 v[118:121], v[156:159], v[176:179], v[118:121]
	v_mfma_f32_16x16x32_bf16 v[98:101], v[168:171], v[206:209], v[98:101]
	v_mfma_f32_16x16x32_bf16 v[86:89], v[156:159], v[214:217], v[86:89]
	v_mfma_f32_16x16x32_bf16 v[66:69], v[168:171], v[236:239], v[66:69]
	v_mfma_f32_16x16x32_bf16 v[102:105], v[156:159], v[206:209], v[102:105]
	v_mfma_f32_16x16x32_bf16 v[114:117], v[168:171], v[176:179], v[114:117]
	v_mfma_f32_16x16x32_bf16 v[70:73], v[156:159], v[236:239], v[70:73]
	v_mfma_f32_16x16x32_bf16 v[82:85], v[168:171], v[214:217], v[82:85]
	v_mfma_f32_16x16x32_bf16 v[118:121], v[160:163], v[180:183], v[118:121]
	v_mfma_f32_16x16x32_bf16 v[98:101], v[172:175], v[210:213], v[98:101]
	v_mfma_f32_16x16x32_bf16 v[86:89], v[160:163], v[218:221], v[86:89]
	v_mfma_f32_16x16x32_bf16 v[66:69], v[172:175], v[240:243], v[66:69]
	v_mfma_f32_16x16x32_bf16 v[102:105], v[160:163], v[210:213], v[102:105]
	v_mfma_f32_16x16x32_bf16 v[114:117], v[172:175], v[180:183], v[114:117]
	v_mfma_f32_16x16x32_bf16 v[70:73], v[160:163], v[240:243], v[70:73]
	v_mfma_f32_16x16x32_bf16 v[82:85], v[172:175], v[218:221], v[82:85]
	s_barrier
; #define PG8_STAGE(bufoff, gbase, voff) do { _Pragma("unroll") for (int _i = 0; _i < 2; ++_i) \
;         __builtin_amdgcn_global_load_lds((const unsigned*)((const char*)(gbase) + (voff)[_i]), (PG8_LAS unsigned*)(lds + (bufoff) + ldsw + _i * 8192), 16, 0, 0); } while (0)
; #define PG8_LDA(dst, b, h) do { _Pragma("unroll") for (int m = 0; m < 4; ++m) _Pragma("unroll") for (int k = 0; k < 2; ++k) dst[m][k] = *(const PG8_LAS bf16x8*)(lds + PG8_SA(b, h) + aoff + m * 2048 + k * 1024); } while (0)
; #define PG8_LDB(dst, b, h) do { _Pragma("unroll") for (int n = 0; n < 2; ++n) _Pragma("unroll") for (int k = 0; k < 2; ++k) dst[n][k] = *(const PG8_LAS bf16x8*)(lds + PG8_SB(b, h) + boff + n * 2048 + k * 1024); } while (0)
; #define PG8_MMA(ai, bj, At, Bt) do { __builtin_amdgcn_s_setprio(1); _Pragma("unroll") for (int m = 0; m < 4; ++m) _Pragma("unroll") for (int n = 0; n < 2; ++n) _Pragma("unroll") for (int k = 0; k < 2; ++k) \
;         acc[ai][bj][m][n] = __builtin_amdgcn_mfma_f32_16x16x32_bf16(Bt[n][k], At[m][k], acc[ai][bj][m][n], 0, 0, 0); __builtin_amdgcn_s_setprio(0); } while (0)
; #define PG8_WAIT_V(n) asm volatile("s_waitcnt vmcnt(" #n ")" ::: "memory")
; #define PG8_WAIT_L(n) asm volatile("s_waitcnt lgkmcnt(" #n ")" ::: "memory")
; #define PG8_BAR __builtin_amdgcn_s_barrier()
; #define PG8_SCHED __builtin_amdgcn_sched_barrier(0)
; template <class Epi, class Sched, bool ALIGN_EPI = false, bool SP2 = false>
; __device__ __forceinline__ void gemm_phase(PG8_LAS unsigned char* lds, const Gemm g, const Sched& S, const Epi& E) {
;     ...
;             PG8_LDA(At, 0, 1); PG8_STAGE(PG8_SB(0, 0), b2, voffB); PG8_STAGE(PG8_SB(0, 1), b2 + hstepB, voffB); PG8_STAGE(PG8_SA(0, 0), a2, voffA);
;             PG8_WAIT_V(8); PG8_WAIT_L(0); PG8_BAR; PG8_MMA(1, 0, At, B0); PG8_MMA(1, 1, At, B1); PG8_BAR; PG8_SCHED;
;             PG8_LDB(B0, 1, 0); PG8_LDB(B1, 1, 1); PG8_SCHED; PG8_LDA(At, 1, 0); PG8_STAGE(PG8_SA(0, 1), a2 + hstep, voffA);
	s_add_i32 s10, s12, s67
	s_mov_b32 m0, s10
	ds_read_b128 v[176:179], v166 offset:16384
	ds_read_b128 v[180:183], v166 offset:17408
	ds_read_b128 v[206:209], v166 offset:18432
	ds_read_b128 v[210:213], v166 offset:19456
	ds_read_b128 v[214:217], v166 offset:20480
	ds_read_b128 v[218:221], v166 offset:21504
	ds_read_b128 v[236:239], v166 offset:22528
	ds_read_b128 v[240:243], v166 offset:23552
	global_load_lds_dwordx4 v146, s[46:47]
	s_add_i32 m0, s10, 0x2000
	s_add_u32 s10, s46, 0x80000
	s_addc_u32 s11, s47, 0
	s_add_i32 s12, s13, s67
	global_load_lds_dwordx4 v142, s[46:47]
	s_mov_b32 m0, s12
	s_nop 0
	global_load_lds_dwordx4 v146, s[10:11]
	s_add_i32 m0, s12, 0x2000
	s_nop 0
	global_load_lds_dwordx4 v142, s[10:11]
	s_mov_b32 m0, s74
	s_nop 0
	global_load_lds_dwordx4 v190, vcc
	s_mov_b32 m0, s75
	s_nop 0
	global_load_lds_dwordx4 v144, vcc
	s_waitcnt vmcnt(8)
	s_waitcnt lgkmcnt(0)
	s_barrier
	v_mfma_f32_16x16x32_bf16 v[62:65], v[130:133], v[176:179], v[62:65]
	v_mfma_f32_16x16x32_bf16 v[42:45], v[138:141], v[206:209], v[42:45]
	v_mfma_f32_16x16x32_bf16 v[30:33], v[130:133], v[214:217], v[30:33]
	v_mfma_f32_16x16x32_bf16 v[10:13], v[138:141], v[236:239], v[10:13]
	v_mfma_f32_16x16x32_bf16 v[46:49], v[130:133], v[206:209], v[46:49]
	v_mfma_f32_16x16x32_bf16 v[58:61], v[138:141], v[176:179], v[58:61]
	v_mfma_f32_16x16x32_bf16 v[14:17], v[130:133], v[236:239], v[14:17]
	v_mfma_f32_16x16x32_bf16 v[26:29], v[138:141], v[214:217], v[26:29]
	v_mfma_f32_16x16x32_bf16 v[62:65], v[134:137], v[180:183], v[62:65]
	v_mfma_f32_16x16x32_bf16 v[42:45], v[152:155], v[210:213], v[42:45]
	v_mfma_f32_16x16x32_bf16 v[30:33], v[134:137], v[218:221], v[30:33]
	v_mfma_f32_16x16x32_bf16 v[10:13], v[152:155], v[240:243], v[10:13]
	v_mfma_f32_16x16x32_bf16 v[46:49], v[134:137], v[210:213], v[46:49]
	v_mfma_f32_16x16x32_bf16 v[58:61], v[152:155], v[180:183], v[58:61]
	v_mfma_f32_16x16x32_bf16 v[14:17], v[134:137], v[240:243], v[14:17]
	v_mfma_f32_16x16x32_bf16 v[26:29], v[152:155], v[218:221], v[26:29]
	v_mfma_f32_16x16x32_bf16 v[54:57], v[156:159], v[176:179], v[54:57]
	v_mfma_f32_16x16x32_bf16 v[34:37], v[168:171], v[206:209], v[34:37]
	v_mfma_f32_16x16x32_bf16 v[22:25], v[156:159], v[214:217], v[22:25]
	v_mfma_f32_16x16x32_bf16 v[2:5], v[168:171], v[236:239], v[2:5]
	v_mfma_f32_16x16x32_bf16 v[38:41], v[156:159], v[206:209], v[38:41]
	v_mfma_f32_16x16x32_bf16 v[50:53], v[168:171], v[176:179], v[50:53]
	v_mfma_f32_16x16x32_bf16 v[6:9], v[156:159], v[236:239], v[6:9]
	v_mfma_f32_16x16x32_bf16 v[18:21], v[168:171], v[214:217], v[18:21]
	v_mfma_f32_16x16x32_bf16 v[54:57], v[160:163], v[180:183], v[54:57]
	v_mfma_f32_16x16x32_bf16 v[34:37], v[172:175], v[210:213], v[34:37]
	v_mfma_f32_16x16x32_bf16 v[22:25], v[160:163], v[218:221], v[22:25]
	v_mfma_f32_16x16x32_bf16 v[2:5], v[172:175], v[240:243], v[2:5]
	v_mfma_f32_16x16x32_bf16 v[38:41], v[160:163], v[210:213], v[38:41]
	v_mfma_f32_16x16x32_bf16 v[50:53], v[172:175], v[180:183], v[50:53]
	v_mfma_f32_16x16x32_bf16 v[6:9], v[160:163], v[240:243], v[6:9]
	v_mfma_f32_16x16x32_bf16 v[18:21], v[172:175], v[218:221], v[18:21]
	s_barrier
	s_add_i32 s12, 0, 0x18000
	s_add_i32 s13, 0, 0x1c000
	ds_read_b128 v[130:133], v198
	ds_read_b128 v[134:137], v198 offset:1024
	ds_read_b128 v[138:141], v198 offset:2048
	ds_read_b128 v[152:155], v198 offset:3072
	ds_read_b128 v[156:159], v199
	ds_read_b128 v[160:163], v199 offset:1024
	ds_read_b128 v[168:171], v199 offset:2048
	ds_read_b128 v[172:175], v199 offset:3072
	s_add_u32 s10, vcc_lo, 0x200000
	s_addc_u32 s11, vcc_hi, 0
	s_mov_b32 m0, s86
	ds_read_b128 v[176:179], v166 offset:32768
	ds_read_b128 v[180:183], v166 offset:33792
	ds_read_b128 v[206:209], v166 offset:34816
	ds_read_b128 v[210:213], v166 offset:35840
	ds_read_b128 v[214:217], v166 offset:36864
	ds_read_b128 v[218:221], v166 offset:37888
	ds_read_b128 v[236:239], v166 offset:38912
	ds_read_b128 v[240:243], v166 offset:39936
	global_load_lds_dwordx4 v190, s[10:11]
	s_mov_b32 m0, s87
	s_nop 0
	global_load_lds_dwordx4 v144, s[10:11]
	s_waitcnt vmcnt(8)
	s_waitcnt lgkmcnt(0)
	s_barrier
; #define PG8_STAGE(bufoff, gbase, voff) do { _Pragma("unroll") for (int _i = 0; _i < 2; ++_i) \
;         __builtin_amdgcn_global_load_lds((const unsigned*)((const char*)(gbase) + (voff)[_i]), (PG8_LAS unsigned*)(lds + (bufoff) + ldsw + _i * 8192), 16, 0, 0); } while (0)
; #define PG8_LDA(dst, b, h) do { _Pragma("unroll") for (int m = 0; m < 4; ++m) _Pragma("unroll") for (int k = 0; k < 2; ++k) dst[m][k] = *(const PG8_LAS bf16x8*)(lds + PG8_SA(b, h) + aoff + m * 2048 + k * 1024); } while (0)
; #define PG8_MMA(ai, bj, At, Bt) do { __builtin_amdgcn_s_setprio(1); _Pragma("unroll") for (int m = 0; m < 4; ++m) _Pragma("unroll") for (int n = 0; n < 2; ++n) _Pragma("unroll") for (int k = 0; k < 2; ++k) \
;         acc[ai][bj][m][n] = __builtin_amdgcn_mfma_f32_16x16x32_bf16(Bt[n][k], At[m][k], acc[ai][bj][m][n], 0, 0, 0); __builtin_amdgcn_s_setprio(0); } while (0)
; #define PG8_WAIT_V(n) asm volatile("s_waitcnt vmcnt(" #n ")" ::: "memory")
; #define PG8_WAIT_L(n) asm volatile("s_waitcnt lgkmcnt(" #n ")" ::: "memory")
; #define PG8_BAR __builtin_amdgcn_s_barrier()
; #define PG8_SCHED __builtin_amdgcn_sched_barrier(0)
; template <class Epi, class Sched, bool ALIGN_EPI = false, bool SP2 = false>
; __device__ __forceinline__ void gemm_phase(PG8_LAS unsigned char* lds, const Gemm g, const Sched& S, const Epi& E) {
;     ...
;             PG8_WAIT_V(8); PG8_WAIT_L(0); PG8_BAR; PG8_MMA(0, 0, At, B0); PG8_MMA(0, 1, At, B1); PG8_BAR; PG8_SCHED;
;             PG8_LDA(At, 1, 1); PG8_STAGE(PG8_SB(1, 0), b3, voffB); PG8_STAGE(PG8_SB(1, 1), b3 + hstepB, voffB); PG8_STAGE(PG8_SA(1, 0), a3, voffA);
;             PG8_WAIT_V(8); PG8_WAIT_L(0); PG8_BAR; PG8_MMA(1, 0, At, B0); PG8_MMA(1, 1, At, B1); PG8_BAR; PG8_SCHED;
;     ...
;         if constexpr (ALIGN_EPI) { if (wr == 0) PG8_BAR; }
	v_mfma_f32_16x16x32_bf16 v[126:129], v[130:133], v[176:179], v[126:129]
	v_mfma_f32_16x16x32_bf16 v[106:109], v[138:141], v[206:209], v[106:109]
	v_mfma_f32_16x16x32_bf16 v[94:97], v[130:133], v[214:217], v[94:97]
	v_mfma_f32_16x16x32_bf16 v[74:77], v[138:141], v[236:239], v[74:77]
	v_mfma_f32_16x16x32_bf16 v[110:113], v[130:133], v[206:209], v[110:113]
	v_mfma_f32_16x16x32_bf16 v[122:125], v[138:141], v[176:179], v[122:125]
	v_mfma_f32_16x16x32_bf16 v[78:81], v[130:133], v[236:239], v[78:81]
	v_mfma_f32_16x16x32_bf16 v[90:93], v[138:141], v[214:217], v[90:93]
	v_mfma_f32_16x16x32_bf16 v[126:129], v[134:137], v[180:183], v[126:129]
	v_mfma_f32_16x16x32_bf16 v[106:109], v[152:155], v[210:213], v[106:109]
	v_mfma_f32_16x16x32_bf16 v[94:97], v[134:137], v[218:221], v[94:97]
	v_mfma_f32_16x16x32_bf16 v[74:77], v[152:155], v[240:243], v[74:77]
	v_mfma_f32_16x16x32_bf16 v[110:113], v[134:137], v[210:213], v[110:113]
	v_mfma_f32_16x16x32_bf16 v[122:125], v[152:155], v[180:183], v[122:125]
	v_mfma_f32_16x16x32_bf16 v[78:81], v[134:137], v[240:243], v[78:81]
	v_mfma_f32_16x16x32_bf16 v[90:93], v[152:155], v[218:221], v[90:93]
	v_mfma_f32_16x16x32_bf16 v[118:121], v[156:159], v[176:179], v[118:121]
	v_mfma_f32_16x16x32_bf16 v[98:101], v[168:171], v[206:209], v[98:101]
	v_mfma_f32_16x16x32_bf16 v[86:89], v[156:159], v[214:217], v[86:89]
	v_mfma_f32_16x16x32_bf16 v[66:69], v[168:171], v[236:239], v[66:69]
	v_mfma_f32_16x16x32_bf16 v[102:105], v[156:159], v[206:209], v[102:105]
	v_mfma_f32_16x16x32_bf16 v[114:117], v[168:171], v[176:179], v[114:117]
	v_mfma_f32_16x16x32_bf16 v[70:73], v[156:159], v[236:239], v[70:73]
	v_mfma_f32_16x16x32_bf16 v[82:85], v[168:171], v[214:217], v[82:85]
	v_mfma_f32_16x16x32_bf16 v[118:121], v[160:163], v[180:183], v[118:121]
	v_mfma_f32_16x16x32_bf16 v[98:101], v[172:175], v[210:213], v[98:101]
	v_mfma_f32_16x16x32_bf16 v[86:89], v[160:163], v[218:221], v[86:89]
	v_mfma_f32_16x16x32_bf16 v[66:69], v[172:175], v[240:243], v[66:69]
	v_mfma_f32_16x16x32_bf16 v[102:105], v[160:163], v[210:213], v[102:105]
	v_mfma_f32_16x16x32_bf16 v[114:117], v[172:175], v[180:183], v[114:117]
	v_mfma_f32_16x16x32_bf16 v[70:73], v[160:163], v[240:243], v[70:73]
	v_mfma_f32_16x16x32_bf16 v[82:85], v[172:175], v[218:221], v[82:85]
	s_barrier
	s_add_i32 s10, s12, s67
	s_mov_b32 m0, s10
	ds_read_b128 v[176:179], v166 offset:49152
	ds_read_b128 v[180:183], v166 offset:50176
	ds_read_b128 v[206:209], v166 offset:51200
	ds_read_b128 v[210:213], v166 offset:52224
	ds_read_b128 v[214:217], v166 offset:53248
	ds_read_b128 v[218:221], v166 offset:54272
	ds_read_b128 v[236:239], v166 offset:55296
	ds_read_b128 v[240:243], v166 offset:56320
	s_add_u32 s100, s46, s60
	s_addc_u32 s101, s47, s61
	global_load_lds_dwordx4 v146, s[100:101]
	s_add_i32 m0, s10, 0x2000
	s_add_u32 s10, s46, 0x80080
	s_addc_u32 s11, s47, 0
	s_add_i32 s12, s13, s67
	global_load_lds_dwordx4 v142, s[100:101]
	s_mov_b32 m0, s12
	s_nop 0
	global_load_lds_dwordx4 v146, s[10:11]
	s_add_i32 m0, s12, 0x2000
	s_nop 0
	global_load_lds_dwordx4 v142, s[10:11]
	s_mov_b32 m0, s82
	s_add_u32 s100, vcc_lo, s60
	s_addc_u32 s101, vcc_hi, s61
	global_load_lds_dwordx4 v190, s[100:101]
	s_mov_b32 m0, s42
	s_nop 0
	global_load_lds_dwordx4 v144, s[100:101]
	s_waitcnt vmcnt(8)
	s_waitcnt lgkmcnt(0)
	s_barrier
	v_mfma_f32_16x16x32_bf16 v[62:65], v[130:133], v[176:179], v[62:65]
	v_mfma_f32_16x16x32_bf16 v[42:45], v[138:141], v[206:209], v[42:45]
	v_mfma_f32_16x16x32_bf16 v[30:33], v[130:133], v[214:217], v[30:33]
	v_mfma_f32_16x16x32_bf16 v[10:13], v[138:141], v[236:239], v[10:13]
	v_mfma_f32_16x16x32_bf16 v[46:49], v[130:133], v[206:209], v[46:49]
	v_mfma_f32_16x16x32_bf16 v[58:61], v[138:141], v[176:179], v[58:61]
	v_mfma_f32_16x16x32_bf16 v[14:17], v[130:133], v[236:239], v[14:17]
	v_mfma_f32_16x16x32_bf16 v[26:29], v[138:141], v[214:217], v[26:29]
	v_mfma_f32_16x16x32_bf16 v[62:65], v[134:137], v[180:183], v[62:65]
	v_mfma_f32_16x16x32_bf16 v[42:45], v[152:155], v[210:213], v[42:45]
	v_mfma_f32_16x16x32_bf16 v[30:33], v[134:137], v[218:221], v[30:33]
	v_mfma_f32_16x16x32_bf16 v[10:13], v[152:155], v[240:243], v[10:13]
	v_mfma_f32_16x16x32_bf16 v[46:49], v[134:137], v[210:213], v[46:49]
	v_mfma_f32_16x16x32_bf16 v[58:61], v[152:155], v[180:183], v[58:61]
	v_mfma_f32_16x16x32_bf16 v[14:17], v[134:137], v[240:243], v[14:17]
	v_mfma_f32_16x16x32_bf16 v[26:29], v[152:155], v[218:221], v[26:29]
	v_mfma_f32_16x16x32_bf16 v[54:57], v[156:159], v[176:179], v[54:57]
	v_mfma_f32_16x16x32_bf16 v[34:37], v[168:171], v[206:209], v[34:37]
	v_mfma_f32_16x16x32_bf16 v[22:25], v[156:159], v[214:217], v[22:25]
	v_mfma_f32_16x16x32_bf16 v[2:5], v[168:171], v[236:239], v[2:5]
	v_mfma_f32_16x16x32_bf16 v[38:41], v[156:159], v[206:209], v[38:41]
	v_mfma_f32_16x16x32_bf16 v[50:53], v[168:171], v[176:179], v[50:53]
	v_mfma_f32_16x16x32_bf16 v[6:9], v[156:159], v[236:239], v[6:9]
	v_mfma_f32_16x16x32_bf16 v[18:21], v[168:171], v[214:217], v[18:21]
	v_mfma_f32_16x16x32_bf16 v[54:57], v[160:163], v[180:183], v[54:57]
	v_mfma_f32_16x16x32_bf16 v[34:37], v[172:175], v[210:213], v[34:37]
	v_mfma_f32_16x16x32_bf16 v[22:25], v[160:163], v[218:221], v[22:25]
	v_mfma_f32_16x16x32_bf16 v[2:5], v[172:175], v[240:243], v[2:5]
	v_mfma_f32_16x16x32_bf16 v[38:41], v[160:163], v[210:213], v[38:41]
	v_mfma_f32_16x16x32_bf16 v[50:53], v[172:175], v[180:183], v[50:53]
	v_mfma_f32_16x16x32_bf16 v[6:9], v[160:163], v[240:243], v[6:9]
	v_mfma_f32_16x16x32_bf16 v[18:21], v[172:175], v[218:221], v[18:21]
	s_barrier
	s_add_i32 s9, s9, 2
	s_add_u32 s38, s38, 0x100
	s_addc_u32 s39, s39, 0
	s_add_u32 s7, s7, 0x100
	s_addc_u32 s8, s8, 0
	s_cmpk_gt_u32 s9, 0x7d
	s_cbranch_scc0 .LBB0_1071
	s_and_b64 vcc, exec, s[72:73]
	s_cbranch_vccz .LBB0_1074
	s_barrier

; #define PG8_STAGE(bufoff, gbase, voff) do { _Pragma("unroll") for (int _i = 0; _i < 2; ++_i) \
;         __builtin_amdgcn_global_load_lds((const unsigned*)((const char*)(gbase) + (voff)[_i]), (PG8_LAS unsigned*)(lds + (bufoff) + ldsw + _i * 8192), 16, 0, 0); } while (0)
; #define PG8_LDA(dst, b, h) do { _Pragma("unroll") for (int m = 0; m < 4; ++m) _Pragma("unroll") for (int k = 0; k < 2; ++k) dst[m][k] = *(const PG8_LAS bf16x8*)(lds + PG8_SA(b, h) + aoff + m * 2048 + k * 1024); } while (0)
; #define PG8_LDB(dst, b, h) do { _Pragma("unroll") for (int n = 0; n < 2; ++n) _Pragma("unroll") for (int k = 0; k < 2; ++k) dst[n][k] = *(const PG8_LAS bf16x8*)(lds + PG8_SB(b, h) + boff + n * 2048 + k * 1024); } while (0)
; #define PG8_MMA(ai, bj, At, Bt) do { __builtin_amdgcn_s_setprio(1); _Pragma("unroll") for (int m = 0; m < 4; ++m) _Pragma("unroll") for (int n = 0; n < 2; ++n) _Pragma("unroll") for (int k = 0; k < 2; ++k) \
;         acc[ai][bj][m][n] = __builtin_amdgcn_mfma_f32_16x16x32_bf16(Bt[n][k], At[m][k], acc[ai][bj][m][n], 0, 0, 0); __builtin_amdgcn_s_setprio(0); } while (0)
; #define PG8_BAR __builtin_amdgcn_s_barrier()
; template <class Epi, class Sched, bool ALIGN_EPI = false, bool SP2 = false>
; __device__ __forceinline__ void gemm_phase(PG8_LAS unsigned char* lds, const Gemm g, const Sched& S, const Epi& E) {
;     ...
;         const bool has_next = S.next(ui + 1, nxt);
;         const char* nA = has_next ? (const char*)g.A + (size_t)nxt.pm * tstep : cA; const char* nB = has_next ? (const char*)g.Bt + (size_t)nxt.pn * tstep : cB;
;         for (int t = 0; t < nt; t += 2) {
;             const bool last = (t == nt - 2);
;             const char* a1 = cA + (size_t)(t + 1) * kstep;
;             const char* a2 = last ? nA : cA + (size_t)(t + 2) * kstep; const char* b2 = last ? nB : cB + (size_t)(t + 2) * kstep;
;             const char* a3 = a2 + kstep; const char* b3 = b2 + kstep;
;             if (last && has_next) S.a_ready(nxt);
;             if constexpr (SP2) {
;             PG8_LDB(B0, 0, 0); PG8_LDB(B1, 0, 1); PG8_SCHED; PG8_LDA(At, 0, 0); PG8_STAGE(PG8_SA(1, 1), a1 + hstep, voffA);
;             PG8_WAIT_V(8); PG8_WAIT_L(0); PG8_BAR; PG8_MMA(0, 0, At, B0); PG8_MMA(0, 1, At, B1); PG8_BAR; PG8_SCHED;
;             PG8_LDA(At, 0, 1); PG8_STAGE(PG8_SB(0, 0), b2, voffB); PG8_STAGE(PG8_SB(0, 1), b2 + hstepB, voffB); PG8_STAGE(PG8_SA(0, 0), a2, voffA);
.LBB0_1232:
	s_add_u32 s36, s80, 0x100
	s_addc_u32 s37, s81, 0
	s_ashr_i32 s73, s72, 31
	s_lshl_b64 s[4:5], s[72:73], 20
	s_add_u32 s78, s0, s4
	s_addc_u32 s79, s1, s5
	s_and_b64 s[4:5], s[46:47], exec
	s_cselect_b32 s4, s79, s69
	s_cselect_b32 s5, s78, s68
	s_ashr_i32 s71, s70, 31
	s_lshl_b64 s[6:7], s[70:71], 20
	s_add_u32 s76, s34, s6
	s_addc_u32 s77, s35, s7
	s_and_b64 s[6:7], s[46:47], exec
	s_cselect_b32 s6, s77, s81
	s_cselect_b32 s7, s76, s80
	s_add_u32 s8, s68, 0x80080
	s_addc_u32 s9, s69, 0
	v_lshl_add_u64 v[140:141], s[8:9], 0, v[136:137]
	v_lshl_add_u64 v[142:143], s[8:9], 0, v[138:139]
	s_mov_b32 s8, -2
	s_mov_b64 s[80:81], 0
	v_add_u32_e32 v186, 0x10000, v145
	v_add_u32_e32 v187, 0x14000, v145
	v_add_u32_e32 v198, 0x18000, v145
	v_add_u32_e32 v199, 0x1c000, v145
	s_add_u32 s9, s68, s80
	s_addc_u32 s10, s69, s81
	s_add_u32 s9, s9, 0x100
	s_addc_u32 s10, s10, 0
	s_add_u32 s100, s9, 0x7ff80
	s_addc_u32 s101, s10, 0
	s_add_u32 s11, s36, s80
	s_addc_u32 s12, s37, s81
	s_add_i32 s13, 0, 0x10000
	s_cmpk_eq_i32 s80, 0xf00
	s_cselect_b32 s93, s4, s10
	s_cselect_b32 s92, s5, s9
	s_cselect_b32 s85, s6, s12
	s_cselect_b32 s84, s7, s11
	s_add_i32 s9, 0, 0x14000
	ds_read_b128 v[152:155], v186
	ds_read_b128 v[156:159], v186 offset:1024
	ds_read_b128 v[160:163], v186 offset:2048
	ds_read_b128 v[164:167], v186 offset:3072
	ds_read_b128 v[168:171], v187
	ds_read_b128 v[172:175], v187 offset:1024
	ds_read_b128 v[176:179], v187 offset:2048
	ds_read_b128 v[180:183], v187 offset:3072
	s_add_i32 m0, s51, 0xc000
	ds_read_b128 v[206:209], v151
	ds_read_b128 v[210:213], v151 offset:1024
	ds_read_b128 v[214:217], v151 offset:2048
	ds_read_b128 v[218:221], v151 offset:3072
	ds_read_b128 v[236:239], v151 offset:4096
	ds_read_b128 v[240:243], v151 offset:5120
	ds_read_b128 v[244:247], v151 offset:6144
	ds_read_b128 v[194:197], v151 offset:7168
	global_load_lds_dwordx4 v136, s[100:101]
	s_add_i32 m0, s51, 0xe000
	s_nop 0
	global_load_lds_dwordx4 v138, s[100:101]
	s_waitcnt vmcnt(8)
	s_waitcnt lgkmcnt(0)
	s_barrier
	v_mfma_f32_16x16x32_bf16 v[126:129], v[152:155], v[206:209], 0
	v_mfma_f32_16x16x32_bf16 v[114:117], v[160:163], v[214:217], 0
	v_mfma_f32_16x16x32_bf16 v[110:113], v[152:155], v[236:239], 0
	v_mfma_f32_16x16x32_bf16 v[98:101], v[160:163], v[244:247], 0
	v_mfma_f32_16x16x32_bf16 v[118:121], v[152:155], v[214:217], 0
	v_mfma_f32_16x16x32_bf16 v[122:125], v[160:163], v[206:209], 0
	v_mfma_f32_16x16x32_bf16 v[102:105], v[152:155], v[244:247], 0
	v_mfma_f32_16x16x32_bf16 v[106:109], v[160:163], v[236:239], 0
	v_mfma_f32_16x16x32_bf16 v[126:129], v[156:159], v[210:213], v[126:129]
	v_mfma_f32_16x16x32_bf16 v[114:117], v[164:167], v[218:221], v[114:117]
	v_mfma_f32_16x16x32_bf16 v[110:113], v[156:159], v[240:243], v[110:113]
	v_mfma_f32_16x16x32_bf16 v[98:101], v[164:167], v[194:197], v[98:101]
	v_mfma_f32_16x16x32_bf16 v[118:121], v[156:159], v[218:221], v[118:121]
	v_mfma_f32_16x16x32_bf16 v[122:125], v[164:167], v[210:213], v[122:125]
	v_mfma_f32_16x16x32_bf16 v[102:105], v[156:159], v[194:197], v[102:105]
	v_mfma_f32_16x16x32_bf16 v[106:109], v[164:167], v[240:243], v[106:109]
	v_mfma_f32_16x16x32_bf16 v[94:97], v[168:171], v[206:209], 0
	v_mfma_f32_16x16x32_bf16 v[82:85], v[176:179], v[214:217], 0
	v_mfma_f32_16x16x32_bf16 v[78:81], v[168:171], v[236:239], 0
	v_mfma_f32_16x16x32_bf16 v[66:69], v[176:179], v[244:247], 0
	v_mfma_f32_16x16x32_bf16 v[86:89], v[168:171], v[214:217], 0
	v_mfma_f32_16x16x32_bf16 v[90:93], v[176:179], v[206:209], 0
	v_mfma_f32_16x16x32_bf16 v[70:73], v[168:171], v[244:247], 0
	v_mfma_f32_16x16x32_bf16 v[74:77], v[176:179], v[236:239], 0
	v_mfma_f32_16x16x32_bf16 v[94:97], v[172:175], v[210:213], v[94:97]
	v_mfma_f32_16x16x32_bf16 v[82:85], v[180:183], v[218:221], v[82:85]
	v_mfma_f32_16x16x32_bf16 v[78:81], v[172:175], v[240:243], v[78:81]
	v_mfma_f32_16x16x32_bf16 v[66:69], v[180:183], v[194:197], v[66:69]
	v_mfma_f32_16x16x32_bf16 v[86:89], v[172:175], v[218:221], v[86:89]
	v_mfma_f32_16x16x32_bf16 v[90:93], v[180:183], v[210:213], v[90:93]
	v_mfma_f32_16x16x32_bf16 v[70:73], v[172:175], v[194:197], v[70:73]
	v_mfma_f32_16x16x32_bf16 v[74:77], v[180:183], v[240:243], v[74:77]
	s_barrier
	s_add_i32 s10, s13, s42
	s_mov_b32 m0, s10
	ds_read_b128 v[194:197], v151 offset:16384
	ds_read_b128 v[206:209], v151 offset:17408
	ds_read_b128 v[210:213], v151 offset:18432
	ds_read_b128 v[214:217], v151 offset:19456
	ds_read_b128 v[218:221], v151 offset:20480
	ds_read_b128 v[236:239], v151 offset:21504
	ds_read_b128 v[240:243], v151 offset:22528
	ds_read_b128 v[244:247], v151 offset:23552
	global_load_lds_dwordx4 v130, s[84:85]
	s_add_i32 m0, s10, 0x2000
	s_add_u32 s10, s84, 0x20000
	s_addc_u32 s11, s85, 0
	s_add_i32 s9, s9, s42
	global_load_lds_dwordx4 v134, s[84:85]
	s_mov_b32 m0, s9
	s_nop 0
	global_load_lds_dwordx4 v130, s[10:11]
	s_add_i32 m0, s9, 0x2000
	s_nop 0
	global_load_lds_dwordx4 v134, s[10:11]
	s_mov_b32 m0, s51
	s_nop 0
	global_load_lds_dwordx4 v190, s[92:93]
	s_mov_b32 m0, s67
	s_nop 0
	global_load_lds_dwordx4 v132, s[92:93]
	s_waitcnt vmcnt(8)
	s_waitcnt lgkmcnt(0)
	s_barrier
; #define PG8_STAGE(bufoff, gbase, voff) do { _Pragma("unroll") for (int _i = 0; _i < 2; ++_i) \
;         __builtin_amdgcn_global_load_lds((const unsigned*)((const char*)(gbase) + (voff)[_i]), (PG8_LAS unsigned*)(lds + (bufoff) + ldsw + _i * 8192), 16, 0, 0); } while (0)
; #define PG8_LDA(dst, b, h) do { _Pragma("unroll") for (int m = 0; m < 4; ++m) _Pragma("unroll") for (int k = 0; k < 2; ++k) dst[m][k] = *(const PG8_LAS bf16x8*)(lds + PG8_SA(b, h) + aoff + m * 2048 + k * 1024); } while (0)
; #define PG8_LDB(dst, b, h) do { _Pragma("unroll") for (int n = 0; n < 2; ++n) _Pragma("unroll") for (int k = 0; k < 2; ++k) dst[n][k] = *(const PG8_LAS bf16x8*)(lds + PG8_SB(b, h) + boff + n * 2048 + k * 1024); } while (0)
; #define PG8_MMA(ai, bj, At, Bt) do { __builtin_amdgcn_s_setprio(1); _Pragma("unroll") for (int m = 0; m < 4; ++m) _Pragma("unroll") for (int n = 0; n < 2; ++n) _Pragma("unroll") for (int k = 0; k < 2; ++k) \
;         acc[ai][bj][m][n] = __builtin_amdgcn_mfma_f32_16x16x32_bf16(Bt[n][k], At[m][k], acc[ai][bj][m][n], 0, 0, 0); __builtin_amdgcn_s_setprio(0); } while (0)
; #define PG8_WAIT_V(n) asm volatile("s_waitcnt vmcnt(" #n ")" ::: "memory")
; #define PG8_WAIT_L(n) asm volatile("s_waitcnt lgkmcnt(" #n ")" ::: "memory")
; #define PG8_BAR __builtin_amdgcn_s_barrier()
; #define PG8_SCHED __builtin_amdgcn_sched_barrier(0)
; template <class Epi, class Sched, bool ALIGN_EPI = false, bool SP2 = false>
; __device__ __forceinline__ void gemm_phase(PG8_LAS unsigned char* lds, const Gemm g, const Sched& S, const Epi& E) {
;     ...
;             PG8_WAIT_V(8); PG8_WAIT_L(0); PG8_BAR; PG8_MMA(1, 0, At, B0); PG8_MMA(1, 1, At, B1); PG8_BAR; PG8_SCHED;
;             PG8_LDB(B0, 1, 0); PG8_LDB(B1, 1, 1); PG8_SCHED; PG8_LDA(At, 1, 0); PG8_STAGE(PG8_SA(0, 1), a2 + hstep, voffA);
;             PG8_WAIT_V(8); PG8_WAIT_L(0); PG8_BAR; PG8_MMA(0, 0, At, B0); PG8_MMA(0, 1, At, B1); PG8_BAR; PG8_SCHED;
	v_mfma_f32_16x16x32_bf16 v[62:65], v[152:155], v[194:197], 0
	v_mfma_f32_16x16x32_bf16 v[50:53], v[160:163], v[210:213], 0
	v_mfma_f32_16x16x32_bf16 v[46:49], v[152:155], v[218:221], 0
	v_mfma_f32_16x16x32_bf16 v[34:37], v[160:163], v[240:243], 0
	v_mfma_f32_16x16x32_bf16 v[54:57], v[152:155], v[210:213], 0
	v_mfma_f32_16x16x32_bf16 v[58:61], v[160:163], v[194:197], 0
	v_mfma_f32_16x16x32_bf16 v[38:41], v[152:155], v[240:243], 0
	v_mfma_f32_16x16x32_bf16 v[42:45], v[160:163], v[218:221], 0
	v_mfma_f32_16x16x32_bf16 v[62:65], v[156:159], v[206:209], v[62:65]
	v_mfma_f32_16x16x32_bf16 v[50:53], v[164:167], v[214:217], v[50:53]
	v_mfma_f32_16x16x32_bf16 v[46:49], v[156:159], v[236:239], v[46:49]
	v_mfma_f32_16x16x32_bf16 v[34:37], v[164:167], v[244:247], v[34:37]
	v_mfma_f32_16x16x32_bf16 v[54:57], v[156:159], v[214:217], v[54:57]
	v_mfma_f32_16x16x32_bf16 v[58:61], v[164:167], v[206:209], v[58:61]
	v_mfma_f32_16x16x32_bf16 v[38:41], v[156:159], v[244:247], v[38:41]
	v_mfma_f32_16x16x32_bf16 v[42:45], v[164:167], v[236:239], v[42:45]
	v_mfma_f32_16x16x32_bf16 v[30:33], v[168:171], v[194:197], 0
	v_mfma_f32_16x16x32_bf16 v[18:21], v[176:179], v[210:213], 0
	v_mfma_f32_16x16x32_bf16 v[14:17], v[168:171], v[218:221], 0
	v_mfma_f32_16x16x32_bf16 v[2:5], v[176:179], v[240:243], 0
	v_mfma_f32_16x16x32_bf16 v[22:25], v[168:171], v[210:213], 0
	v_mfma_f32_16x16x32_bf16 v[26:29], v[176:179], v[194:197], 0
	v_mfma_f32_16x16x32_bf16 v[6:9], v[168:171], v[240:243], 0
	v_mfma_f32_16x16x32_bf16 v[10:13], v[176:179], v[218:221], 0
	v_mfma_f32_16x16x32_bf16 v[30:33], v[172:175], v[206:209], v[30:33]
	v_mfma_f32_16x16x32_bf16 v[18:21], v[180:183], v[214:217], v[18:21]
	v_mfma_f32_16x16x32_bf16 v[14:17], v[172:175], v[236:239], v[14:17]
	v_mfma_f32_16x16x32_bf16 v[2:5], v[180:183], v[244:247], v[2:5]
	v_mfma_f32_16x16x32_bf16 v[22:25], v[172:175], v[214:217], v[22:25]
	v_mfma_f32_16x16x32_bf16 v[26:29], v[180:183], v[206:209], v[26:29]
	v_mfma_f32_16x16x32_bf16 v[6:9], v[172:175], v[244:247], v[6:9]
	v_mfma_f32_16x16x32_bf16 v[10:13], v[180:183], v[236:239], v[10:13]
	s_barrier
	s_add_i32 s9, 0, 0x18000
	s_add_i32 s12, 0, 0x1c000
	ds_read_b128 v[152:155], v198
	ds_read_b128 v[156:159], v198 offset:1024
	ds_read_b128 v[160:163], v198 offset:2048
	ds_read_b128 v[164:167], v198 offset:3072
	ds_read_b128 v[168:171], v199
	ds_read_b128 v[172:175], v199 offset:1024
	ds_read_b128 v[176:179], v199 offset:2048
	ds_read_b128 v[180:183], v199 offset:3072
	s_add_u32 s10, s92, 0x80000
	s_addc_u32 s11, s93, 0
	s_mov_b32 m0, s74
	ds_read_b128 v[194:197], v151 offset:32768
	ds_read_b128 v[206:209], v151 offset:33792
	ds_read_b128 v[210:213], v151 offset:34816
	ds_read_b128 v[214:217], v151 offset:35840
	ds_read_b128 v[218:221], v151 offset:36864
	ds_read_b128 v[236:239], v151 offset:37888
	ds_read_b128 v[240:243], v151 offset:38912
	ds_read_b128 v[244:247], v151 offset:39936
	global_load_lds_dwordx4 v190, s[10:11]
	s_mov_b32 m0, s75
	s_nop 0
	global_load_lds_dwordx4 v132, s[10:11]
	s_waitcnt vmcnt(8)
	s_waitcnt lgkmcnt(0)
	s_barrier
	v_mfma_f32_16x16x32_bf16 v[126:129], v[152:155], v[194:197], v[126:129]
	v_mfma_f32_16x16x32_bf16 v[114:117], v[160:163], v[210:213], v[114:117]
	v_mfma_f32_16x16x32_bf16 v[110:113], v[152:155], v[218:221], v[110:113]
	v_mfma_f32_16x16x32_bf16 v[98:101], v[160:163], v[240:243], v[98:101]
	v_mfma_f32_16x16x32_bf16 v[118:121], v[152:155], v[210:213], v[118:121]
	v_mfma_f32_16x16x32_bf16 v[122:125], v[160:163], v[194:197], v[122:125]
	v_mfma_f32_16x16x32_bf16 v[102:105], v[152:155], v[240:243], v[102:105]
	v_mfma_f32_16x16x32_bf16 v[106:109], v[160:163], v[218:221], v[106:109]
	v_mfma_f32_16x16x32_bf16 v[126:129], v[156:159], v[206:209], v[126:129]
	v_mfma_f32_16x16x32_bf16 v[114:117], v[164:167], v[214:217], v[114:117]
	v_mfma_f32_16x16x32_bf16 v[110:113], v[156:159], v[236:239], v[110:113]
	v_mfma_f32_16x16x32_bf16 v[98:101], v[164:167], v[244:247], v[98:101]
	v_mfma_f32_16x16x32_bf16 v[118:121], v[156:159], v[214:217], v[118:121]
	v_mfma_f32_16x16x32_bf16 v[122:125], v[164:167], v[206:209], v[122:125]
	v_mfma_f32_16x16x32_bf16 v[102:105], v[156:159], v[244:247], v[102:105]
	v_mfma_f32_16x16x32_bf16 v[106:109], v[164:167], v[236:239], v[106:109]
	v_mfma_f32_16x16x32_bf16 v[94:97], v[168:171], v[194:197], v[94:97]
	v_mfma_f32_16x16x32_bf16 v[82:85], v[176:179], v[210:213], v[82:85]
	v_mfma_f32_16x16x32_bf16 v[78:81], v[168:171], v[218:221], v[78:81]
	v_mfma_f32_16x16x32_bf16 v[66:69], v[176:179], v[240:243], v[66:69]
	v_mfma_f32_16x16x32_bf16 v[86:89], v[168:171], v[210:213], v[86:89]
	v_mfma_f32_16x16x32_bf16 v[90:93], v[176:179], v[194:197], v[90:93]
	v_mfma_f32_16x16x32_bf16 v[70:73], v[168:171], v[240:243], v[70:73]
	v_mfma_f32_16x16x32_bf16 v[74:77], v[176:179], v[218:221], v[74:77]
	v_mfma_f32_16x16x32_bf16 v[94:97], v[172:175], v[206:209], v[94:97]
	v_mfma_f32_16x16x32_bf16 v[82:85], v[180:183], v[214:217], v[82:85]
	v_mfma_f32_16x16x32_bf16 v[78:81], v[172:175], v[236:239], v[78:81]
	v_mfma_f32_16x16x32_bf16 v[66:69], v[180:183], v[244:247], v[66:69]
	v_mfma_f32_16x16x32_bf16 v[86:89], v[172:175], v[214:217], v[86:89]
	v_mfma_f32_16x16x32_bf16 v[90:93], v[180:183], v[206:209], v[90:93]
	v_mfma_f32_16x16x32_bf16 v[70:73], v[172:175], v[244:247], v[70:73]
	v_mfma_f32_16x16x32_bf16 v[74:77], v[180:183], v[236:239], v[74:77]
	s_barrier
; #define PG8_STAGE(bufoff, gbase, voff) do { _Pragma("unroll") for (int _i = 0; _i < 2; ++_i) \
;         __builtin_amdgcn_global_load_lds((const unsigned*)((const char*)(gbase) + (voff)[_i]), (PG8_LAS unsigned*)(lds + (bufoff) + ldsw + _i * 8192), 16, 0, 0); } while (0)
; #define PG8_LDA(dst, b, h) do { _Pragma("unroll") for (int m = 0; m < 4; ++m) _Pragma("unroll") for (int k = 0; k < 2; ++k) dst[m][k] = *(const PG8_LAS bf16x8*)(lds + PG8_SA(b, h) + aoff + m * 2048 + k * 1024); } while (0)
; #define PG8_LDB(dst, b, h) do { _Pragma("unroll") for (int n = 0; n < 2; ++n) _Pragma("unroll") for (int k = 0; k < 2; ++k) dst[n][k] = *(const PG8_LAS bf16x8*)(lds + PG8_SB(b, h) + boff + n * 2048 + k * 1024); } while (0)
; template <class Epi, class Sched, bool ALIGN_EPI = false, bool SP2 = false>
; __device__ __forceinline__ void gemm_phase(PG8_LAS unsigned char* lds, const Gemm g, const Sched& S, const Epi& E) {
;     ...
;         for (int t = 0; t < nt; t += 2) {
;             const bool last = (t == nt - 2);
;             const char* a1 = cA + (size_t)(t + 1) * kstep;
;             const char* a2 = last ? nA : cA + (size_t)(t + 2) * kstep; const char* b2 = last ? nB : cB + (size_t)(t + 2) * kstep;
;             const char* a3 = a2 + kstep; const char* b3 = b2 + kstep;
;             if (last && has_next) S.a_ready(nxt);
;             if constexpr (SP2) {
;             PG8_LDB(B0, 0, 0); PG8_LDB(B1, 0, 1); PG8_SCHED; PG8_LDA(At, 0, 0); PG8_STAGE(PG8_SA(1, 1), a1 + hstep, voffA);
;             PG8_WAIT_V(8); PG8_WAIT_L(0); PG8_BAR; PG8_MMA(0, 0, At, B0); PG8_MMA(0, 1, At, B1); PG8_BAR; PG8_SCHED;
;             PG8_LDA(At, 0, 1); PG8_STAGE(PG8_SB(0, 0), b2, voffB); PG8_STAGE(PG8_SB(0, 1), b2 + hstepB, voffB); PG8_STAGE(PG8_SA(0, 0), a2, voffA);
;             PG8_WAIT_V(8); PG8_WAIT_L(0); PG8_BAR; PG8_MMA(1, 0, At, B0); PG8_MMA(1, 1, At, B1); PG8_BAR; PG8_SCHED;
;             PG8_LDB(B0, 1, 0); PG8_LDB(B1, 1, 1); PG8_SCHED; PG8_LDA(At, 1, 0); PG8_STAGE(PG8_SA(0, 1), a2 + hstep, voffA);
;             PG8_WAIT_V(8); PG8_WAIT_L(0); PG8_BAR; PG8_MMA(0, 0, At, B0); PG8_MMA(0, 1, At, B1); PG8_BAR; PG8_SCHED;
;             PG8_LDA(At, 1, 1); PG8_STAGE(PG8_SB(1, 0), b3, voffB); PG8_STAGE(PG8_SB(1, 1), b3 + hstepB, voffB); PG8_STAGE(PG8_SA(1, 0), a3, voffA);
;             PG8_WAIT_V(8); PG8_WAIT_L(0); PG8_BAR; PG8_MMA(1, 0, At, B0); PG8_MMA(1, 1, At, B1); PG8_BAR; PG8_SCHED;
	s_add_i32 s9, s9, s42
	s_mov_b32 m0, s9
	ds_read_b128 v[194:197], v151 offset:49152
	ds_read_b128 v[206:209], v151 offset:50176
	ds_read_b128 v[210:213], v151 offset:51200
	ds_read_b128 v[214:217], v151 offset:52224
	ds_read_b128 v[218:221], v151 offset:53248
	ds_read_b128 v[236:239], v151 offset:54272
	ds_read_b128 v[240:243], v151 offset:55296
	ds_read_b128 v[244:247], v151 offset:56320
	s_add_u32 s100, s84, s60
	s_addc_u32 s101, s85, s61
	global_load_lds_dwordx4 v130, s[100:101]
	s_add_i32 m0, s9, 0x2000
	s_add_u32 s10, s84, 0x20080
	s_addc_u32 s11, s85, 0
	s_add_i32 s9, s12, s42
	global_load_lds_dwordx4 v134, s[100:101]
	s_mov_b32 m0, s9
	s_nop 0
	global_load_lds_dwordx4 v130, s[10:11]
	s_add_i32 m0, s9, 0x2000
	s_nop 0
	global_load_lds_dwordx4 v134, s[10:11]
	s_mov_b32 m0, s82
	s_add_u32 s100, s92, s60
	s_addc_u32 s101, s93, s61
	global_load_lds_dwordx4 v190, s[100:101]
	s_mov_b32 m0, s86
	s_nop 0
	global_load_lds_dwordx4 v132, s[100:101]
	s_waitcnt vmcnt(8)
	s_waitcnt lgkmcnt(0)
	s_barrier
	v_mfma_f32_16x16x32_bf16 v[62:65], v[152:155], v[194:197], v[62:65]
	v_mfma_f32_16x16x32_bf16 v[50:53], v[160:163], v[210:213], v[50:53]
	v_mfma_f32_16x16x32_bf16 v[46:49], v[152:155], v[218:221], v[46:49]
	v_mfma_f32_16x16x32_bf16 v[34:37], v[160:163], v[240:243], v[34:37]
	v_mfma_f32_16x16x32_bf16 v[54:57], v[152:155], v[210:213], v[54:57]
	v_mfma_f32_16x16x32_bf16 v[58:61], v[160:163], v[194:197], v[58:61]
	v_mfma_f32_16x16x32_bf16 v[38:41], v[152:155], v[240:243], v[38:41]
	v_mfma_f32_16x16x32_bf16 v[42:45], v[160:163], v[218:221], v[42:45]
	v_mfma_f32_16x16x32_bf16 v[62:65], v[156:159], v[206:209], v[62:65]
	v_mfma_f32_16x16x32_bf16 v[50:53], v[164:167], v[214:217], v[50:53]
	v_mfma_f32_16x16x32_bf16 v[46:49], v[156:159], v[236:239], v[46:49]
	v_mfma_f32_16x16x32_bf16 v[34:37], v[164:167], v[244:247], v[34:37]
	v_mfma_f32_16x16x32_bf16 v[54:57], v[156:159], v[214:217], v[54:57]
	v_mfma_f32_16x16x32_bf16 v[58:61], v[164:167], v[206:209], v[58:61]
	v_mfma_f32_16x16x32_bf16 v[38:41], v[156:159], v[244:247], v[38:41]
	v_mfma_f32_16x16x32_bf16 v[42:45], v[164:167], v[236:239], v[42:45]
	v_mfma_f32_16x16x32_bf16 v[30:33], v[168:171], v[194:197], v[30:33]
	v_mfma_f32_16x16x32_bf16 v[18:21], v[176:179], v[210:213], v[18:21]
	v_mfma_f32_16x16x32_bf16 v[14:17], v[168:171], v[218:221], v[14:17]
	v_mfma_f32_16x16x32_bf16 v[2:5], v[176:179], v[240:243], v[2:5]
	v_mfma_f32_16x16x32_bf16 v[22:25], v[168:171], v[210:213], v[22:25]
	v_mfma_f32_16x16x32_bf16 v[26:29], v[176:179], v[194:197], v[26:29]
	v_mfma_f32_16x16x32_bf16 v[6:9], v[168:171], v[240:243], v[6:9]
	v_mfma_f32_16x16x32_bf16 v[10:13], v[176:179], v[218:221], v[10:13]
	v_mfma_f32_16x16x32_bf16 v[30:33], v[172:175], v[206:209], v[30:33]
	v_mfma_f32_16x16x32_bf16 v[18:21], v[180:183], v[214:217], v[18:21]
	v_mfma_f32_16x16x32_bf16 v[14:17], v[172:175], v[236:239], v[14:17]
	v_mfma_f32_16x16x32_bf16 v[2:5], v[180:183], v[244:247], v[2:5]
	v_mfma_f32_16x16x32_bf16 v[22:25], v[172:175], v[214:217], v[22:25]
	v_mfma_f32_16x16x32_bf16 v[26:29], v[180:183], v[206:209], v[26:29]
	v_mfma_f32_16x16x32_bf16 v[6:9], v[172:175], v[244:247], v[6:9]
	v_mfma_f32_16x16x32_bf16 v[10:13], v[180:183], v[236:239], v[10:13]
	s_barrier
	s_add_i32 s8, s8, 2
	s_add_u32 s80, s80, 0x100
	s_addc_u32 s81, s81, 0
	s_cmp_gt_u32 s8, 29
.LBB0_1233:
	s_add_u32 s9, s68, s80
	s_addc_u32 s10, s69, s81
	s_add_u32 s9, s9, 0x100
	s_addc_u32 s10, s10, 0
	s_add_u32 s100, s9, 0x7ff80
	s_addc_u32 s101, s10, 0
	s_add_u32 s11, s36, s80
	s_addc_u32 s12, s37, s81
	s_add_i32 s13, 0, 0x10000
	s_cmpk_eq_i32 s80, 0xf00
	s_cselect_b32 s93, s4, s10
	s_cselect_b32 s92, s5, s9
	s_cselect_b32 s85, s6, s12
	s_cselect_b32 s84, s7, s11
	s_add_i32 s9, 0, 0x14000
	ds_read_b128 v[152:155], v186
	ds_read_b128 v[156:159], v186 offset:1024
	ds_read_b128 v[160:163], v186 offset:2048
	ds_read_b128 v[164:167], v186 offset:3072
	ds_read_b128 v[168:171], v187
	ds_read_b128 v[172:175], v187 offset:1024
	ds_read_b128 v[176:179], v187 offset:2048
	ds_read_b128 v[180:183], v187 offset:3072
	s_add_i32 m0, s51, 0xc000
	ds_read_b128 v[206:209], v151
	ds_read_b128 v[210:213], v151 offset:1024
	ds_read_b128 v[214:217], v151 offset:2048
	ds_read_b128 v[218:221], v151 offset:3072
	ds_read_b128 v[236:239], v151 offset:4096
	ds_read_b128 v[240:243], v151 offset:5120
	ds_read_b128 v[244:247], v151 offset:6144
	ds_read_b128 v[194:197], v151 offset:7168
	global_load_lds_dwordx4 v136, s[100:101]
	s_add_i32 m0, s51, 0xe000
	s_nop 0
	global_load_lds_dwordx4 v138, s[100:101]
	s_waitcnt vmcnt(8)
	s_waitcnt lgkmcnt(0)
	s_barrier
; #define PG8_STAGE(bufoff, gbase, voff) do { _Pragma("unroll") for (int _i = 0; _i < 2; ++_i) \
;         __builtin_amdgcn_global_load_lds((const unsigned*)((const char*)(gbase) + (voff)[_i]), (PG8_LAS unsigned*)(lds + (bufoff) + ldsw + _i * 8192), 16, 0, 0); } while (0)
; #define PG8_LDA(dst, b, h) do { _Pragma("unroll") for (int m = 0; m < 4; ++m) _Pragma("unroll") for (int k = 0; k < 2; ++k) dst[m][k] = *(const PG8_LAS bf16x8*)(lds + PG8_SA(b, h) + aoff + m * 2048 + k * 1024); } while (0)
; #define PG8_MMA(ai, bj, At, Bt) do { __builtin_amdgcn_s_setprio(1); _Pragma("unroll") for (int m = 0; m < 4; ++m) _Pragma("unroll") for (int n = 0; n < 2; ++n) _Pragma("unroll") for (int k = 0; k < 2; ++k) \
;         acc[ai][bj][m][n] = __builtin_amdgcn_mfma_f32_16x16x32_bf16(Bt[n][k], At[m][k], acc[ai][bj][m][n], 0, 0, 0); __builtin_amdgcn_s_setprio(0); } while (0)
; #define PG8_WAIT_V(n) asm volatile("s_waitcnt vmcnt(" #n ")" ::: "memory")
; #define PG8_WAIT_L(n) asm volatile("s_waitcnt lgkmcnt(" #n ")" ::: "memory")
; #define PG8_BAR __builtin_amdgcn_s_barrier()
; #define PG8_SCHED __builtin_amdgcn_sched_barrier(0)
; template <class Epi, class Sched, bool ALIGN_EPI = false, bool SP2 = false>
; __device__ __forceinline__ void gemm_phase(PG8_LAS unsigned char* lds, const Gemm g, const Sched& S, const Epi& E) {
;     ...
;             PG8_WAIT_V(8); PG8_WAIT_L(0); PG8_BAR; PG8_MMA(0, 0, At, B0); PG8_MMA(0, 1, At, B1); PG8_BAR; PG8_SCHED;
;             PG8_LDA(At, 0, 1); PG8_STAGE(PG8_SB(0, 0), b2, voffB); PG8_STAGE(PG8_SB(0, 1), b2 + hstepB, voffB); PG8_STAGE(PG8_SA(0, 0), a2, voffA);
;             PG8_WAIT_V(8); PG8_WAIT_L(0); PG8_BAR; PG8_MMA(1, 0, At, B0); PG8_MMA(1, 1, At, B1); PG8_BAR; PG8_SCHED;
	v_mfma_f32_16x16x32_bf16 v[126:129], v[152:155], v[206:209], v[126:129]
	v_mfma_f32_16x16x32_bf16 v[114:117], v[160:163], v[214:217], v[114:117]
	v_mfma_f32_16x16x32_bf16 v[110:113], v[152:155], v[236:239], v[110:113]
	v_mfma_f32_16x16x32_bf16 v[98:101], v[160:163], v[244:247], v[98:101]
	v_mfma_f32_16x16x32_bf16 v[118:121], v[152:155], v[214:217], v[118:121]
	v_mfma_f32_16x16x32_bf16 v[122:125], v[160:163], v[206:209], v[122:125]
	v_mfma_f32_16x16x32_bf16 v[102:105], v[152:155], v[244:247], v[102:105]
	v_mfma_f32_16x16x32_bf16 v[106:109], v[160:163], v[236:239], v[106:109]
	v_mfma_f32_16x16x32_bf16 v[126:129], v[156:159], v[210:213], v[126:129]
	v_mfma_f32_16x16x32_bf16 v[114:117], v[164:167], v[218:221], v[114:117]
	v_mfma_f32_16x16x32_bf16 v[110:113], v[156:159], v[240:243], v[110:113]
	v_mfma_f32_16x16x32_bf16 v[98:101], v[164:167], v[194:197], v[98:101]
	v_mfma_f32_16x16x32_bf16 v[118:121], v[156:159], v[218:221], v[118:121]
	v_mfma_f32_16x16x32_bf16 v[122:125], v[164:167], v[210:213], v[122:125]
	v_mfma_f32_16x16x32_bf16 v[102:105], v[156:159], v[194:197], v[102:105]
	v_mfma_f32_16x16x32_bf16 v[106:109], v[164:167], v[240:243], v[106:109]
	v_mfma_f32_16x16x32_bf16 v[94:97], v[168:171], v[206:209], v[94:97]
	v_mfma_f32_16x16x32_bf16 v[82:85], v[176:179], v[214:217], v[82:85]
	v_mfma_f32_16x16x32_bf16 v[78:81], v[168:171], v[236:239], v[78:81]
	v_mfma_f32_16x16x32_bf16 v[66:69], v[176:179], v[244:247], v[66:69]
	v_mfma_f32_16x16x32_bf16 v[86:89], v[168:171], v[214:217], v[86:89]
	v_mfma_f32_16x16x32_bf16 v[90:93], v[176:179], v[206:209], v[90:93]
	v_mfma_f32_16x16x32_bf16 v[70:73], v[168:171], v[244:247], v[70:73]
	v_mfma_f32_16x16x32_bf16 v[74:77], v[176:179], v[236:239], v[74:77]
	v_mfma_f32_16x16x32_bf16 v[94:97], v[172:175], v[210:213], v[94:97]
	v_mfma_f32_16x16x32_bf16 v[82:85], v[180:183], v[218:221], v[82:85]
	v_mfma_f32_16x16x32_bf16 v[78:81], v[172:175], v[240:243], v[78:81]
	v_mfma_f32_16x16x32_bf16 v[66:69], v[180:183], v[194:197], v[66:69]
	v_mfma_f32_16x16x32_bf16 v[86:89], v[172:175], v[218:221], v[86:89]
	v_mfma_f32_16x16x32_bf16 v[90:93], v[180:183], v[210:213], v[90:93]
	v_mfma_f32_16x16x32_bf16 v[70:73], v[172:175], v[194:197], v[70:73]
	v_mfma_f32_16x16x32_bf16 v[74:77], v[180:183], v[240:243], v[74:77]
	s_barrier
	s_add_i32 s10, s13, s42
	s_mov_b32 m0, s10
	ds_read_b128 v[194:197], v151 offset:16384
	ds_read_b128 v[206:209], v151 offset:17408
	ds_read_b128 v[210:213], v151 offset:18432
	ds_read_b128 v[214:217], v151 offset:19456
	ds_read_b128 v[218:221], v151 offset:20480
	ds_read_b128 v[236:239], v151 offset:21504
	ds_read_b128 v[240:243], v151 offset:22528
	ds_read_b128 v[244:247], v151 offset:23552
	global_load_lds_dwordx4 v130, s[84:85]
	s_add_i32 m0, s10, 0x2000
	s_add_u32 s10, s84, 0x20000
	s_addc_u32 s11, s85, 0
	s_add_i32 s9, s9, s42
	global_load_lds_dwordx4 v134, s[84:85]
	s_mov_b32 m0, s9
	s_nop 0
	global_load_lds_dwordx4 v130, s[10:11]
	s_add_i32 m0, s9, 0x2000
	s_nop 0
	global_load_lds_dwordx4 v134, s[10:11]
	s_mov_b32 m0, s51
	s_nop 0
	global_load_lds_dwordx4 v190, s[92:93]
	s_mov_b32 m0, s67
	s_nop 0
	global_load_lds_dwordx4 v132, s[92:93]
	s_waitcnt vmcnt(8)
	s_waitcnt lgkmcnt(0)
	s_barrier
	v_mfma_f32_16x16x32_bf16 v[62:65], v[152:155], v[194:197], v[62:65]
	v_mfma_f32_16x16x32_bf16 v[50:53], v[160:163], v[210:213], v[50:53]
	v_mfma_f32_16x16x32_bf16 v[46:49], v[152:155], v[218:221], v[46:49]
	v_mfma_f32_16x16x32_bf16 v[34:37], v[160:163], v[240:243], v[34:37]
	v_mfma_f32_16x16x32_bf16 v[54:57], v[152:155], v[210:213], v[54:57]
	v_mfma_f32_16x16x32_bf16 v[58:61], v[160:163], v[194:197], v[58:61]
	v_mfma_f32_16x16x32_bf16 v[38:41], v[152:155], v[240:243], v[38:41]
	v_mfma_f32_16x16x32_bf16 v[42:45], v[160:163], v[218:221], v[42:45]
	v_mfma_f32_16x16x32_bf16 v[62:65], v[156:159], v[206:209], v[62:65]
	v_mfma_f32_16x16x32_bf16 v[50:53], v[164:167], v[214:217], v[50:53]
	v_mfma_f32_16x16x32_bf16 v[46:49], v[156:159], v[236:239], v[46:49]
	v_mfma_f32_16x16x32_bf16 v[34:37], v[164:167], v[244:247], v[34:37]
	v_mfma_f32_16x16x32_bf16 v[54:57], v[156:159], v[214:217], v[54:57]
	v_mfma_f32_16x16x32_bf16 v[58:61], v[164:167], v[206:209], v[58:61]
	v_mfma_f32_16x16x32_bf16 v[38:41], v[156:159], v[244:247], v[38:41]
	v_mfma_f32_16x16x32_bf16 v[42:45], v[164:167], v[236:239], v[42:45]
	v_mfma_f32_16x16x32_bf16 v[30:33], v[168:171], v[194:197], v[30:33]
	v_mfma_f32_16x16x32_bf16 v[18:21], v[176:179], v[210:213], v[18:21]
	v_mfma_f32_16x16x32_bf16 v[14:17], v[168:171], v[218:221], v[14:17]
	v_mfma_f32_16x16x32_bf16 v[2:5], v[176:179], v[240:243], v[2:5]
	v_mfma_f32_16x16x32_bf16 v[22:25], v[168:171], v[210:213], v[22:25]
	v_mfma_f32_16x16x32_bf16 v[26:29], v[176:179], v[194:197], v[26:29]
	v_mfma_f32_16x16x32_bf16 v[6:9], v[168:171], v[240:243], v[6:9]
	v_mfma_f32_16x16x32_bf16 v[10:13], v[176:179], v[218:221], v[10:13]
	v_mfma_f32_16x16x32_bf16 v[30:33], v[172:175], v[206:209], v[30:33]
	v_mfma_f32_16x16x32_bf16 v[18:21], v[180:183], v[214:217], v[18:21]
	v_mfma_f32_16x16x32_bf16 v[14:17], v[172:175], v[236:239], v[14:17]
	v_mfma_f32_16x16x32_bf16 v[2:5], v[180:183], v[244:247], v[2:5]
	v_mfma_f32_16x16x32_bf16 v[22:25], v[172:175], v[214:217], v[22:25]
	v_mfma_f32_16x16x32_bf16 v[26:29], v[180:183], v[206:209], v[26:29]
	v_mfma_f32_16x16x32_bf16 v[6:9], v[172:175], v[244:247], v[6:9]
	v_mfma_f32_16x16x32_bf16 v[10:13], v[180:183], v[236:239], v[10:13]
	s_barrier
; #define PG8_STAGE(bufoff, gbase, voff) do { _Pragma("unroll") for (int _i = 0; _i < 2; ++_i) \
;         __builtin_amdgcn_global_load_lds((const unsigned*)((const char*)(gbase) + (voff)[_i]), (PG8_LAS unsigned*)(lds + (bufoff) + ldsw + _i * 8192), 16, 0, 0); } while (0)
; #define PG8_LDA(dst, b, h) do { _Pragma("unroll") for (int m = 0; m < 4; ++m) _Pragma("unroll") for (int k = 0; k < 2; ++k) dst[m][k] = *(const PG8_LAS bf16x8*)(lds + PG8_SA(b, h) + aoff + m * 2048 + k * 1024); } while (0)
; #define PG8_LDB(dst, b, h) do { _Pragma("unroll") for (int n = 0; n < 2; ++n) _Pragma("unroll") for (int k = 0; k < 2; ++k) dst[n][k] = *(const PG8_LAS bf16x8*)(lds + PG8_SB(b, h) + boff + n * 2048 + k * 1024); } while (0)
; template <class Epi, class Sched, bool ALIGN_EPI = false, bool SP2 = false>
; __device__ __forceinline__ void gemm_phase(PG8_LAS unsigned char* lds, const Gemm g, const Sched& S, const Epi& E) {
;     ...
;         for (int t = 0; t < nt; t += 2) {
;             const bool last = (t == nt - 2);
;             const char* a1 = cA + (size_t)(t + 1) * kstep;
;             const char* a2 = last ? nA : cA + (size_t)(t + 2) * kstep; const char* b2 = last ? nB : cB + (size_t)(t + 2) * kstep;
;             const char* a3 = a2 + kstep; const char* b3 = b2 + kstep;
;             if (last && has_next) S.a_ready(nxt);
;             if constexpr (SP2) {
;             PG8_LDB(B0, 0, 0); PG8_LDB(B1, 0, 1); PG8_SCHED; PG8_LDA(At, 0, 0); PG8_STAGE(PG8_SA(1, 1), a1 + hstep, voffA);
;             PG8_WAIT_V(8); PG8_WAIT_L(0); PG8_BAR; PG8_MMA(0, 0, At, B0); PG8_MMA(0, 1, At, B1); PG8_BAR; PG8_SCHED;
;             PG8_LDA(At, 0, 1); PG8_STAGE(PG8_SB(0, 0), b2, voffB); PG8_STAGE(PG8_SB(0, 1), b2 + hstepB, voffB); PG8_STAGE(PG8_SA(0, 0), a2, voffA);
;             PG8_WAIT_V(8); PG8_WAIT_L(0); PG8_BAR; PG8_MMA(1, 0, At, B0); PG8_MMA(1, 1, At, B1); PG8_BAR; PG8_SCHED;
;             PG8_LDB(B0, 1, 0); PG8_LDB(B1, 1, 1); PG8_SCHED; PG8_LDA(At, 1, 0); PG8_STAGE(PG8_SA(0, 1), a2 + hstep, voffA);
;             PG8_WAIT_V(8); PG8_WAIT_L(0); PG8_BAR; PG8_MMA(0, 0, At, B0); PG8_MMA(0, 1, At, B1); PG8_BAR; PG8_SCHED;
;             PG8_LDA(At, 1, 1); PG8_STAGE(PG8_SB(1, 0), b3, voffB); PG8_STAGE(PG8_SB(1, 1), b3 + hstepB, voffB); PG8_STAGE(PG8_SA(1, 0), a3, voffA);
;             PG8_WAIT_V(8); PG8_WAIT_L(0); PG8_BAR; PG8_MMA(1, 0, At, B0); PG8_MMA(1, 1, At, B1); PG8_BAR; PG8_SCHED;
	s_add_i32 s9, 0, 0x18000
	s_add_i32 s12, 0, 0x1c000
	ds_read_b128 v[152:155], v198
	ds_read_b128 v[156:159], v198 offset:1024
	ds_read_b128 v[160:163], v198 offset:2048
	ds_read_b128 v[164:167], v198 offset:3072
	ds_read_b128 v[168:171], v199
	ds_read_b128 v[172:175], v199 offset:1024
	ds_read_b128 v[176:179], v199 offset:2048
	ds_read_b128 v[180:183], v199 offset:3072
	s_add_u32 s10, s92, 0x80000
	s_addc_u32 s11, s93, 0
	s_mov_b32 m0, s74
	ds_read_b128 v[194:197], v151 offset:32768
	ds_read_b128 v[206:209], v151 offset:33792
	ds_read_b128 v[210:213], v151 offset:34816
	ds_read_b128 v[214:217], v151 offset:35840
	ds_read_b128 v[218:221], v151 offset:36864
	ds_read_b128 v[236:239], v151 offset:37888
	ds_read_b128 v[240:243], v151 offset:38912
	ds_read_b128 v[244:247], v151 offset:39936
	global_load_lds_dwordx4 v190, s[10:11]
	s_mov_b32 m0, s75
	s_nop 0
	global_load_lds_dwordx4 v132, s[10:11]
	s_waitcnt vmcnt(8)
	s_waitcnt lgkmcnt(0)
	s_barrier
	v_mfma_f32_16x16x32_bf16 v[126:129], v[152:155], v[194:197], v[126:129]
	v_mfma_f32_16x16x32_bf16 v[114:117], v[160:163], v[210:213], v[114:117]
	v_mfma_f32_16x16x32_bf16 v[110:113], v[152:155], v[218:221], v[110:113]
	v_mfma_f32_16x16x32_bf16 v[98:101], v[160:163], v[240:243], v[98:101]
	v_mfma_f32_16x16x32_bf16 v[118:121], v[152:155], v[210:213], v[118:121]
	v_mfma_f32_16x16x32_bf16 v[122:125], v[160:163], v[194:197], v[122:125]
	v_mfma_f32_16x16x32_bf16 v[102:105], v[152:155], v[240:243], v[102:105]
	v_mfma_f32_16x16x32_bf16 v[106:109], v[160:163], v[218:221], v[106:109]
	v_mfma_f32_16x16x32_bf16 v[126:129], v[156:159], v[206:209], v[126:129]
	v_mfma_f32_16x16x32_bf16 v[114:117], v[164:167], v[214:217], v[114:117]
	v_mfma_f32_16x16x32_bf16 v[110:113], v[156:159], v[236:239], v[110:113]
	v_mfma_f32_16x16x32_bf16 v[98:101], v[164:167], v[244:247], v[98:101]
	v_mfma_f32_16x16x32_bf16 v[118:121], v[156:159], v[214:217], v[118:121]
	v_mfma_f32_16x16x32_bf16 v[122:125], v[164:167], v[206:209], v[122:125]
	v_mfma_f32_16x16x32_bf16 v[102:105], v[156:159], v[244:247], v[102:105]
	v_mfma_f32_16x16x32_bf16 v[106:109], v[164:167], v[236:239], v[106:109]
	v_mfma_f32_16x16x32_bf16 v[94:97], v[168:171], v[194:197], v[94:97]
	v_mfma_f32_16x16x32_bf16 v[82:85], v[176:179], v[210:213], v[82:85]
	v_mfma_f32_16x16x32_bf16 v[78:81], v[168:171], v[218:221], v[78:81]
	v_mfma_f32_16x16x32_bf16 v[66:69], v[176:179], v[240:243], v[66:69]
	v_mfma_f32_16x16x32_bf16 v[86:89], v[168:171], v[210:213], v[86:89]
	v_mfma_f32_16x16x32_bf16 v[90:93], v[176:179], v[194:197], v[90:93]
	v_mfma_f32_16x16x32_bf16 v[70:73], v[168:171], v[240:243], v[70:73]
	v_mfma_f32_16x16x32_bf16 v[74:77], v[176:179], v[218:221], v[74:77]
	v_mfma_f32_16x16x32_bf16 v[94:97], v[172:175], v[206:209], v[94:97]
	v_mfma_f32_16x16x32_bf16 v[82:85], v[180:183], v[214:217], v[82:85]
	v_mfma_f32_16x16x32_bf16 v[78:81], v[172:175], v[236:239], v[78:81]
	v_mfma_f32_16x16x32_bf16 v[66:69], v[180:183], v[244:247], v[66:69]
	v_mfma_f32_16x16x32_bf16 v[86:89], v[172:175], v[214:217], v[86:89]
	v_mfma_f32_16x16x32_bf16 v[90:93], v[180:183], v[206:209], v[90:93]
	v_mfma_f32_16x16x32_bf16 v[70:73], v[172:175], v[244:247], v[70:73]
	v_mfma_f32_16x16x32_bf16 v[74:77], v[180:183], v[236:239], v[74:77]
	s_barrier
	s_add_i32 s9, s9, s42
	s_mov_b32 m0, s9
	ds_read_b128 v[194:197], v151 offset:49152
	ds_read_b128 v[206:209], v151 offset:50176
	ds_read_b128 v[210:213], v151 offset:51200
	ds_read_b128 v[214:217], v151 offset:52224
	ds_read_b128 v[218:221], v151 offset:53248
	ds_read_b128 v[236:239], v151 offset:54272
	ds_read_b128 v[240:243], v151 offset:55296
	ds_read_b128 v[244:247], v151 offset:56320
	s_add_u32 s100, s84, s60
	s_addc_u32 s101, s85, s61
	global_load_lds_dwordx4 v130, s[100:101]
	s_add_i32 m0, s9, 0x2000
	s_add_u32 s10, s84, 0x20080
	s_addc_u32 s11, s85, 0
	s_add_i32 s9, s12, s42
	global_load_lds_dwordx4 v134, s[100:101]
	s_mov_b32 m0, s9
	s_nop 0
	global_load_lds_dwordx4 v130, s[10:11]
	s_add_i32 m0, s9, 0x2000
	s_nop 0
	global_load_lds_dwordx4 v134, s[10:11]
	s_mov_b32 m0, s82
	s_add_u32 s100, s92, s60
	s_addc_u32 s101, s93, s61
	global_load_lds_dwordx4 v190, s[100:101]
	s_mov_b32 m0, s86
	s_nop 0
	global_load_lds_dwordx4 v132, s[100:101]
	s_waitcnt vmcnt(8)
	s_waitcnt lgkmcnt(0)
	s_barrier
	v_mfma_f32_16x16x32_bf16 v[62:65], v[152:155], v[194:197], v[62:65]
	v_mfma_f32_16x16x32_bf16 v[50:53], v[160:163], v[210:213], v[50:53]
	v_mfma_f32_16x16x32_bf16 v[46:49], v[152:155], v[218:221], v[46:49]
	v_mfma_f32_16x16x32_bf16 v[34:37], v[160:163], v[240:243], v[34:37]
	v_mfma_f32_16x16x32_bf16 v[54:57], v[152:155], v[210:213], v[54:57]
	v_mfma_f32_16x16x32_bf16 v[58:61], v[160:163], v[194:197], v[58:61]
	v_mfma_f32_16x16x32_bf16 v[38:41], v[152:155], v[240:243], v[38:41]
	v_mfma_f32_16x16x32_bf16 v[42:45], v[160:163], v[218:221], v[42:45]
	v_mfma_f32_16x16x32_bf16 v[62:65], v[156:159], v[206:209], v[62:65]
	v_mfma_f32_16x16x32_bf16 v[50:53], v[164:167], v[214:217], v[50:53]
	v_mfma_f32_16x16x32_bf16 v[46:49], v[156:159], v[236:239], v[46:49]
	v_mfma_f32_16x16x32_bf16 v[34:37], v[164:167], v[244:247], v[34:37]
	v_mfma_f32_16x16x32_bf16 v[54:57], v[156:159], v[214:217], v[54:57]
	v_mfma_f32_16x16x32_bf16 v[58:61], v[164:167], v[206:209], v[58:61]
	v_mfma_f32_16x16x32_bf16 v[38:41], v[156:159], v[244:247], v[38:41]
	v_mfma_f32_16x16x32_bf16 v[42:45], v[164:167], v[236:239], v[42:45]
	v_mfma_f32_16x16x32_bf16 v[30:33], v[168:171], v[194:197], v[30:33]
	v_mfma_f32_16x16x32_bf16 v[18:21], v[176:179], v[210:213], v[18:21]
	v_mfma_f32_16x16x32_bf16 v[14:17], v[168:171], v[218:221], v[14:17]
	v_mfma_f32_16x16x32_bf16 v[2:5], v[176:179], v[240:243], v[2:5]
	v_mfma_f32_16x16x32_bf16 v[22:25], v[168:171], v[210:213], v[22:25]
	v_mfma_f32_16x16x32_bf16 v[26:29], v[176:179], v[194:197], v[26:29]
	v_mfma_f32_16x16x32_bf16 v[6:9], v[168:171], v[240:243], v[6:9]
	v_mfma_f32_16x16x32_bf16 v[10:13], v[176:179], v[218:221], v[10:13]
	v_mfma_f32_16x16x32_bf16 v[30:33], v[172:175], v[206:209], v[30:33]
	v_mfma_f32_16x16x32_bf16 v[18:21], v[180:183], v[214:217], v[18:21]
	v_mfma_f32_16x16x32_bf16 v[14:17], v[172:175], v[236:239], v[14:17]
	v_mfma_f32_16x16x32_bf16 v[2:5], v[180:183], v[244:247], v[2:5]
	v_mfma_f32_16x16x32_bf16 v[22:25], v[172:175], v[214:217], v[22:25]
	v_mfma_f32_16x16x32_bf16 v[26:29], v[180:183], v[206:209], v[26:29]
	v_mfma_f32_16x16x32_bf16 v[6:9], v[172:175], v[244:247], v[6:9]
	v_mfma_f32_16x16x32_bf16 v[10:13], v[180:183], v[236:239], v[10:13]
	s_barrier
	s_add_i32 s8, s8, 2
	s_add_u32 s80, s80, 0x100
	s_addc_u32 s81, s81, 0
	s_cmp_gt_u32 s8, 29
	s_cbranch_scc0 .LBB0_1233
	s_and_b64 vcc, exec, s[62:63]
	s_cbranch_vccz .LBB0_1236
	s_barrier
